# K-loop MFMA order: adjacent accumulate pairs, alternating k direction, pair path prefers sharing the A operand (6 A-shares + 1 B-share per 16-block)
# baseline (speedup 1.0000x reference)
; #define PG8_STAGE(bufoff, gbase, voff) do { _Pragma("unroll") for (int _i = 0; _i < 2; ++_i) \
;         __builtin_amdgcn_global_load_lds((const unsigned*)((const char*)(gbase) + (voff)[_i]), (PG8_LAS unsigned*)(lds + (bufoff) + ldsw + _i * 8192), 16, 0, 0); } while (0)
; #define PG8_LDA(dst, b, h) do { _Pragma("unroll") for (int m = 0; m < 4; ++m) _Pragma("unroll") for (int k = 0; k < 2; ++k) dst[m][k] = *(const PG8_LAS bf16x8*)(lds + PG8_SA(b, h) + aoff + m * 2048 + k * 1024); } while (0)
; #define PG8_LDB(dst, b, h) do { _Pragma("unroll") for (int n = 0; n < 2; ++n) _Pragma("unroll") for (int k = 0; k < 2; ++k) dst[n][k] = *(const PG8_LAS bf16x8*)(lds + PG8_SB(b, h) + boff + n * 2048 + k * 1024); } while (0)
; #define PG8_MMA(ai, bj, At, Bt) do { __builtin_amdgcn_s_setprio(1); _Pragma("unroll") for (int m = 0; m < 4; ++m) _Pragma("unroll") for (int n = 0; n < 2; ++n) _Pragma("unroll") for (int k = 0; k < 2; ++k) \
;         acc[ai][bj][m][n] = __builtin_amdgcn_mfma_f32_16x16x32_bf16(Bt[n][k], At[m][k], acc[ai][bj][m][n], 0, 0, 0); __builtin_amdgcn_s_setprio(0); } while (0)
; #define PG8_WAIT_V(n) asm volatile("s_waitcnt vmcnt(" #n ")" ::: "memory")
; #define PG8_WAIT_L(n) asm volatile("s_waitcnt lgkmcnt(" #n ")" ::: "memory")
; #define PG8_BAR __builtin_amdgcn_s_barrier()
; #define PG8_SCHED __builtin_amdgcn_sched_barrier(0)
; template <class Epi, class Sched, bool ALIGN_EPI = false, bool SP2 = false>
; __device__ __forceinline__ void gemm_phase(PG8_LAS unsigned char* lds, const Gemm g, const Sched& S, const Epi& E) {
;     ...
;             const bool last = (t == nt - 2);
;             const char* a1 = cA + (size_t)(t + 1) * kstep;
;             const char* a2 = last ? nA : cA + (size_t)(t + 2) * kstep; const char* b2 = last ? nB : cB + (size_t)(t + 2) * kstep;
;             const char* a3 = a2 + kstep; const char* b3 = b2 + kstep;
;             if (last && has_next) S.a_ready(nxt);
;             if constexpr (SP2) {
;             PG8_LDB(B0, 0, 0); PG8_LDB(B1, 0, 1); PG8_SCHED; PG8_LDA(At, 0, 0); PG8_STAGE(PG8_SA(1, 1), a1 + hstep, voffA);
;             PG8_WAIT_V(8); PG8_WAIT_L(0); PG8_BAR; PG8_MMA(0, 0, At, B0); PG8_MMA(0, 1, At, B1); PG8_BAR; PG8_SCHED;
;             PG8_LDA(At, 0, 1); PG8_STAGE(PG8_SB(0, 0), b2, voffB); PG8_STAGE(PG8_SB(0, 1), b2 + hstep, voffB); PG8_STAGE(PG8_SA(0, 0), a2, voffA);
.LBB0_139:
	ds_read_b128 v[2:5], v187
	ds_read_b128 v[6:9], v187 offset:1024
	ds_read_b128 v[138:141], v187 offset:2048
	ds_read_b128 v[142:145], v187 offset:3072
	ds_read_b128 v[146:149], v197
	ds_read_b128 v[150:153], v197 offset:1024
	ds_read_b128 v[154:157], v197 offset:2048
	ds_read_b128 v[158:161], v197 offset:3072
	s_add_u32 s14, s12, 0xfff00080
	s_addc_u32 s15, s13, -1
	s_cmp_eq_u32 s33, 60
	s_cselect_b32 s17, s2, s15
	s_cselect_b32 s16, s11, s14
	s_cselect_b32 s15, s26, s30
	s_cselect_b32 s14, s28, s29
	v_lshl_add_u64 v[162:163], s[12:13], 0, v[188:189]
	s_add_i32 m0, s27, 0xc000
	ds_read_b128 v[202:205], v199
	ds_read_b128 v[206:209], v199 offset:1024
	ds_read_b128 v[214:217], v199 offset:2048
	ds_read_b128 v[218:221], v199 offset:3072
	ds_read_b128 v[222:225], v199 offset:4096
	ds_read_b128 v[226:229], v199 offset:5120
	ds_read_b128 v[230:233], v199 offset:6144
	ds_read_b128 v[234:237], v199 offset:7168
	global_load_lds_dwordx4 v[162:163], off
	v_lshl_add_u64 v[162:163], s[12:13], 0, v[190:191]
	s_add_i32 m0, s27, 0xe000
	s_nop 0
	global_load_lds_dwordx4 v[162:163], off
	s_waitcnt vmcnt(8)
	s_waitcnt lgkmcnt(0)
	s_setprio 1
	s_barrier
	v_mfma_f32_16x16x32_bf16 v[134:137], v[2:5], v[202:205], v[134:137]
	v_mfma_f32_16x16x32_bf16 v[134:137], v[6:9], v[206:209], v[134:137]
	v_mfma_f32_16x16x32_bf16 v[118:121], v[6:9], v[218:221], v[118:121]
	v_mfma_f32_16x16x32_bf16 v[118:121], v[2:5], v[214:217], v[118:121]
	v_mfma_f32_16x16x32_bf16 v[102:105], v[2:5], v[222:225], v[102:105]
	v_mfma_f32_16x16x32_bf16 v[102:105], v[6:9], v[226:229], v[102:105]
	v_mfma_f32_16x16x32_bf16 v[86:89], v[6:9], v[234:237], v[86:89]
	v_mfma_f32_16x16x32_bf16 v[86:89], v[2:5], v[230:233], v[86:89]
	v_mfma_f32_16x16x32_bf16 v[82:85], v[138:141], v[230:233], v[82:85]
	v_mfma_f32_16x16x32_bf16 v[82:85], v[142:145], v[234:237], v[82:85]
	v_mfma_f32_16x16x32_bf16 v[130:133], v[142:145], v[206:209], v[130:133]
	v_mfma_f32_16x16x32_bf16 v[130:133], v[138:141], v[202:205], v[130:133]
	v_mfma_f32_16x16x32_bf16 v[114:117], v[138:141], v[214:217], v[114:117]
	v_mfma_f32_16x16x32_bf16 v[114:117], v[142:145], v[218:221], v[114:117]
	v_mfma_f32_16x16x32_bf16 v[98:101], v[142:145], v[226:229], v[98:101]
	v_mfma_f32_16x16x32_bf16 v[98:101], v[138:141], v[222:225], v[98:101]
	s_setprio 0
	s_setprio 1
	v_mfma_f32_16x16x32_bf16 v[126:129], v[146:149], v[202:205], v[126:129]
	v_mfma_f32_16x16x32_bf16 v[126:129], v[150:153], v[206:209], v[126:129]
	v_mfma_f32_16x16x32_bf16 v[110:113], v[150:153], v[218:221], v[110:113]
	v_mfma_f32_16x16x32_bf16 v[110:113], v[146:149], v[214:217], v[110:113]
	v_mfma_f32_16x16x32_bf16 v[94:97], v[146:149], v[222:225], v[94:97]
	v_mfma_f32_16x16x32_bf16 v[94:97], v[150:153], v[226:229], v[94:97]
	v_mfma_f32_16x16x32_bf16 v[78:81], v[150:153], v[234:237], v[78:81]
	v_mfma_f32_16x16x32_bf16 v[78:81], v[146:149], v[230:233], v[78:81]
	v_mfma_f32_16x16x32_bf16 v[74:77], v[154:157], v[230:233], v[74:77]
	v_mfma_f32_16x16x32_bf16 v[74:77], v[158:161], v[234:237], v[74:77]
	v_mfma_f32_16x16x32_bf16 v[122:125], v[158:161], v[206:209], v[122:125]
	v_mfma_f32_16x16x32_bf16 v[122:125], v[154:157], v[202:205], v[122:125]
	v_mfma_f32_16x16x32_bf16 v[106:109], v[154:157], v[214:217], v[106:109]
	v_mfma_f32_16x16x32_bf16 v[106:109], v[158:161], v[218:221], v[106:109]
	v_mfma_f32_16x16x32_bf16 v[90:93], v[158:161], v[226:229], v[90:93]
	v_mfma_f32_16x16x32_bf16 v[90:93], v[154:157], v[222:225], v[90:93]
	s_barrier
	s_setprio 0
	s_add_i32 s34, s41, s25
	v_lshl_add_u64 v[162:163], s[14:15], 0, v[168:169]
	s_mov_b32 m0, s34
	ds_read_b128 v[202:205], v199 offset:16384
	ds_read_b128 v[206:209], v199 offset:17408
	ds_read_b128 v[214:217], v199 offset:18432
	ds_read_b128 v[218:221], v199 offset:19456
	ds_read_b128 v[222:225], v199 offset:20480
	ds_read_b128 v[226:229], v199 offset:21504
	ds_read_b128 v[230:233], v199 offset:22528
	ds_read_b128 v[234:237], v199 offset:23552
	global_load_lds_dwordx4 v[162:163], off
	s_add_i32 m0, s34, 0x2000
	s_add_u32 s34, s14, 0x100000
	v_lshl_add_u64 v[210:211], s[14:15], 0, v[172:173]
	s_addc_u32 s35, s15, 0
	s_add_i32 s79, s92, s25
	global_load_lds_dwordx4 v[210:211], off
	v_lshl_add_u64 v[238:239], s[34:35], 0, v[168:169]
	s_mov_b32 m0, s79
	v_lshl_add_u64 v[240:241], s[16:17], 0, v[170:171]
	global_load_lds_dwordx4 v[238:239], off
	v_lshl_add_u64 v[238:239], s[34:35], 0, v[172:173]
	s_add_i32 m0, s79, 0x2000
	s_nop 0
	global_load_lds_dwordx4 v[238:239], off
	v_lshl_add_u64 v[238:239], s[16:17], 0, v[164:165]
	s_mov_b32 m0, s27
	s_nop 0
	global_load_lds_dwordx4 v[238:239], off
	s_mov_b32 m0, s39
	s_nop 0
	global_load_lds_dwordx4 v[240:241], off
	s_waitcnt vmcnt(8)
	s_waitcnt lgkmcnt(0)
	s_setprio 1
	s_barrier
; #define PG8_STAGE(bufoff, gbase, voff) do { _Pragma("unroll") for (int _i = 0; _i < 2; ++_i) \
;         __builtin_amdgcn_global_load_lds((const unsigned*)((const char*)(gbase) + (voff)[_i]), (PG8_LAS unsigned*)(lds + (bufoff) + ldsw + _i * 8192), 16, 0, 0); } while (0)
; #define PG8_LDA(dst, b, h) do { _Pragma("unroll") for (int m = 0; m < 4; ++m) _Pragma("unroll") for (int k = 0; k < 2; ++k) dst[m][k] = *(const PG8_LAS bf16x8*)(lds + PG8_SA(b, h) + aoff + m * 2048 + k * 1024); } while (0)
; #define PG8_LDB(dst, b, h) do { _Pragma("unroll") for (int n = 0; n < 2; ++n) _Pragma("unroll") for (int k = 0; k < 2; ++k) dst[n][k] = *(const PG8_LAS bf16x8*)(lds + PG8_SB(b, h) + boff + n * 2048 + k * 1024); } while (0)
; #define PG8_MMA(ai, bj, At, Bt) do { __builtin_amdgcn_s_setprio(1); _Pragma("unroll") for (int m = 0; m < 4; ++m) _Pragma("unroll") for (int n = 0; n < 2; ++n) _Pragma("unroll") for (int k = 0; k < 2; ++k) \
;         acc[ai][bj][m][n] = __builtin_amdgcn_mfma_f32_16x16x32_bf16(Bt[n][k], At[m][k], acc[ai][bj][m][n], 0, 0, 0); __builtin_amdgcn_s_setprio(0); } while (0)
; #define PG8_WAIT_V(n) asm volatile("s_waitcnt vmcnt(" #n ")" ::: "memory")
; #define PG8_WAIT_L(n) asm volatile("s_waitcnt lgkmcnt(" #n ")" ::: "memory")
; #define PG8_BAR __builtin_amdgcn_s_barrier()
; #define PG8_SCHED __builtin_amdgcn_sched_barrier(0)
; template <class Epi, class Sched, bool ALIGN_EPI = false, bool SP2 = false>
; __device__ __forceinline__ void gemm_phase(PG8_LAS unsigned char* lds, const Gemm g, const Sched& S, const Epi& E) {
;     ...
;             PG8_WAIT_V(8); PG8_WAIT_L(0); PG8_BAR; PG8_MMA(1, 0, At, B0); PG8_MMA(1, 1, At, B1); PG8_BAR; PG8_SCHED;
;             PG8_LDB(B0, 1, 0); PG8_LDB(B1, 1, 1); PG8_SCHED; PG8_LDA(At, 1, 0); PG8_STAGE(PG8_SA(0, 1), a2 + hstep, voffA);
;             PG8_WAIT_V(8); PG8_WAIT_L(0); PG8_BAR; PG8_MMA(0, 0, At, B0); PG8_MMA(0, 1, At, B1); PG8_BAR; PG8_SCHED;
	v_mfma_f32_16x16x32_bf16 v[70:73], v[2:5], v[202:205], v[70:73]
	v_mfma_f32_16x16x32_bf16 v[66:69], v[138:141], v[202:205], v[66:69]
	v_mfma_f32_16x16x32_bf16 v[54:57], v[2:5], v[214:217], v[54:57]
	v_mfma_f32_16x16x32_bf16 v[50:53], v[138:141], v[214:217], v[50:53]
	v_mfma_f32_16x16x32_bf16 v[38:41], v[2:5], v[222:225], v[38:41]
	v_mfma_f32_16x16x32_bf16 v[34:37], v[138:141], v[222:225], v[34:37]
	v_mfma_f32_16x16x32_bf16 v[2:5], v[2:5], v[230:233], v[22:25]
	v_mfma_f32_16x16x32_bf16 v[70:73], v[6:9], v[206:209], v[70:73]
	v_mfma_f32_16x16x32_bf16 v[66:69], v[142:145], v[206:209], v[66:69]
	v_mfma_f32_16x16x32_bf16 v[54:57], v[6:9], v[218:221], v[54:57]
	v_mfma_f32_16x16x32_bf16 v[50:53], v[142:145], v[218:221], v[50:53]
	v_mfma_f32_16x16x32_bf16 v[38:41], v[6:9], v[226:229], v[38:41]
	v_mfma_f32_16x16x32_bf16 v[34:37], v[142:145], v[226:229], v[34:37]
	v_mfma_f32_16x16x32_bf16 v[2:5], v[6:9], v[234:237], v[2:5]
	v_mfma_f32_16x16x32_bf16 v[6:9], v[138:141], v[230:233], v[18:21]
	v_mfma_f32_16x16x32_bf16 v[6:9], v[142:145], v[234:237], v[6:9]
	s_setprio 0
	s_setprio 1
	v_mfma_f32_16x16x32_bf16 v[18:21], v[146:149], v[202:205], v[62:65]
	v_mfma_f32_16x16x32_bf16 v[62:65], v[150:153], v[206:209], v[18:21]
	v_mfma_f32_16x16x32_bf16 v[18:21], v[154:157], v[202:205], v[58:61]
	v_mfma_f32_16x16x32_bf16 v[58:61], v[158:161], v[206:209], v[18:21]
	v_mfma_f32_16x16x32_bf16 v[18:21], v[146:149], v[214:217], v[46:49]
	v_mfma_f32_16x16x32_bf16 v[46:49], v[150:153], v[218:221], v[18:21]
	v_mfma_f32_16x16x32_bf16 v[18:21], v[154:157], v[214:217], v[42:45]
	v_mfma_f32_16x16x32_bf16 v[42:45], v[158:161], v[218:221], v[18:21]
	v_mfma_f32_16x16x32_bf16 v[18:21], v[146:149], v[222:225], v[30:33]
	v_mfma_f32_16x16x32_bf16 v[30:33], v[150:153], v[226:229], v[18:21]
	v_mfma_f32_16x16x32_bf16 v[18:21], v[154:157], v[222:225], v[26:29]
	v_mfma_f32_16x16x32_bf16 v[14:17], v[146:149], v[230:233], v[14:17]
	v_mfma_f32_16x16x32_bf16 v[10:13], v[154:157], v[230:233], v[10:13]
	v_mfma_f32_16x16x32_bf16 v[26:29], v[158:161], v[226:229], v[18:21]
	v_mfma_f32_16x16x32_bf16 v[14:17], v[150:153], v[234:237], v[14:17]
	v_mfma_f32_16x16x32_bf16 v[10:13], v[158:161], v[234:237], v[10:13]
	s_barrier
	s_setprio 0
	s_add_i32 s34, 0, 0x18000
	s_add_i32 s35, 0, 0x1c000
	v_add_u32_e32 v142, s34, v179
	v_add_u32_e32 v158, s35, v179
	ds_read_b128 v[18:21], v142
	ds_read_b128 v[22:25], v142 offset:1024
	ds_read_b128 v[138:141], v142 offset:2048
	ds_read_b128 v[142:145], v142 offset:3072
	ds_read_b128 v[146:149], v158
	ds_read_b128 v[150:153], v158 offset:1024
	ds_read_b128 v[154:157], v158 offset:2048
	ds_read_b128 v[158:161], v158 offset:3072
	s_add_u32 s16, s16, 0x100000
	s_addc_u32 s17, s17, 0
	s_mov_b32 m0, s71
	v_lshl_add_u64 v[242:243], s[16:17], 0, v[164:165]
	ds_read_b128 v[202:205], v199 offset:32768
	ds_read_b128 v[206:209], v199 offset:33792
	ds_read_b128 v[214:217], v199 offset:34816
	ds_read_b128 v[218:221], v199 offset:35840
	ds_read_b128 v[222:225], v199 offset:36864
	ds_read_b128 v[226:229], v199 offset:37888
	ds_read_b128 v[230:233], v199 offset:38912
	ds_read_b128 v[234:237], v199 offset:39936
	global_load_lds_dwordx4 v[242:243], off
	v_lshl_add_u64 v[242:243], s[16:17], 0, v[170:171]
	s_mov_b32 m0, s87
	s_nop 0
	global_load_lds_dwordx4 v[242:243], off
	s_waitcnt vmcnt(8)
	s_waitcnt lgkmcnt(0)
	s_setprio 1
	s_barrier
	v_mfma_f32_16x16x32_bf16 v[134:137], v[18:21], v[202:205], v[134:137]
	v_mfma_f32_16x16x32_bf16 v[134:137], v[22:25], v[206:209], v[134:137]
	v_mfma_f32_16x16x32_bf16 v[118:121], v[22:25], v[218:221], v[118:121]
	v_mfma_f32_16x16x32_bf16 v[118:121], v[18:21], v[214:217], v[118:121]
	v_mfma_f32_16x16x32_bf16 v[102:105], v[18:21], v[222:225], v[102:105]
	v_mfma_f32_16x16x32_bf16 v[102:105], v[22:25], v[226:229], v[102:105]
	v_mfma_f32_16x16x32_bf16 v[86:89], v[22:25], v[234:237], v[86:89]
	v_mfma_f32_16x16x32_bf16 v[86:89], v[18:21], v[230:233], v[86:89]
	v_mfma_f32_16x16x32_bf16 v[82:85], v[138:141], v[230:233], v[82:85]
	v_mfma_f32_16x16x32_bf16 v[82:85], v[142:145], v[234:237], v[82:85]
	v_mfma_f32_16x16x32_bf16 v[130:133], v[142:145], v[206:209], v[130:133]
	v_mfma_f32_16x16x32_bf16 v[130:133], v[138:141], v[202:205], v[130:133]
	v_mfma_f32_16x16x32_bf16 v[114:117], v[138:141], v[214:217], v[114:117]
	v_mfma_f32_16x16x32_bf16 v[114:117], v[142:145], v[218:221], v[114:117]
	v_mfma_f32_16x16x32_bf16 v[98:101], v[142:145], v[226:229], v[98:101]
	v_mfma_f32_16x16x32_bf16 v[98:101], v[138:141], v[222:225], v[98:101]
	s_setprio 0
	s_setprio 1
	v_mfma_f32_16x16x32_bf16 v[126:129], v[146:149], v[202:205], v[126:129]
	v_mfma_f32_16x16x32_bf16 v[126:129], v[150:153], v[206:209], v[126:129]
	v_mfma_f32_16x16x32_bf16 v[110:113], v[150:153], v[218:221], v[110:113]
	v_mfma_f32_16x16x32_bf16 v[110:113], v[146:149], v[214:217], v[110:113]
	v_mfma_f32_16x16x32_bf16 v[94:97], v[146:149], v[222:225], v[94:97]
	v_mfma_f32_16x16x32_bf16 v[94:97], v[150:153], v[226:229], v[94:97]
	v_mfma_f32_16x16x32_bf16 v[78:81], v[150:153], v[234:237], v[78:81]
	v_mfma_f32_16x16x32_bf16 v[78:81], v[146:149], v[230:233], v[78:81]
	v_mfma_f32_16x16x32_bf16 v[74:77], v[154:157], v[230:233], v[74:77]
	v_mfma_f32_16x16x32_bf16 v[74:77], v[158:161], v[234:237], v[74:77]
	v_mfma_f32_16x16x32_bf16 v[122:125], v[158:161], v[206:209], v[122:125]
	v_mfma_f32_16x16x32_bf16 v[122:125], v[154:157], v[202:205], v[122:125]
	v_mfma_f32_16x16x32_bf16 v[106:109], v[154:157], v[214:217], v[106:109]
	v_mfma_f32_16x16x32_bf16 v[106:109], v[158:161], v[218:221], v[106:109]
	v_mfma_f32_16x16x32_bf16 v[90:93], v[158:161], v[226:229], v[90:93]
	v_mfma_f32_16x16x32_bf16 v[90:93], v[154:157], v[222:225], v[90:93]
	s_barrier
; #define PG8_STAGE(bufoff, gbase, voff) do { _Pragma("unroll") for (int _i = 0; _i < 2; ++_i) \
;         __builtin_amdgcn_global_load_lds((const unsigned*)((const char*)(gbase) + (voff)[_i]), (PG8_LAS unsigned*)(lds + (bufoff) + ldsw + _i * 8192), 16, 0, 0); } while (0)
; #define PG8_LDA(dst, b, h) do { _Pragma("unroll") for (int m = 0; m < 4; ++m) _Pragma("unroll") for (int k = 0; k < 2; ++k) dst[m][k] = *(const PG8_LAS bf16x8*)(lds + PG8_SA(b, h) + aoff + m * 2048 + k * 1024); } while (0)
; #define PG8_MMA(ai, bj, At, Bt) do { __builtin_amdgcn_s_setprio(1); _Pragma("unroll") for (int m = 0; m < 4; ++m) _Pragma("unroll") for (int n = 0; n < 2; ++n) _Pragma("unroll") for (int k = 0; k < 2; ++k) \
;         acc[ai][bj][m][n] = __builtin_amdgcn_mfma_f32_16x16x32_bf16(Bt[n][k], At[m][k], acc[ai][bj][m][n], 0, 0, 0); __builtin_amdgcn_s_setprio(0); } while (0)
; #define PG8_WAIT_V(n) asm volatile("s_waitcnt vmcnt(" #n ")" ::: "memory")
; #define PG8_WAIT_L(n) asm volatile("s_waitcnt lgkmcnt(" #n ")" ::: "memory")
; #define PG8_BAR __builtin_amdgcn_s_barrier()
; #define PG8_SCHED __builtin_amdgcn_sched_barrier(0)
; template <class Epi, class Sched, bool ALIGN_EPI = false, bool SP2 = false>
; __device__ __forceinline__ void gemm_phase(PG8_LAS unsigned char* lds, const Gemm g, const Sched& S, const Epi& E) {
;     ...
;             PG8_LDA(At, 1, 1); PG8_STAGE(PG8_SB(1, 0), b3, voffB); PG8_STAGE(PG8_SB(1, 1), b3 + hstep, voffB); PG8_STAGE(PG8_SA(1, 0), a3, voffA);
;             PG8_WAIT_V(8); PG8_WAIT_L(0); PG8_BAR; PG8_MMA(1, 0, At, B0); PG8_MMA(1, 1, At, B1); PG8_BAR; PG8_SCHED;
;     ...
;         if constexpr (ALIGN_EPI) { if (wr == 0) PG8_BAR; }
	s_setprio 0
	s_add_i32 s16, s34, s25
	v_lshl_add_u64 v[162:163], v[162:163], 0, s[46:47]
	s_mov_b32 m0, s16
	ds_read_b128 v[202:205], v199 offset:49152
	ds_read_b128 v[206:209], v199 offset:50176
	ds_read_b128 v[214:217], v199 offset:51200
	ds_read_b128 v[218:221], v199 offset:52224
	ds_read_b128 v[222:225], v199 offset:53248
	ds_read_b128 v[226:229], v199 offset:54272
	ds_read_b128 v[230:233], v199 offset:55296
	ds_read_b128 v[234:237], v199 offset:56320
	global_load_lds_dwordx4 v[162:163], off
	s_add_i32 m0, s16, 0x2000
	s_add_u32 s14, s14, 0x100080
	v_lshl_add_u64 v[162:163], v[210:211], 0, s[46:47]
	s_addc_u32 s15, s15, 0
	s_add_i32 s16, s35, s25
	global_load_lds_dwordx4 v[162:163], off
	v_lshl_add_u64 v[162:163], s[14:15], 0, v[168:169]
	s_mov_b32 m0, s16
	s_nop 0
	global_load_lds_dwordx4 v[162:163], off
	v_lshl_add_u64 v[162:163], s[14:15], 0, v[172:173]
	s_add_i32 m0, s16, 0x2000
	s_nop 0
	global_load_lds_dwordx4 v[162:163], off
	v_lshl_add_u64 v[162:163], v[238:239], 0, s[46:47]
	s_mov_b32 m0, s95
	s_nop 0
	global_load_lds_dwordx4 v[162:163], off
	v_lshl_add_u64 v[162:163], v[240:241], 0, s[46:47]
	s_mov_b32 m0, s96
	s_nop 0
	global_load_lds_dwordx4 v[162:163], off
	s_waitcnt vmcnt(8)
	s_waitcnt lgkmcnt(0)
	s_setprio 1
	s_barrier
	v_mfma_f32_16x16x32_bf16 v[70:73], v[18:21], v[202:205], v[70:73]
	v_mfma_f32_16x16x32_bf16 v[54:57], v[18:21], v[214:217], v[54:57]
	v_mfma_f32_16x16x32_bf16 v[38:41], v[18:21], v[222:225], v[38:41]
	v_mfma_f32_16x16x32_bf16 v[2:5], v[18:21], v[230:233], v[2:5]
	v_mfma_f32_16x16x32_bf16 v[70:73], v[22:25], v[206:209], v[70:73]
	v_mfma_f32_16x16x32_bf16 v[66:69], v[138:141], v[202:205], v[66:69]
	v_mfma_f32_16x16x32_bf16 v[54:57], v[22:25], v[218:221], v[54:57]
	v_mfma_f32_16x16x32_bf16 v[50:53], v[138:141], v[214:217], v[50:53]
	v_mfma_f32_16x16x32_bf16 v[38:41], v[22:25], v[226:229], v[38:41]
	v_mfma_f32_16x16x32_bf16 v[34:37], v[138:141], v[222:225], v[34:37]
	v_mfma_f32_16x16x32_bf16 v[22:25], v[22:25], v[234:237], v[2:5]
	v_mfma_f32_16x16x32_bf16 v[2:5], v[138:141], v[230:233], v[6:9]
	v_mfma_f32_16x16x32_bf16 v[66:69], v[142:145], v[206:209], v[66:69]
	v_mfma_f32_16x16x32_bf16 v[50:53], v[142:145], v[218:221], v[50:53]
	v_mfma_f32_16x16x32_bf16 v[34:37], v[142:145], v[226:229], v[34:37]
	v_mfma_f32_16x16x32_bf16 v[18:21], v[142:145], v[234:237], v[2:5]
	s_setprio 0
	s_setprio 1
	v_mfma_f32_16x16x32_bf16 v[2:5], v[146:149], v[202:205], v[62:65]
	v_mfma_f32_16x16x32_bf16 v[62:65], v[150:153], v[206:209], v[2:5]
	v_mfma_f32_16x16x32_bf16 v[2:5], v[154:157], v[202:205], v[58:61]
	v_mfma_f32_16x16x32_bf16 v[58:61], v[158:161], v[206:209], v[2:5]
	v_mfma_f32_16x16x32_bf16 v[2:5], v[146:149], v[214:217], v[46:49]
	v_mfma_f32_16x16x32_bf16 v[46:49], v[150:153], v[218:221], v[2:5]
	v_mfma_f32_16x16x32_bf16 v[2:5], v[154:157], v[214:217], v[42:45]
	v_mfma_f32_16x16x32_bf16 v[42:45], v[158:161], v[218:221], v[2:5]
	v_mfma_f32_16x16x32_bf16 v[2:5], v[146:149], v[222:225], v[30:33]
	v_mfma_f32_16x16x32_bf16 v[30:33], v[150:153], v[226:229], v[2:5]
	v_mfma_f32_16x16x32_bf16 v[2:5], v[154:157], v[222:225], v[26:29]
	v_mfma_f32_16x16x32_bf16 v[26:29], v[158:161], v[226:229], v[2:5]
	v_mfma_f32_16x16x32_bf16 v[2:5], v[146:149], v[230:233], v[14:17]
	v_mfma_f32_16x16x32_bf16 v[14:17], v[150:153], v[234:237], v[2:5]
	v_mfma_f32_16x16x32_bf16 v[2:5], v[154:157], v[230:233], v[10:13]
	v_mfma_f32_16x16x32_bf16 v[10:13], v[158:161], v[234:237], v[2:5]
	s_barrier
	s_setprio 0
	s_add_i32 s33, s33, 2
	s_add_u32 s12, s12, 0x100
	s_addc_u32 s13, s13, 0
	s_add_u32 s29, s29, 0x100
	s_addc_u32 s30, s30, 0
	s_cmp_gt_u32 s33, 61
	s_cbranch_scc0 .LBB0_139
	s_and_b64 vcc, exec, s[48:49]
	s_cbranch_vccz .LBB0_142
	s_barrier

; #define PG8_STAGE(bufoff, gbase, voff) do { _Pragma("unroll") for (int _i = 0; _i < 2; ++_i) \
;         __builtin_amdgcn_global_load_lds((const unsigned*)((const char*)(gbase) + (voff)[_i]), (PG8_LAS unsigned*)(lds + (bufoff) + ldsw + _i * 8192), 16, 0, 0); } while (0)
; #define PG8_LDA(dst, b, h) do { _Pragma("unroll") for (int m = 0; m < 4; ++m) _Pragma("unroll") for (int k = 0; k < 2; ++k) dst[m][k] = *(const PG8_LAS bf16x8*)(lds + PG8_SA(b, h) + aoff + m * 2048 + k * 1024); } while (0)
; #define PG8_LDB(dst, b, h) do { _Pragma("unroll") for (int n = 0; n < 2; ++n) _Pragma("unroll") for (int k = 0; k < 2; ++k) dst[n][k] = *(const PG8_LAS bf16x8*)(lds + PG8_SB(b, h) + boff + n * 2048 + k * 1024); } while (0)
; #define PG8_MMA(ai, bj, At, Bt) do { __builtin_amdgcn_s_setprio(1); _Pragma("unroll") for (int m = 0; m < 4; ++m) _Pragma("unroll") for (int n = 0; n < 2; ++n) _Pragma("unroll") for (int k = 0; k < 2; ++k) \
;         acc[ai][bj][m][n] = __builtin_amdgcn_mfma_f32_16x16x32_bf16(Bt[n][k], At[m][k], acc[ai][bj][m][n], 0, 0, 0); __builtin_amdgcn_s_setprio(0); } while (0)
; #define PG8_WAIT_V(n) asm volatile("s_waitcnt vmcnt(" #n ")" ::: "memory")
; #define PG8_WAIT_L(n) asm volatile("s_waitcnt lgkmcnt(" #n ")" ::: "memory")
; template <class Epi, class Sched, bool ALIGN_EPI = false, bool SP2 = false>
; __device__ __forceinline__ void gemm_phase(PG8_LAS unsigned char* lds, const Gemm g, const Sched& S, const Epi& E) {
;     ...
;             const bool last = (t == nt - 2);
;             const char* a1 = cA + (size_t)(t + 1) * kstep;
;             const char* a2 = last ? nA : cA + (size_t)(t + 2) * kstep; const char* b2 = last ? nB : cB + (size_t)(t + 2) * kstep;
;             const char* a3 = a2 + kstep; const char* b3 = b2 + kstep;
;             if (last && has_next) S.a_ready(nxt);
;             if constexpr (SP2) {
;             PG8_LDB(B0, 0, 0); PG8_LDB(B1, 0, 1); PG8_SCHED; PG8_LDA(At, 0, 0); PG8_STAGE(PG8_SA(1, 1), a1 + hstep, voffA);
;             PG8_WAIT_V(8); PG8_WAIT_L(0); PG8_BAR; PG8_MMA(0, 0, At, B0); PG8_MMA(0, 1, At, B1); PG8_BAR; PG8_SCHED;
;             PG8_LDA(At, 0, 1); PG8_STAGE(PG8_SB(0, 0), b2, voffB); PG8_STAGE(PG8_SB(0, 1), b2 + hstep, voffB); PG8_STAGE(PG8_SA(0, 0), a2, voffA);
;             PG8_WAIT_V(8); PG8_WAIT_L(0); PG8_BAR; PG8_MMA(1, 0, At, B0); PG8_MMA(1, 1, At, B1); PG8_BAR; PG8_SCHED;
.LBB0_592:
	s_or_b32 s10, s52, 1
	s_lshl_b64 s[96:97], s[10:11], 7
	s_add_i32 s10, s52, 2
	s_lshl_b64 s[54:55], s[10:11], 7
	s_cmp_lg_u32 s52, s94
	s_cselect_b32 s52, s54, 0
	s_cselect_b32 s53, s55, 0
	s_add_u32 s54, s50, s52
	s_addc_u32 s55, s51, s53
	s_add_i32 s95, 0, 0x10000
	v_add_u32_e32 v87, s95, v85
	ds_read_b128 v[88:91], v87
	ds_read_b128 v[92:95], v87 offset:1024
	ds_read_b128 v[100:103], v87 offset:2048
	ds_read_b128 v[104:107], v87 offset:3072
	s_add_u32 s52, s48, s52
	s_addc_u32 s53, s49, s53
	s_add_u32 s96, s50, s96
	s_addc_u32 s97, s51, s97
	s_add_u32 s96, s96, 0x100000
	s_addc_u32 s97, s97, 0
	v_lshl_add_u64 v[96:97], s[96:97], 0, v[66:67]
	s_add_i32 m0, s17, 0xc000
	ds_read_b128 v[108:111], v86
	ds_read_b128 v[112:115], v86 offset:1024
	ds_read_b128 v[116:119], v86 offset:2048
	ds_read_b128 v[120:123], v86 offset:3072
	ds_read_b128 v[124:127], v86 offset:4096
	ds_read_b128 v[128:131], v86 offset:5120
	ds_read_b128 v[132:135], v86 offset:6144
	ds_read_b128 v[136:139], v86 offset:7168
	global_load_lds_dwordx4 v[96:97], off
	v_lshl_add_u64 v[96:97], s[96:97], 0, v[76:77]
	s_add_i32 m0, s17, 0xe000
	s_nop 0
	global_load_lds_dwordx4 v[96:97], off
	s_waitcnt vmcnt(8)
	s_waitcnt lgkmcnt(0)
	s_setprio 1
	s_barrier
	v_mfma_f32_16x16x32_bf16 v[62:65], v[88:91], v[108:111], v[62:65]
	v_mfma_f32_16x16x32_bf16 v[62:65], v[92:95], v[112:115], v[62:65]
	v_mfma_f32_16x16x32_bf16 v[54:57], v[92:95], v[120:123], v[54:57]
	v_mfma_f32_16x16x32_bf16 v[54:57], v[88:91], v[116:119], v[54:57]
	v_mfma_f32_16x16x32_bf16 v[46:49], v[88:91], v[124:127], v[46:49]
	v_mfma_f32_16x16x32_bf16 v[46:49], v[92:95], v[128:131], v[46:49]
	v_mfma_f32_16x16x32_bf16 v[38:41], v[92:95], v[136:139], v[38:41]
	v_mfma_f32_16x16x32_bf16 v[38:41], v[88:91], v[132:135], v[38:41]
	v_mfma_f32_16x16x32_bf16 v[34:37], v[100:103], v[132:135], v[34:37]
	v_mfma_f32_16x16x32_bf16 v[34:37], v[104:107], v[136:139], v[34:37]
	v_mfma_f32_16x16x32_bf16 v[58:61], v[104:107], v[112:115], v[58:61]
	v_mfma_f32_16x16x32_bf16 v[58:61], v[100:103], v[108:111], v[58:61]
	v_mfma_f32_16x16x32_bf16 v[50:53], v[100:103], v[116:119], v[50:53]
	v_mfma_f32_16x16x32_bf16 v[50:53], v[104:107], v[120:123], v[50:53]
	v_mfma_f32_16x16x32_bf16 v[42:45], v[104:107], v[128:131], v[42:45]
	v_mfma_f32_16x16x32_bf16 v[42:45], v[100:103], v[124:127], v[42:45]
	s_setprio 0
	s_setprio 1
	s_setprio 0
	s_barrier
	s_add_i32 s95, s95, s29
	v_lshl_add_u64 v[96:97], s[52:53], 0, v[78:79]
	s_mov_b32 m0, s95
	ds_read_b128 v[108:111], v86 offset:16384
	ds_read_b128 v[112:115], v86 offset:17408
	ds_read_b128 v[116:119], v86 offset:18432
	ds_read_b128 v[120:123], v86 offset:19456
	ds_read_b128 v[124:127], v86 offset:20480
	ds_read_b128 v[128:131], v86 offset:21504
	ds_read_b128 v[132:135], v86 offset:22528
	ds_read_b128 v[136:139], v86 offset:23552
	global_load_lds_dwordx4 v[96:97], off
	s_add_i32 m0, s95, 0x2000
	s_add_u32 s96, s52, 0x100000
	v_lshl_add_u64 v[140:141], s[52:53], 0, v[74:75]
	s_addc_u32 s97, s53, 0
	global_load_lds_dwordx4 v[140:141], off
	v_lshl_add_u64 v[142:143], s[96:97], 0, v[78:79]
	s_mov_b32 m0, s30
	v_lshl_add_u64 v[144:145], s[54:55], 0, v[76:77]
	global_load_lds_dwordx4 v[142:143], off
	v_lshl_add_u64 v[142:143], s[96:97], 0, v[74:75]
	s_mov_b32 m0, s33
	s_nop 0
	global_load_lds_dwordx4 v[142:143], off
	v_lshl_add_u64 v[142:143], s[54:55], 0, v[66:67]
	s_mov_b32 m0, s17
	s_nop 0
	global_load_lds_dwordx4 v[142:143], off
	s_mov_b32 m0, s34
	s_nop 0
	global_load_lds_dwordx4 v[144:145], off
	s_waitcnt vmcnt(8)
	s_waitcnt lgkmcnt(0)
	s_setprio 1
	s_barrier
	v_mfma_f32_16x16x32_bf16 v[30:33], v[88:91], v[108:111], v[30:33]
	v_mfma_f32_16x16x32_bf16 v[30:33], v[92:95], v[112:115], v[30:33]
	v_mfma_f32_16x16x32_bf16 v[22:25], v[92:95], v[120:123], v[22:25]
	v_mfma_f32_16x16x32_bf16 v[22:25], v[88:91], v[116:119], v[22:25]
	v_mfma_f32_16x16x32_bf16 v[14:17], v[88:91], v[124:127], v[14:17]
	v_mfma_f32_16x16x32_bf16 v[14:17], v[92:95], v[128:131], v[14:17]
	v_mfma_f32_16x16x32_bf16 v[6:9], v[92:95], v[136:139], v[6:9]
	v_mfma_f32_16x16x32_bf16 v[6:9], v[88:91], v[132:135], v[6:9]
	v_mfma_f32_16x16x32_bf16 v[2:5], v[100:103], v[132:135], v[2:5]
	v_mfma_f32_16x16x32_bf16 v[2:5], v[104:107], v[136:139], v[2:5]
	v_mfma_f32_16x16x32_bf16 v[26:29], v[104:107], v[112:115], v[26:29]
	v_mfma_f32_16x16x32_bf16 v[26:29], v[100:103], v[108:111], v[26:29]
	v_mfma_f32_16x16x32_bf16 v[18:21], v[100:103], v[116:119], v[18:21]
	v_mfma_f32_16x16x32_bf16 v[18:21], v[104:107], v[120:123], v[18:21]
	v_mfma_f32_16x16x32_bf16 v[10:13], v[104:107], v[128:131], v[10:13]
	v_mfma_f32_16x16x32_bf16 v[10:13], v[100:103], v[124:127], v[10:13]
	s_setprio 0
	s_setprio 1
	s_setprio 0
	s_barrier
; #define PG8_STAGE(bufoff, gbase, voff) do { _Pragma("unroll") for (int _i = 0; _i < 2; ++_i) \
;         __builtin_amdgcn_global_load_lds((const unsigned*)((const char*)(gbase) + (voff)[_i]), (PG8_LAS unsigned*)(lds + (bufoff) + ldsw + _i * 8192), 16, 0, 0); } while (0)
; #define PG8_LDA(dst, b, h) do { _Pragma("unroll") for (int m = 0; m < 4; ++m) _Pragma("unroll") for (int k = 0; k < 2; ++k) dst[m][k] = *(const PG8_LAS bf16x8*)(lds + PG8_SA(b, h) + aoff + m * 2048 + k * 1024); } while (0)
; #define PG8_LDB(dst, b, h) do { _Pragma("unroll") for (int n = 0; n < 2; ++n) _Pragma("unroll") for (int k = 0; k < 2; ++k) dst[n][k] = *(const PG8_LAS bf16x8*)(lds + PG8_SB(b, h) + boff + n * 2048 + k * 1024); } while (0)
; #define PG8_MMA(ai, bj, At, Bt) do { __builtin_amdgcn_s_setprio(1); _Pragma("unroll") for (int m = 0; m < 4; ++m) _Pragma("unroll") for (int n = 0; n < 2; ++n) _Pragma("unroll") for (int k = 0; k < 2; ++k) \
;         acc[ai][bj][m][n] = __builtin_amdgcn_mfma_f32_16x16x32_bf16(Bt[n][k], At[m][k], acc[ai][bj][m][n], 0, 0, 0); __builtin_amdgcn_s_setprio(0); } while (0)
; #define PG8_WAIT_V(n) asm volatile("s_waitcnt vmcnt(" #n ")" ::: "memory")
; #define PG8_WAIT_L(n) asm volatile("s_waitcnt lgkmcnt(" #n ")" ::: "memory")
; #define PG8_BAR __builtin_amdgcn_s_barrier()
; #define PG8_SCHED __builtin_amdgcn_sched_barrier(0)
; template <class Epi, class Sched, bool ALIGN_EPI = false, bool SP2 = false>
; __device__ __forceinline__ void gemm_phase(PG8_LAS unsigned char* lds, const Gemm g, const Sched& S, const Epi& E) {
;     ...
;             PG8_LDB(B0, 1, 0); PG8_LDB(B1, 1, 1); PG8_SCHED; PG8_LDA(At, 1, 0); PG8_STAGE(PG8_SA(0, 1), a2 + hstep, voffA);
;             PG8_WAIT_V(8); PG8_WAIT_L(0); PG8_BAR; PG8_MMA(0, 0, At, B0); PG8_MMA(0, 1, At, B1); PG8_BAR; PG8_SCHED;
;             PG8_LDA(At, 1, 1); PG8_STAGE(PG8_SB(1, 0), b3, voffB); PG8_STAGE(PG8_SB(1, 1), b3 + hstep, voffB); PG8_STAGE(PG8_SA(1, 0), a3, voffA);
;             PG8_WAIT_V(8); PG8_WAIT_L(0); PG8_BAR; PG8_MMA(1, 0, At, B0); PG8_MMA(1, 1, At, B1); PG8_BAR; PG8_SCHED;
;     ...
;         if constexpr (ALIGN_EPI) { if (wr == 0) PG8_BAR; }
	s_add_i32 s95, 0, 0x18000
	v_add_u32_e32 v87, s95, v85
	ds_read_b128 v[88:91], v87
	ds_read_b128 v[92:95], v87 offset:1024
	ds_read_b128 v[100:103], v87 offset:2048
	ds_read_b128 v[104:107], v87 offset:3072
	s_add_u32 s54, s54, 0x100000
	s_addc_u32 s55, s55, 0
	s_mov_b32 m0, s35
	v_lshl_add_u64 v[146:147], s[54:55], 0, v[66:67]
	ds_read_b128 v[108:111], v86 offset:32768
	ds_read_b128 v[112:115], v86 offset:33792
	ds_read_b128 v[116:119], v86 offset:34816
	ds_read_b128 v[120:123], v86 offset:35840
	ds_read_b128 v[124:127], v86 offset:36864
	ds_read_b128 v[128:131], v86 offset:37888
	ds_read_b128 v[132:135], v86 offset:38912
	ds_read_b128 v[136:139], v86 offset:39936
	global_load_lds_dwordx4 v[146:147], off
	v_lshl_add_u64 v[146:147], s[54:55], 0, v[76:77]
	s_mov_b32 m0, s88
	s_nop 0
	global_load_lds_dwordx4 v[146:147], off
	s_waitcnt vmcnt(8)
	s_waitcnt lgkmcnt(0)
	s_setprio 1
	s_barrier
	v_mfma_f32_16x16x32_bf16 v[62:65], v[88:91], v[108:111], v[62:65]
	v_mfma_f32_16x16x32_bf16 v[62:65], v[92:95], v[112:115], v[62:65]
	v_mfma_f32_16x16x32_bf16 v[54:57], v[92:95], v[120:123], v[54:57]
	v_mfma_f32_16x16x32_bf16 v[54:57], v[88:91], v[116:119], v[54:57]
	v_mfma_f32_16x16x32_bf16 v[46:49], v[88:91], v[124:127], v[46:49]
	v_mfma_f32_16x16x32_bf16 v[46:49], v[92:95], v[128:131], v[46:49]
	v_mfma_f32_16x16x32_bf16 v[38:41], v[92:95], v[136:139], v[38:41]
	v_mfma_f32_16x16x32_bf16 v[38:41], v[88:91], v[132:135], v[38:41]
	v_mfma_f32_16x16x32_bf16 v[34:37], v[100:103], v[132:135], v[34:37]
	v_mfma_f32_16x16x32_bf16 v[34:37], v[104:107], v[136:139], v[34:37]
	v_mfma_f32_16x16x32_bf16 v[58:61], v[104:107], v[112:115], v[58:61]
	v_mfma_f32_16x16x32_bf16 v[58:61], v[100:103], v[108:111], v[58:61]
	v_mfma_f32_16x16x32_bf16 v[50:53], v[100:103], v[116:119], v[50:53]
	v_mfma_f32_16x16x32_bf16 v[50:53], v[104:107], v[120:123], v[50:53]
	v_mfma_f32_16x16x32_bf16 v[42:45], v[104:107], v[128:131], v[42:45]
	v_mfma_f32_16x16x32_bf16 v[42:45], v[100:103], v[124:127], v[42:45]
	s_setprio 0
	s_setprio 1
	s_setprio 0
	s_barrier
	s_add_i32 s54, s95, s29
	v_lshl_add_u64 v[96:97], v[96:97], 0, s[14:15]
	s_mov_b32 m0, s54
	ds_read_b128 v[108:111], v86 offset:49152
	ds_read_b128 v[112:115], v86 offset:50176
	ds_read_b128 v[116:119], v86 offset:51200
	ds_read_b128 v[120:123], v86 offset:52224
	ds_read_b128 v[124:127], v86 offset:53248
	ds_read_b128 v[128:131], v86 offset:54272
	ds_read_b128 v[132:135], v86 offset:55296
	ds_read_b128 v[136:139], v86 offset:56320
	global_load_lds_dwordx4 v[96:97], off
	s_add_i32 m0, s54, 0x2000
	s_add_u32 s52, s52, 0x100080
	v_lshl_add_u64 v[96:97], v[140:141], 0, s[14:15]
	s_addc_u32 s53, s53, 0
	global_load_lds_dwordx4 v[96:97], off
	v_lshl_add_u64 v[96:97], s[52:53], 0, v[78:79]
	s_mov_b32 m0, s92
	s_nop 0
	global_load_lds_dwordx4 v[96:97], off
	v_lshl_add_u64 v[96:97], s[52:53], 0, v[74:75]
	s_mov_b32 m0, s93
	s_nop 0
	global_load_lds_dwordx4 v[96:97], off
	v_lshl_add_u64 v[96:97], v[142:143], 0, s[14:15]
	s_mov_b32 m0, s90
	s_nop 0
	global_load_lds_dwordx4 v[96:97], off
	v_lshl_add_u64 v[96:97], v[144:145], 0, s[14:15]
	s_mov_b32 m0, s91
	s_nop 0
	global_load_lds_dwordx4 v[96:97], off
	s_waitcnt vmcnt(8)
	s_waitcnt lgkmcnt(0)
	s_setprio 1
	s_barrier
	v_mfma_f32_16x16x32_bf16 v[30:33], v[88:91], v[108:111], v[30:33]
	v_mfma_f32_16x16x32_bf16 v[30:33], v[92:95], v[112:115], v[30:33]
	v_mfma_f32_16x16x32_bf16 v[22:25], v[92:95], v[120:123], v[22:25]
	v_mfma_f32_16x16x32_bf16 v[22:25], v[88:91], v[116:119], v[22:25]
	v_mfma_f32_16x16x32_bf16 v[14:17], v[88:91], v[124:127], v[14:17]
	v_mfma_f32_16x16x32_bf16 v[14:17], v[92:95], v[128:131], v[14:17]
	v_mfma_f32_16x16x32_bf16 v[6:9], v[92:95], v[136:139], v[6:9]
	v_mfma_f32_16x16x32_bf16 v[6:9], v[88:91], v[132:135], v[6:9]
	v_mfma_f32_16x16x32_bf16 v[2:5], v[100:103], v[132:135], v[2:5]
	v_mfma_f32_16x16x32_bf16 v[2:5], v[104:107], v[136:139], v[2:5]
	v_mfma_f32_16x16x32_bf16 v[26:29], v[104:107], v[112:115], v[26:29]
	v_mfma_f32_16x16x32_bf16 v[26:29], v[100:103], v[108:111], v[26:29]
	v_mfma_f32_16x16x32_bf16 v[18:21], v[100:103], v[116:119], v[18:21]
	v_mfma_f32_16x16x32_bf16 v[18:21], v[104:107], v[120:123], v[18:21]
	v_mfma_f32_16x16x32_bf16 v[10:13], v[104:107], v[128:131], v[10:13]
	v_mfma_f32_16x16x32_bf16 v[10:13], v[100:103], v[124:127], v[10:13]
	s_setprio 0
	s_setprio 1
	s_setprio 0
	s_barrier
	s_cmp_ge_u32 s10, s28
	s_mov_b32 s52, s10
	s_cbranch_scc0 .LBB0_592
	s_cmpk_lt_u32 s26, 0x100
	s_cbranch_scc0 .LBB0_482
	s_barrier
	s_branch .LBB0_482

; #define PG8_STAGE(bufoff, gbase, voff) do { _Pragma("unroll") for (int _i = 0; _i < 2; ++_i) \
;         __builtin_amdgcn_global_load_lds((const unsigned*)((const char*)(gbase) + (voff)[_i]), (PG8_LAS unsigned*)(lds + (bufoff) + ldsw + _i * 8192), 16, 0, 0); } while (0)
; #define PG8_LDA(dst, b, h) do { _Pragma("unroll") for (int m = 0; m < 4; ++m) _Pragma("unroll") for (int k = 0; k < 2; ++k) dst[m][k] = *(const PG8_LAS bf16x8*)(lds + PG8_SA(b, h) + aoff + m * 2048 + k * 1024); } while (0)
; #define PG8_LDB(dst, b, h) do { _Pragma("unroll") for (int n = 0; n < 2; ++n) _Pragma("unroll") for (int k = 0; k < 2; ++k) dst[n][k] = *(const PG8_LAS bf16x8*)(lds + PG8_SB(b, h) + boff + n * 2048 + k * 1024); } while (0)
; #define PG8_MMA(ai, bj, At, Bt) do { __builtin_amdgcn_s_setprio(1); _Pragma("unroll") for (int m = 0; m < 4; ++m) _Pragma("unroll") for (int n = 0; n < 2; ++n) _Pragma("unroll") for (int k = 0; k < 2; ++k) \
;         acc[ai][bj][m][n] = __builtin_amdgcn_mfma_f32_16x16x32_bf16(Bt[n][k], At[m][k], acc[ai][bj][m][n], 0, 0, 0); __builtin_amdgcn_s_setprio(0); } while (0)
; #define PG8_WAIT_V(n) asm volatile("s_waitcnt vmcnt(" #n ")" ::: "memory")
; #define PG8_WAIT_L(n) asm volatile("s_waitcnt lgkmcnt(" #n ")" ::: "memory")
; #define PG8_BAR __builtin_amdgcn_s_barrier()
; #define PG8_SCHED __builtin_amdgcn_sched_barrier(0)
; template <class Epi, class Sched, bool ALIGN_EPI = false, bool SP2 = false>
; __device__ __forceinline__ void gemm_phase(PG8_LAS unsigned char* lds, const Gemm g, const Sched& S, const Epi& E) {
;     ...
;             const bool last = (t == nt - 2);
;             const char* a1 = cA + (size_t)(t + 1) * kstep;
;             const char* a2 = last ? nA : cA + (size_t)(t + 2) * kstep; const char* b2 = last ? nB : cB + (size_t)(t + 2) * kstep;
;             const char* a3 = a2 + kstep; const char* b3 = b2 + kstep;
;             if (last && has_next) S.a_ready(nxt);
;             if constexpr (SP2) {
;             PG8_LDB(B0, 0, 0); PG8_LDB(B1, 0, 1); PG8_SCHED; PG8_LDA(At, 0, 0); PG8_STAGE(PG8_SA(1, 1), a1 + hstep, voffA);
;             PG8_WAIT_V(8); PG8_WAIT_L(0); PG8_BAR; PG8_MMA(0, 0, At, B0); PG8_MMA(0, 1, At, B1); PG8_BAR; PG8_SCHED;
;             PG8_LDA(At, 0, 1); PG8_STAGE(PG8_SB(0, 0), b2, voffB); PG8_STAGE(PG8_SB(0, 1), b2 + hstep, voffB); PG8_STAGE(PG8_SA(0, 0), a2, voffA);
.LBB0_1062:
	ds_read_b128 v[146:149], v155
	ds_read_b128 v[158:161], v155 offset:1024
	ds_read_b128 v[168:171], v155 offset:2048
	ds_read_b128 v[172:175], v155 offset:3072
	ds_read_b128 v[176:179], v156
	ds_read_b128 v[180:183], v156 offset:1024
	ds_read_b128 v[184:187], v156 offset:2048
	ds_read_b128 v[188:191], v156 offset:3072
	s_add_u32 s72, s70, 0xfff80080
	s_addc_u32 s73, s71, -1
	s_cmp_eq_u32 s77, 28
	s_cselect_b32 s75, s34, s73
	s_cselect_b32 s74, s35, s72
	s_cselect_b32 s73, s61, s76
	s_cselect_b32 s72, s63, s69
	v_lshl_add_u64 v[150:151], s[70:71], 0, v[138:139]
	s_add_i32 m0, s25, 0xc000
	ds_read_b128 v[200:203], v157
	ds_read_b128 v[204:207], v157 offset:1024
	ds_read_b128 v[208:211], v157 offset:2048
	ds_read_b128 v[212:215], v157 offset:3072
	ds_read_b128 v[216:219], v157 offset:4096
	ds_read_b128 v[220:223], v157 offset:5120
	ds_read_b128 v[224:227], v157 offset:6144
	ds_read_b128 v[228:231], v157 offset:7168
	global_load_lds_dwordx4 v[150:151], off
	v_lshl_add_u64 v[150:151], s[70:71], 0, v[140:141]
	s_add_i32 m0, s25, 0xe000
	s_nop 0
	global_load_lds_dwordx4 v[150:151], off
	s_waitcnt vmcnt(8)
	s_waitcnt lgkmcnt(0)
	s_setprio 1
	s_barrier
	v_mfma_f32_16x16x32_bf16 v[126:129], v[146:149], v[200:203], v[126:129]
	v_mfma_f32_16x16x32_bf16 v[126:129], v[158:161], v[204:207], v[126:129]
	v_mfma_f32_16x16x32_bf16 v[110:113], v[158:161], v[212:215], v[110:113]
	v_mfma_f32_16x16x32_bf16 v[110:113], v[146:149], v[208:211], v[110:113]
	v_mfma_f32_16x16x32_bf16 v[94:97], v[146:149], v[216:219], v[94:97]
	v_mfma_f32_16x16x32_bf16 v[94:97], v[158:161], v[220:223], v[94:97]
	v_mfma_f32_16x16x32_bf16 v[78:81], v[158:161], v[228:231], v[78:81]
	v_mfma_f32_16x16x32_bf16 v[78:81], v[146:149], v[224:227], v[78:81]
	v_mfma_f32_16x16x32_bf16 v[74:77], v[168:171], v[224:227], v[74:77]
	v_mfma_f32_16x16x32_bf16 v[74:77], v[172:175], v[228:231], v[74:77]
	v_mfma_f32_16x16x32_bf16 v[122:125], v[172:175], v[204:207], v[122:125]
	v_mfma_f32_16x16x32_bf16 v[122:125], v[168:171], v[200:203], v[122:125]
	v_mfma_f32_16x16x32_bf16 v[106:109], v[168:171], v[208:211], v[106:109]
	v_mfma_f32_16x16x32_bf16 v[106:109], v[172:175], v[212:215], v[106:109]
	v_mfma_f32_16x16x32_bf16 v[90:93], v[172:175], v[220:223], v[90:93]
	v_mfma_f32_16x16x32_bf16 v[90:93], v[168:171], v[216:219], v[90:93]
	s_setprio 0
	s_setprio 1
	v_mfma_f32_16x16x32_bf16 v[118:121], v[176:179], v[200:203], v[118:121]
	v_mfma_f32_16x16x32_bf16 v[118:121], v[180:183], v[204:207], v[118:121]
	v_mfma_f32_16x16x32_bf16 v[102:105], v[180:183], v[212:215], v[102:105]
	v_mfma_f32_16x16x32_bf16 v[102:105], v[176:179], v[208:211], v[102:105]
	v_mfma_f32_16x16x32_bf16 v[86:89], v[176:179], v[216:219], v[86:89]
	v_mfma_f32_16x16x32_bf16 v[86:89], v[180:183], v[220:223], v[86:89]
	v_mfma_f32_16x16x32_bf16 v[70:73], v[180:183], v[228:231], v[70:73]
	v_mfma_f32_16x16x32_bf16 v[70:73], v[176:179], v[224:227], v[70:73]
	v_mfma_f32_16x16x32_bf16 v[66:69], v[184:187], v[224:227], v[66:69]
	v_mfma_f32_16x16x32_bf16 v[66:69], v[188:191], v[228:231], v[66:69]
	v_mfma_f32_16x16x32_bf16 v[114:117], v[188:191], v[204:207], v[114:117]
	v_mfma_f32_16x16x32_bf16 v[114:117], v[184:187], v[200:203], v[114:117]
	v_mfma_f32_16x16x32_bf16 v[98:101], v[184:187], v[208:211], v[98:101]
	v_mfma_f32_16x16x32_bf16 v[98:101], v[188:191], v[212:215], v[98:101]
	v_mfma_f32_16x16x32_bf16 v[82:85], v[188:191], v[220:223], v[82:85]
	v_mfma_f32_16x16x32_bf16 v[82:85], v[184:187], v[216:219], v[82:85]
	s_barrier
	s_setprio 0
	s_add_i32 s78, s31, s2
	v_lshl_add_u64 v[150:151], s[72:73], 0, v[134:135]
	s_mov_b32 m0, s78
	ds_read_b128 v[200:203], v157 offset:16384
	ds_read_b128 v[204:207], v157 offset:17408
	ds_read_b128 v[208:211], v157 offset:18432
	ds_read_b128 v[212:215], v157 offset:19456
	ds_read_b128 v[216:219], v157 offset:20480
	ds_read_b128 v[220:223], v157 offset:21504
	ds_read_b128 v[224:227], v157 offset:22528
	ds_read_b128 v[228:231], v157 offset:23552
	global_load_lds_dwordx4 v[150:151], off
	s_add_i32 m0, s78, 0x2000
	s_add_u32 s78, s72, 0x80000
	v_lshl_add_u64 v[162:163], s[72:73], 0, v[130:131]
	s_addc_u32 s79, s73, 0
	s_add_i32 s80, s40, s2
	global_load_lds_dwordx4 v[162:163], off
	v_lshl_add_u64 v[192:193], s[78:79], 0, v[134:135]
	s_mov_b32 m0, s80
	v_lshl_add_u64 v[232:233], s[74:75], 0, v[132:133]
	global_load_lds_dwordx4 v[192:193], off
	v_lshl_add_u64 v[192:193], s[78:79], 0, v[130:131]
	s_add_i32 m0, s80, 0x2000
	s_nop 0
	global_load_lds_dwordx4 v[192:193], off
	v_lshl_add_u64 v[192:193], s[74:75], 0, v[136:137]
	s_mov_b32 m0, s25
	s_nop 0
	global_load_lds_dwordx4 v[192:193], off
	s_mov_b32 m0, s26
	s_nop 0
	global_load_lds_dwordx4 v[232:233], off
	s_waitcnt vmcnt(8)
	s_waitcnt lgkmcnt(0)
	s_setprio 1
	s_barrier
; #define PG8_STAGE(bufoff, gbase, voff) do { _Pragma("unroll") for (int _i = 0; _i < 2; ++_i) \
;         __builtin_amdgcn_global_load_lds((const unsigned*)((const char*)(gbase) + (voff)[_i]), (PG8_LAS unsigned*)(lds + (bufoff) + ldsw + _i * 8192), 16, 0, 0); } while (0)
; #define PG8_LDA(dst, b, h) do { _Pragma("unroll") for (int m = 0; m < 4; ++m) _Pragma("unroll") for (int k = 0; k < 2; ++k) dst[m][k] = *(const PG8_LAS bf16x8*)(lds + PG8_SA(b, h) + aoff + m * 2048 + k * 1024); } while (0)
; #define PG8_LDB(dst, b, h) do { _Pragma("unroll") for (int n = 0; n < 2; ++n) _Pragma("unroll") for (int k = 0; k < 2; ++k) dst[n][k] = *(const PG8_LAS bf16x8*)(lds + PG8_SB(b, h) + boff + n * 2048 + k * 1024); } while (0)
; #define PG8_MMA(ai, bj, At, Bt) do { __builtin_amdgcn_s_setprio(1); _Pragma("unroll") for (int m = 0; m < 4; ++m) _Pragma("unroll") for (int n = 0; n < 2; ++n) _Pragma("unroll") for (int k = 0; k < 2; ++k) \
;         acc[ai][bj][m][n] = __builtin_amdgcn_mfma_f32_16x16x32_bf16(Bt[n][k], At[m][k], acc[ai][bj][m][n], 0, 0, 0); __builtin_amdgcn_s_setprio(0); } while (0)
; #define PG8_WAIT_V(n) asm volatile("s_waitcnt vmcnt(" #n ")" ::: "memory")
; #define PG8_WAIT_L(n) asm volatile("s_waitcnt lgkmcnt(" #n ")" ::: "memory")
; #define PG8_BAR __builtin_amdgcn_s_barrier()
; #define PG8_SCHED __builtin_amdgcn_sched_barrier(0)
; template <class Epi, class Sched, bool ALIGN_EPI = false, bool SP2 = false>
; __device__ __forceinline__ void gemm_phase(PG8_LAS unsigned char* lds, const Gemm g, const Sched& S, const Epi& E) {
;     ...
;             PG8_WAIT_V(8); PG8_WAIT_L(0); PG8_BAR; PG8_MMA(1, 0, At, B0); PG8_MMA(1, 1, At, B1); PG8_BAR; PG8_SCHED;
;             PG8_LDB(B0, 1, 0); PG8_LDB(B1, 1, 1); PG8_SCHED; PG8_LDA(At, 1, 0); PG8_STAGE(PG8_SA(0, 1), a2 + hstep, voffA);
;             PG8_WAIT_V(8); PG8_WAIT_L(0); PG8_BAR; PG8_MMA(0, 0, At, B0); PG8_MMA(0, 1, At, B1); PG8_BAR; PG8_SCHED;
	v_mfma_f32_16x16x32_bf16 v[62:65], v[146:149], v[200:203], v[62:65]
	v_mfma_f32_16x16x32_bf16 v[62:65], v[158:161], v[204:207], v[62:65]
	v_mfma_f32_16x16x32_bf16 v[46:49], v[158:161], v[212:215], v[46:49]
	v_mfma_f32_16x16x32_bf16 v[46:49], v[146:149], v[208:211], v[46:49]
	v_mfma_f32_16x16x32_bf16 v[30:33], v[146:149], v[216:219], v[30:33]
	v_mfma_f32_16x16x32_bf16 v[30:33], v[158:161], v[220:223], v[30:33]
	v_mfma_f32_16x16x32_bf16 v[14:17], v[158:161], v[228:231], v[14:17]
	v_mfma_f32_16x16x32_bf16 v[14:17], v[146:149], v[224:227], v[14:17]
	v_mfma_f32_16x16x32_bf16 v[10:13], v[168:171], v[224:227], v[10:13]
	v_mfma_f32_16x16x32_bf16 v[10:13], v[172:175], v[228:231], v[10:13]
	v_mfma_f32_16x16x32_bf16 v[58:61], v[172:175], v[204:207], v[58:61]
	v_mfma_f32_16x16x32_bf16 v[58:61], v[168:171], v[200:203], v[58:61]
	v_mfma_f32_16x16x32_bf16 v[42:45], v[168:171], v[208:211], v[42:45]
	v_mfma_f32_16x16x32_bf16 v[42:45], v[172:175], v[212:215], v[42:45]
	v_mfma_f32_16x16x32_bf16 v[26:29], v[172:175], v[220:223], v[26:29]
	v_mfma_f32_16x16x32_bf16 v[26:29], v[168:171], v[216:219], v[26:29]
	s_setprio 0
	s_setprio 1
	v_mfma_f32_16x16x32_bf16 v[54:57], v[176:179], v[200:203], v[54:57]
	v_mfma_f32_16x16x32_bf16 v[54:57], v[180:183], v[204:207], v[54:57]
	v_mfma_f32_16x16x32_bf16 v[38:41], v[180:183], v[212:215], v[38:41]
	v_mfma_f32_16x16x32_bf16 v[38:41], v[176:179], v[208:211], v[38:41]
	v_mfma_f32_16x16x32_bf16 v[22:25], v[176:179], v[216:219], v[22:25]
	v_mfma_f32_16x16x32_bf16 v[22:25], v[180:183], v[220:223], v[22:25]
	v_mfma_f32_16x16x32_bf16 v[6:9], v[180:183], v[228:231], v[6:9]
	v_mfma_f32_16x16x32_bf16 v[6:9], v[176:179], v[224:227], v[6:9]
	v_mfma_f32_16x16x32_bf16 v[2:5], v[184:187], v[224:227], v[2:5]
	v_mfma_f32_16x16x32_bf16 v[2:5], v[188:191], v[228:231], v[2:5]
	v_mfma_f32_16x16x32_bf16 v[50:53], v[188:191], v[204:207], v[50:53]
	v_mfma_f32_16x16x32_bf16 v[50:53], v[184:187], v[200:203], v[50:53]
	v_mfma_f32_16x16x32_bf16 v[34:37], v[184:187], v[208:211], v[34:37]
	v_mfma_f32_16x16x32_bf16 v[34:37], v[188:191], v[212:215], v[34:37]
	v_mfma_f32_16x16x32_bf16 v[18:21], v[188:191], v[220:223], v[18:21]
	v_mfma_f32_16x16x32_bf16 v[18:21], v[184:187], v[216:219], v[18:21]
	s_barrier
	s_setprio 0
	s_add_i32 s78, 0, 0x18000
	v_add_u32_e32 v166, s78, v153
	s_add_i32 s79, 0, 0x1c000
	ds_read_b128 v[146:149], v166
	ds_read_b128 v[158:161], v166 offset:1024
	ds_read_b128 v[168:171], v166 offset:2048
	ds_read_b128 v[172:175], v166 offset:3072
	v_add_u32_e32 v166, s79, v153
	ds_read_b128 v[176:179], v166
	ds_read_b128 v[180:183], v166 offset:1024
	ds_read_b128 v[184:187], v166 offset:2048
	ds_read_b128 v[188:191], v166 offset:3072
	s_add_u32 s74, s74, 0x80000
	s_addc_u32 s75, s75, 0
	s_mov_b32 m0, s27
	v_lshl_add_u64 v[240:241], s[74:75], 0, v[136:137]
	ds_read_b128 v[200:203], v157 offset:32768
	ds_read_b128 v[204:207], v157 offset:33792
	ds_read_b128 v[208:211], v157 offset:34816
	ds_read_b128 v[212:215], v157 offset:35840
	ds_read_b128 v[216:219], v157 offset:36864
	ds_read_b128 v[220:223], v157 offset:37888
	ds_read_b128 v[224:227], v157 offset:38912
	ds_read_b128 v[228:231], v157 offset:39936
	global_load_lds_dwordx4 v[240:241], off
	v_lshl_add_u64 v[240:241], s[74:75], 0, v[132:133]
	s_mov_b32 m0, s28
	s_nop 0
	global_load_lds_dwordx4 v[240:241], off
	s_waitcnt vmcnt(8)
	s_waitcnt lgkmcnt(0)
	s_setprio 1
	s_barrier
	v_mfma_f32_16x16x32_bf16 v[126:129], v[146:149], v[200:203], v[126:129]
	v_mfma_f32_16x16x32_bf16 v[126:129], v[158:161], v[204:207], v[126:129]
	v_mfma_f32_16x16x32_bf16 v[110:113], v[158:161], v[212:215], v[110:113]
	v_mfma_f32_16x16x32_bf16 v[110:113], v[146:149], v[208:211], v[110:113]
	v_mfma_f32_16x16x32_bf16 v[94:97], v[146:149], v[216:219], v[94:97]
	v_mfma_f32_16x16x32_bf16 v[94:97], v[158:161], v[220:223], v[94:97]
	v_mfma_f32_16x16x32_bf16 v[78:81], v[158:161], v[228:231], v[78:81]
	v_mfma_f32_16x16x32_bf16 v[78:81], v[146:149], v[224:227], v[78:81]
	v_mfma_f32_16x16x32_bf16 v[74:77], v[168:171], v[224:227], v[74:77]
	v_mfma_f32_16x16x32_bf16 v[74:77], v[172:175], v[228:231], v[74:77]
	v_mfma_f32_16x16x32_bf16 v[122:125], v[172:175], v[204:207], v[122:125]
	v_mfma_f32_16x16x32_bf16 v[122:125], v[168:171], v[200:203], v[122:125]
	v_mfma_f32_16x16x32_bf16 v[106:109], v[168:171], v[208:211], v[106:109]
	v_mfma_f32_16x16x32_bf16 v[106:109], v[172:175], v[212:215], v[106:109]
	v_mfma_f32_16x16x32_bf16 v[90:93], v[172:175], v[220:223], v[90:93]
	v_mfma_f32_16x16x32_bf16 v[90:93], v[168:171], v[216:219], v[90:93]
	s_setprio 0
	s_setprio 1
	v_mfma_f32_16x16x32_bf16 v[118:121], v[176:179], v[200:203], v[118:121]
	v_mfma_f32_16x16x32_bf16 v[118:121], v[180:183], v[204:207], v[118:121]
	v_mfma_f32_16x16x32_bf16 v[102:105], v[180:183], v[212:215], v[102:105]
	v_mfma_f32_16x16x32_bf16 v[102:105], v[176:179], v[208:211], v[102:105]
	v_mfma_f32_16x16x32_bf16 v[86:89], v[176:179], v[216:219], v[86:89]
	v_mfma_f32_16x16x32_bf16 v[86:89], v[180:183], v[220:223], v[86:89]
	v_mfma_f32_16x16x32_bf16 v[70:73], v[180:183], v[228:231], v[70:73]
	v_mfma_f32_16x16x32_bf16 v[70:73], v[176:179], v[224:227], v[70:73]
	v_mfma_f32_16x16x32_bf16 v[66:69], v[184:187], v[224:227], v[66:69]
	v_mfma_f32_16x16x32_bf16 v[66:69], v[188:191], v[228:231], v[66:69]
	v_mfma_f32_16x16x32_bf16 v[114:117], v[188:191], v[204:207], v[114:117]
	v_mfma_f32_16x16x32_bf16 v[114:117], v[184:187], v[200:203], v[114:117]
	v_mfma_f32_16x16x32_bf16 v[98:101], v[184:187], v[208:211], v[98:101]
	v_mfma_f32_16x16x32_bf16 v[98:101], v[188:191], v[212:215], v[98:101]
	v_mfma_f32_16x16x32_bf16 v[82:85], v[188:191], v[220:223], v[82:85]
	v_mfma_f32_16x16x32_bf16 v[82:85], v[184:187], v[216:219], v[82:85]
	s_barrier
; #define PG8_STAGE(bufoff, gbase, voff) do { _Pragma("unroll") for (int _i = 0; _i < 2; ++_i) \
;         __builtin_amdgcn_global_load_lds((const unsigned*)((const char*)(gbase) + (voff)[_i]), (PG8_LAS unsigned*)(lds + (bufoff) + ldsw + _i * 8192), 16, 0, 0); } while (0)
; #define PG8_LDA(dst, b, h) do { _Pragma("unroll") for (int m = 0; m < 4; ++m) _Pragma("unroll") for (int k = 0; k < 2; ++k) dst[m][k] = *(const PG8_LAS bf16x8*)(lds + PG8_SA(b, h) + aoff + m * 2048 + k * 1024); } while (0)
; #define PG8_MMA(ai, bj, At, Bt) do { __builtin_amdgcn_s_setprio(1); _Pragma("unroll") for (int m = 0; m < 4; ++m) _Pragma("unroll") for (int n = 0; n < 2; ++n) _Pragma("unroll") for (int k = 0; k < 2; ++k) \
;         acc[ai][bj][m][n] = __builtin_amdgcn_mfma_f32_16x16x32_bf16(Bt[n][k], At[m][k], acc[ai][bj][m][n], 0, 0, 0); __builtin_amdgcn_s_setprio(0); } while (0)
; #define PG8_WAIT_V(n) asm volatile("s_waitcnt vmcnt(" #n ")" ::: "memory")
; #define PG8_WAIT_L(n) asm volatile("s_waitcnt lgkmcnt(" #n ")" ::: "memory")
; #define PG8_BAR __builtin_amdgcn_s_barrier()
; #define PG8_SCHED __builtin_amdgcn_sched_barrier(0)
; template <class Epi, class Sched, bool ALIGN_EPI = false, bool SP2 = false>
; __device__ __forceinline__ void gemm_phase(PG8_LAS unsigned char* lds, const Gemm g, const Sched& S, const Epi& E) {
;     ...
;             PG8_LDA(At, 1, 1); PG8_STAGE(PG8_SB(1, 0), b3, voffB); PG8_STAGE(PG8_SB(1, 1), b3 + hstep, voffB); PG8_STAGE(PG8_SA(1, 0), a3, voffA);
;             PG8_WAIT_V(8); PG8_WAIT_L(0); PG8_BAR; PG8_MMA(1, 0, At, B0); PG8_MMA(1, 1, At, B1); PG8_BAR; PG8_SCHED;
;     ...
;         if constexpr (ALIGN_EPI) { if (wr == 0) PG8_BAR; }
	s_setprio 0
	s_add_i32 s74, s78, s2
	v_lshl_add_u64 v[150:151], v[150:151], 0, s[10:11]
	s_mov_b32 m0, s74
	ds_read_b128 v[200:203], v157 offset:49152
	ds_read_b128 v[204:207], v157 offset:50176
	ds_read_b128 v[208:211], v157 offset:51200
	ds_read_b128 v[212:215], v157 offset:52224
	ds_read_b128 v[216:219], v157 offset:53248
	ds_read_b128 v[220:223], v157 offset:54272
	ds_read_b128 v[224:227], v157 offset:55296
	ds_read_b128 v[228:231], v157 offset:56320
	global_load_lds_dwordx4 v[150:151], off
	s_add_i32 m0, s74, 0x2000
	s_add_u32 s72, s72, 0x80080
	v_lshl_add_u64 v[150:151], v[162:163], 0, s[10:11]
	s_addc_u32 s73, s73, 0
	s_add_i32 s74, s79, s2
	global_load_lds_dwordx4 v[150:151], off
	v_lshl_add_u64 v[150:151], s[72:73], 0, v[134:135]
	s_mov_b32 m0, s74
	s_nop 0
	global_load_lds_dwordx4 v[150:151], off
	v_lshl_add_u64 v[150:151], s[72:73], 0, v[130:131]
	s_add_i32 m0, s74, 0x2000
	s_nop 0
	global_load_lds_dwordx4 v[150:151], off
	v_lshl_add_u64 v[150:151], v[192:193], 0, s[10:11]
	s_mov_b32 m0, s30
	s_nop 0
	global_load_lds_dwordx4 v[150:151], off
	v_lshl_add_u64 v[150:151], v[232:233], 0, s[10:11]
	s_mov_b32 m0, s33
	s_nop 0
	global_load_lds_dwordx4 v[150:151], off
	s_waitcnt vmcnt(8)
	s_waitcnt lgkmcnt(0)
	s_setprio 1
	s_barrier
	v_mfma_f32_16x16x32_bf16 v[62:65], v[146:149], v[200:203], v[62:65]
	v_mfma_f32_16x16x32_bf16 v[62:65], v[158:161], v[204:207], v[62:65]
	v_mfma_f32_16x16x32_bf16 v[46:49], v[158:161], v[212:215], v[46:49]
	v_mfma_f32_16x16x32_bf16 v[46:49], v[146:149], v[208:211], v[46:49]
	v_mfma_f32_16x16x32_bf16 v[30:33], v[146:149], v[216:219], v[30:33]
	v_mfma_f32_16x16x32_bf16 v[30:33], v[158:161], v[220:223], v[30:33]
	v_mfma_f32_16x16x32_bf16 v[14:17], v[158:161], v[228:231], v[14:17]
	v_mfma_f32_16x16x32_bf16 v[14:17], v[146:149], v[224:227], v[14:17]
	v_mfma_f32_16x16x32_bf16 v[10:13], v[168:171], v[224:227], v[10:13]
	v_mfma_f32_16x16x32_bf16 v[10:13], v[172:175], v[228:231], v[10:13]
	v_mfma_f32_16x16x32_bf16 v[58:61], v[172:175], v[204:207], v[58:61]
	v_mfma_f32_16x16x32_bf16 v[58:61], v[168:171], v[200:203], v[58:61]
	v_mfma_f32_16x16x32_bf16 v[42:45], v[168:171], v[208:211], v[42:45]
	v_mfma_f32_16x16x32_bf16 v[42:45], v[172:175], v[212:215], v[42:45]
	v_mfma_f32_16x16x32_bf16 v[26:29], v[172:175], v[220:223], v[26:29]
	v_mfma_f32_16x16x32_bf16 v[26:29], v[168:171], v[216:219], v[26:29]
	s_setprio 0
	s_setprio 1
	v_mfma_f32_16x16x32_bf16 v[54:57], v[176:179], v[200:203], v[54:57]
	v_mfma_f32_16x16x32_bf16 v[54:57], v[180:183], v[204:207], v[54:57]
	v_mfma_f32_16x16x32_bf16 v[38:41], v[180:183], v[212:215], v[38:41]
	v_mfma_f32_16x16x32_bf16 v[38:41], v[176:179], v[208:211], v[38:41]
	v_mfma_f32_16x16x32_bf16 v[22:25], v[176:179], v[216:219], v[22:25]
	v_mfma_f32_16x16x32_bf16 v[22:25], v[180:183], v[220:223], v[22:25]
	v_mfma_f32_16x16x32_bf16 v[6:9], v[180:183], v[228:231], v[6:9]
	v_mfma_f32_16x16x32_bf16 v[6:9], v[176:179], v[224:227], v[6:9]
	v_mfma_f32_16x16x32_bf16 v[2:5], v[184:187], v[224:227], v[2:5]
	v_mfma_f32_16x16x32_bf16 v[2:5], v[188:191], v[228:231], v[2:5]
	v_mfma_f32_16x16x32_bf16 v[50:53], v[188:191], v[204:207], v[50:53]
	v_mfma_f32_16x16x32_bf16 v[50:53], v[184:187], v[200:203], v[50:53]
	v_mfma_f32_16x16x32_bf16 v[34:37], v[184:187], v[208:211], v[34:37]
	v_mfma_f32_16x16x32_bf16 v[34:37], v[188:191], v[212:215], v[34:37]
	v_mfma_f32_16x16x32_bf16 v[18:21], v[188:191], v[220:223], v[18:21]
	v_mfma_f32_16x16x32_bf16 v[18:21], v[184:187], v[216:219], v[18:21]
	s_barrier
	s_setprio 0
	s_add_i32 s77, s77, 2
	s_add_u32 s70, s70, 0x100
	s_addc_u32 s71, s71, 0
	s_add_u32 s69, s69, 0x100
	s_addc_u32 s76, s76, 0
	s_cmp_gt_u32 s77, 29
	s_cbranch_scc0 .LBB0_1062
	s_and_b64 vcc, exec, s[48:49]
	s_cbranch_vccz .LBB0_1065
	s_barrier

; #define PG8_STAGE(bufoff, gbase, voff) do { _Pragma("unroll") for (int _i = 0; _i < 2; ++_i) \
;         __builtin_amdgcn_global_load_lds((const unsigned*)((const char*)(gbase) + (voff)[_i]), (PG8_LAS unsigned*)(lds + (bufoff) + ldsw + _i * 8192), 16, 0, 0); } while (0)
; #define PG8_LDA(dst, b, h) do { _Pragma("unroll") for (int m = 0; m < 4; ++m) _Pragma("unroll") for (int k = 0; k < 2; ++k) dst[m][k] = *(const PG8_LAS bf16x8*)(lds + PG8_SA(b, h) + aoff + m * 2048 + k * 1024); } while (0)
; #define PG8_LDB(dst, b, h) do { _Pragma("unroll") for (int n = 0; n < 2; ++n) _Pragma("unroll") for (int k = 0; k < 2; ++k) dst[n][k] = *(const PG8_LAS bf16x8*)(lds + PG8_SB(b, h) + boff + n * 2048 + k * 1024); } while (0)
; #define PG8_MMA(ai, bj, At, Bt) do { __builtin_amdgcn_s_setprio(1); _Pragma("unroll") for (int m = 0; m < 4; ++m) _Pragma("unroll") for (int n = 0; n < 2; ++n) _Pragma("unroll") for (int k = 0; k < 2; ++k) \
;         acc[ai][bj][m][n] = __builtin_amdgcn_mfma_f32_16x16x32_bf16(Bt[n][k], At[m][k], acc[ai][bj][m][n], 0, 0, 0); __builtin_amdgcn_s_setprio(0); } while (0)
; #define PG8_WAIT_V(n) asm volatile("s_waitcnt vmcnt(" #n ")" ::: "memory")
; #define PG8_WAIT_L(n) asm volatile("s_waitcnt lgkmcnt(" #n ")" ::: "memory")
; #define PG8_BAR __builtin_amdgcn_s_barrier()
; #define PG8_SCHED __builtin_amdgcn_sched_barrier(0)
; template <class Epi, class Sched, bool ALIGN_EPI = false, bool SP2 = false>
; __device__ __forceinline__ void gemm_phase(PG8_LAS unsigned char* lds, const Gemm g, const Sched& S, const Epi& E) {
;     ...
;             const bool last = (t == nt - 2);
;             const char* a1 = cA + (size_t)(t + 1) * kstep;
;             const char* a2 = last ? nA : cA + (size_t)(t + 2) * kstep; const char* b2 = last ? nB : cB + (size_t)(t + 2) * kstep;
;             const char* a3 = a2 + kstep; const char* b3 = b2 + kstep;
;             if (last && has_next) S.a_ready(nxt);
;             if constexpr (SP2) {
;             PG8_LDB(B0, 0, 0); PG8_LDB(B1, 0, 1); PG8_SCHED; PG8_LDA(At, 0, 0); PG8_STAGE(PG8_SA(1, 1), a1 + hstep, voffA);
;             PG8_WAIT_V(8); PG8_WAIT_L(0); PG8_BAR; PG8_MMA(0, 0, At, B0); PG8_MMA(0, 1, At, B1); PG8_BAR; PG8_SCHED;
;             PG8_LDA(At, 0, 1); PG8_STAGE(PG8_SB(0, 0), b2, voffB); PG8_STAGE(PG8_SB(0, 1), b2 + hstep, voffB); PG8_STAGE(PG8_SA(0, 0), a2, voffA);
.LBB0_1078:
	ds_read_b128 v[146:149], v155
	ds_read_b128 v[158:161], v155 offset:1024
	ds_read_b128 v[168:171], v155 offset:2048
	ds_read_b128 v[172:175], v155 offset:3072
	ds_read_b128 v[176:179], v156
	ds_read_b128 v[180:183], v156 offset:1024
	ds_read_b128 v[184:187], v156 offset:2048
	ds_read_b128 v[188:191], v156 offset:3072
	s_add_u32 s68, s66, 0xfff80080
	s_addc_u32 s69, s67, -1
	s_cmp_eq_u32 s73, 28
	s_cselect_b32 s71, s34, s69
	s_cselect_b32 s70, s35, s68
	s_cselect_b32 s69, s57, s72
	s_cselect_b32 s68, s59, s65
	v_lshl_add_u64 v[150:151], s[66:67], 0, v[138:139]
	s_add_i32 m0, s25, 0xc000
	ds_read_b128 v[200:203], v157
	ds_read_b128 v[204:207], v157 offset:1024
	ds_read_b128 v[208:211], v157 offset:2048
	ds_read_b128 v[212:215], v157 offset:3072
	ds_read_b128 v[216:219], v157 offset:4096
	ds_read_b128 v[220:223], v157 offset:5120
	ds_read_b128 v[224:227], v157 offset:6144
	ds_read_b128 v[228:231], v157 offset:7168
	global_load_lds_dwordx4 v[150:151], off
	v_lshl_add_u64 v[150:151], s[66:67], 0, v[140:141]
	s_add_i32 m0, s25, 0xe000
	s_nop 0
	global_load_lds_dwordx4 v[150:151], off
	s_waitcnt vmcnt(8)
	s_waitcnt lgkmcnt(0)
	s_setprio 1
	s_barrier
	v_mfma_f32_16x16x32_bf16 v[126:129], v[146:149], v[200:203], v[126:129]
	v_mfma_f32_16x16x32_bf16 v[126:129], v[158:161], v[204:207], v[126:129]
	v_mfma_f32_16x16x32_bf16 v[110:113], v[158:161], v[212:215], v[110:113]
	v_mfma_f32_16x16x32_bf16 v[110:113], v[146:149], v[208:211], v[110:113]
	v_mfma_f32_16x16x32_bf16 v[94:97], v[146:149], v[216:219], v[94:97]
	v_mfma_f32_16x16x32_bf16 v[94:97], v[158:161], v[220:223], v[94:97]
	v_mfma_f32_16x16x32_bf16 v[78:81], v[158:161], v[228:231], v[78:81]
	v_mfma_f32_16x16x32_bf16 v[78:81], v[146:149], v[224:227], v[78:81]
	v_mfma_f32_16x16x32_bf16 v[74:77], v[168:171], v[224:227], v[74:77]
	v_mfma_f32_16x16x32_bf16 v[74:77], v[172:175], v[228:231], v[74:77]
	v_mfma_f32_16x16x32_bf16 v[122:125], v[172:175], v[204:207], v[122:125]
	v_mfma_f32_16x16x32_bf16 v[122:125], v[168:171], v[200:203], v[122:125]
	v_mfma_f32_16x16x32_bf16 v[106:109], v[168:171], v[208:211], v[106:109]
	v_mfma_f32_16x16x32_bf16 v[106:109], v[172:175], v[212:215], v[106:109]
	v_mfma_f32_16x16x32_bf16 v[90:93], v[172:175], v[220:223], v[90:93]
	v_mfma_f32_16x16x32_bf16 v[90:93], v[168:171], v[216:219], v[90:93]
	s_setprio 0
	s_setprio 1
	v_mfma_f32_16x16x32_bf16 v[118:121], v[176:179], v[200:203], v[118:121]
	v_mfma_f32_16x16x32_bf16 v[118:121], v[180:183], v[204:207], v[118:121]
	v_mfma_f32_16x16x32_bf16 v[102:105], v[180:183], v[212:215], v[102:105]
	v_mfma_f32_16x16x32_bf16 v[102:105], v[176:179], v[208:211], v[102:105]
	v_mfma_f32_16x16x32_bf16 v[86:89], v[176:179], v[216:219], v[86:89]
	v_mfma_f32_16x16x32_bf16 v[86:89], v[180:183], v[220:223], v[86:89]
	v_mfma_f32_16x16x32_bf16 v[70:73], v[180:183], v[228:231], v[70:73]
	v_mfma_f32_16x16x32_bf16 v[70:73], v[176:179], v[224:227], v[70:73]
	v_mfma_f32_16x16x32_bf16 v[66:69], v[184:187], v[224:227], v[66:69]
	v_mfma_f32_16x16x32_bf16 v[66:69], v[188:191], v[228:231], v[66:69]
	v_mfma_f32_16x16x32_bf16 v[114:117], v[188:191], v[204:207], v[114:117]
	v_mfma_f32_16x16x32_bf16 v[114:117], v[184:187], v[200:203], v[114:117]
	v_mfma_f32_16x16x32_bf16 v[98:101], v[184:187], v[208:211], v[98:101]
	v_mfma_f32_16x16x32_bf16 v[98:101], v[188:191], v[212:215], v[98:101]
	v_mfma_f32_16x16x32_bf16 v[82:85], v[188:191], v[220:223], v[82:85]
	v_mfma_f32_16x16x32_bf16 v[82:85], v[184:187], v[216:219], v[82:85]
	s_barrier
	s_setprio 0
	s_add_i32 s74, s31, s2
	v_lshl_add_u64 v[150:151], s[68:69], 0, v[134:135]
	s_mov_b32 m0, s74
	ds_read_b128 v[200:203], v157 offset:16384
	ds_read_b128 v[204:207], v157 offset:17408
	ds_read_b128 v[208:211], v157 offset:18432
	ds_read_b128 v[212:215], v157 offset:19456
	ds_read_b128 v[216:219], v157 offset:20480
	ds_read_b128 v[220:223], v157 offset:21504
	ds_read_b128 v[224:227], v157 offset:22528
	ds_read_b128 v[228:231], v157 offset:23552
	global_load_lds_dwordx4 v[150:151], off
	s_add_i32 m0, s74, 0x2000
	s_add_u32 s74, s68, 0x80000
	v_lshl_add_u64 v[162:163], s[68:69], 0, v[130:131]
	s_addc_u32 s75, s69, 0
	s_add_i32 s76, s40, s2
	global_load_lds_dwordx4 v[162:163], off
	v_lshl_add_u64 v[192:193], s[74:75], 0, v[134:135]
	s_mov_b32 m0, s76
	v_lshl_add_u64 v[232:233], s[70:71], 0, v[132:133]
	global_load_lds_dwordx4 v[192:193], off
	v_lshl_add_u64 v[192:193], s[74:75], 0, v[130:131]
	s_add_i32 m0, s76, 0x2000
	s_nop 0
	global_load_lds_dwordx4 v[192:193], off
	v_lshl_add_u64 v[192:193], s[70:71], 0, v[136:137]
	s_mov_b32 m0, s25
	s_nop 0
	global_load_lds_dwordx4 v[192:193], off
	s_mov_b32 m0, s26
	s_nop 0
	global_load_lds_dwordx4 v[232:233], off
	s_waitcnt vmcnt(8)
	s_waitcnt lgkmcnt(0)
	s_setprio 1
	s_barrier
; #define PG8_STAGE(bufoff, gbase, voff) do { _Pragma("unroll") for (int _i = 0; _i < 2; ++_i) \
;         __builtin_amdgcn_global_load_lds((const unsigned*)((const char*)(gbase) + (voff)[_i]), (PG8_LAS unsigned*)(lds + (bufoff) + ldsw + _i * 8192), 16, 0, 0); } while (0)
; #define PG8_LDA(dst, b, h) do { _Pragma("unroll") for (int m = 0; m < 4; ++m) _Pragma("unroll") for (int k = 0; k < 2; ++k) dst[m][k] = *(const PG8_LAS bf16x8*)(lds + PG8_SA(b, h) + aoff + m * 2048 + k * 1024); } while (0)
; #define PG8_LDB(dst, b, h) do { _Pragma("unroll") for (int n = 0; n < 2; ++n) _Pragma("unroll") for (int k = 0; k < 2; ++k) dst[n][k] = *(const PG8_LAS bf16x8*)(lds + PG8_SB(b, h) + boff + n * 2048 + k * 1024); } while (0)
; #define PG8_MMA(ai, bj, At, Bt) do { __builtin_amdgcn_s_setprio(1); _Pragma("unroll") for (int m = 0; m < 4; ++m) _Pragma("unroll") for (int n = 0; n < 2; ++n) _Pragma("unroll") for (int k = 0; k < 2; ++k) \
;         acc[ai][bj][m][n] = __builtin_amdgcn_mfma_f32_16x16x32_bf16(Bt[n][k], At[m][k], acc[ai][bj][m][n], 0, 0, 0); __builtin_amdgcn_s_setprio(0); } while (0)
; #define PG8_WAIT_V(n) asm volatile("s_waitcnt vmcnt(" #n ")" ::: "memory")
; #define PG8_WAIT_L(n) asm volatile("s_waitcnt lgkmcnt(" #n ")" ::: "memory")
; #define PG8_BAR __builtin_amdgcn_s_barrier()
; #define PG8_SCHED __builtin_amdgcn_sched_barrier(0)
; template <class Epi, class Sched, bool ALIGN_EPI = false, bool SP2 = false>
; __device__ __forceinline__ void gemm_phase(PG8_LAS unsigned char* lds, const Gemm g, const Sched& S, const Epi& E) {
;     ...
;             PG8_WAIT_V(8); PG8_WAIT_L(0); PG8_BAR; PG8_MMA(1, 0, At, B0); PG8_MMA(1, 1, At, B1); PG8_BAR; PG8_SCHED;
;             PG8_LDB(B0, 1, 0); PG8_LDB(B1, 1, 1); PG8_SCHED; PG8_LDA(At, 1, 0); PG8_STAGE(PG8_SA(0, 1), a2 + hstep, voffA);
;             PG8_WAIT_V(8); PG8_WAIT_L(0); PG8_BAR; PG8_MMA(0, 0, At, B0); PG8_MMA(0, 1, At, B1); PG8_BAR; PG8_SCHED;
	v_mfma_f32_16x16x32_bf16 v[62:65], v[146:149], v[200:203], v[62:65]
	v_mfma_f32_16x16x32_bf16 v[62:65], v[158:161], v[204:207], v[62:65]
	v_mfma_f32_16x16x32_bf16 v[46:49], v[158:161], v[212:215], v[46:49]
	v_mfma_f32_16x16x32_bf16 v[46:49], v[146:149], v[208:211], v[46:49]
	v_mfma_f32_16x16x32_bf16 v[30:33], v[146:149], v[216:219], v[30:33]
	v_mfma_f32_16x16x32_bf16 v[30:33], v[158:161], v[220:223], v[30:33]
	v_mfma_f32_16x16x32_bf16 v[14:17], v[158:161], v[228:231], v[14:17]
	v_mfma_f32_16x16x32_bf16 v[14:17], v[146:149], v[224:227], v[14:17]
	v_mfma_f32_16x16x32_bf16 v[10:13], v[168:171], v[224:227], v[10:13]
	v_mfma_f32_16x16x32_bf16 v[10:13], v[172:175], v[228:231], v[10:13]
	v_mfma_f32_16x16x32_bf16 v[58:61], v[172:175], v[204:207], v[58:61]
	v_mfma_f32_16x16x32_bf16 v[58:61], v[168:171], v[200:203], v[58:61]
	v_mfma_f32_16x16x32_bf16 v[42:45], v[168:171], v[208:211], v[42:45]
	v_mfma_f32_16x16x32_bf16 v[42:45], v[172:175], v[212:215], v[42:45]
	v_mfma_f32_16x16x32_bf16 v[26:29], v[172:175], v[220:223], v[26:29]
	v_mfma_f32_16x16x32_bf16 v[26:29], v[168:171], v[216:219], v[26:29]
	s_setprio 0
	s_setprio 1
	v_mfma_f32_16x16x32_bf16 v[54:57], v[176:179], v[200:203], v[54:57]
	v_mfma_f32_16x16x32_bf16 v[54:57], v[180:183], v[204:207], v[54:57]
	v_mfma_f32_16x16x32_bf16 v[38:41], v[180:183], v[212:215], v[38:41]
	v_mfma_f32_16x16x32_bf16 v[38:41], v[176:179], v[208:211], v[38:41]
	v_mfma_f32_16x16x32_bf16 v[22:25], v[176:179], v[216:219], v[22:25]
	v_mfma_f32_16x16x32_bf16 v[22:25], v[180:183], v[220:223], v[22:25]
	v_mfma_f32_16x16x32_bf16 v[6:9], v[180:183], v[228:231], v[6:9]
	v_mfma_f32_16x16x32_bf16 v[6:9], v[176:179], v[224:227], v[6:9]
	v_mfma_f32_16x16x32_bf16 v[2:5], v[184:187], v[224:227], v[2:5]
	v_mfma_f32_16x16x32_bf16 v[2:5], v[188:191], v[228:231], v[2:5]
	v_mfma_f32_16x16x32_bf16 v[50:53], v[188:191], v[204:207], v[50:53]
	v_mfma_f32_16x16x32_bf16 v[50:53], v[184:187], v[200:203], v[50:53]
	v_mfma_f32_16x16x32_bf16 v[34:37], v[184:187], v[208:211], v[34:37]
	v_mfma_f32_16x16x32_bf16 v[34:37], v[188:191], v[212:215], v[34:37]
	v_mfma_f32_16x16x32_bf16 v[18:21], v[188:191], v[220:223], v[18:21]
	v_mfma_f32_16x16x32_bf16 v[18:21], v[184:187], v[216:219], v[18:21]
	s_barrier
	s_setprio 0
	s_add_i32 s74, 0, 0x18000
	v_add_u32_e32 v166, s74, v153
	s_add_i32 s75, 0, 0x1c000
	ds_read_b128 v[146:149], v166
	ds_read_b128 v[158:161], v166 offset:1024
	ds_read_b128 v[168:171], v166 offset:2048
	ds_read_b128 v[172:175], v166 offset:3072
	v_add_u32_e32 v166, s75, v153
	ds_read_b128 v[176:179], v166
	ds_read_b128 v[180:183], v166 offset:1024
	ds_read_b128 v[184:187], v166 offset:2048
	ds_read_b128 v[188:191], v166 offset:3072
	s_add_u32 s70, s70, 0x80000
	s_addc_u32 s71, s71, 0
	s_mov_b32 m0, s27
	v_lshl_add_u64 v[240:241], s[70:71], 0, v[136:137]
	ds_read_b128 v[200:203], v157 offset:32768
	ds_read_b128 v[204:207], v157 offset:33792
	ds_read_b128 v[208:211], v157 offset:34816
	ds_read_b128 v[212:215], v157 offset:35840
	ds_read_b128 v[216:219], v157 offset:36864
	ds_read_b128 v[220:223], v157 offset:37888
	ds_read_b128 v[224:227], v157 offset:38912
	ds_read_b128 v[228:231], v157 offset:39936
	global_load_lds_dwordx4 v[240:241], off
	v_lshl_add_u64 v[240:241], s[70:71], 0, v[132:133]
	s_mov_b32 m0, s28
	s_nop 0
	global_load_lds_dwordx4 v[240:241], off
	s_waitcnt vmcnt(8)
	s_waitcnt lgkmcnt(0)
	s_setprio 1
	s_barrier
	v_mfma_f32_16x16x32_bf16 v[126:129], v[146:149], v[200:203], v[126:129]
	v_mfma_f32_16x16x32_bf16 v[126:129], v[158:161], v[204:207], v[126:129]
	v_mfma_f32_16x16x32_bf16 v[110:113], v[158:161], v[212:215], v[110:113]
	v_mfma_f32_16x16x32_bf16 v[110:113], v[146:149], v[208:211], v[110:113]
	v_mfma_f32_16x16x32_bf16 v[94:97], v[146:149], v[216:219], v[94:97]
	v_mfma_f32_16x16x32_bf16 v[94:97], v[158:161], v[220:223], v[94:97]
	v_mfma_f32_16x16x32_bf16 v[78:81], v[158:161], v[228:231], v[78:81]
	v_mfma_f32_16x16x32_bf16 v[78:81], v[146:149], v[224:227], v[78:81]
	v_mfma_f32_16x16x32_bf16 v[74:77], v[168:171], v[224:227], v[74:77]
	v_mfma_f32_16x16x32_bf16 v[74:77], v[172:175], v[228:231], v[74:77]
	v_mfma_f32_16x16x32_bf16 v[122:125], v[172:175], v[204:207], v[122:125]
	v_mfma_f32_16x16x32_bf16 v[122:125], v[168:171], v[200:203], v[122:125]
	v_mfma_f32_16x16x32_bf16 v[106:109], v[168:171], v[208:211], v[106:109]
	v_mfma_f32_16x16x32_bf16 v[106:109], v[172:175], v[212:215], v[106:109]
	v_mfma_f32_16x16x32_bf16 v[90:93], v[172:175], v[220:223], v[90:93]
	v_mfma_f32_16x16x32_bf16 v[90:93], v[168:171], v[216:219], v[90:93]
	s_setprio 0
	s_setprio 1
	v_mfma_f32_16x16x32_bf16 v[118:121], v[176:179], v[200:203], v[118:121]
	v_mfma_f32_16x16x32_bf16 v[118:121], v[180:183], v[204:207], v[118:121]
	v_mfma_f32_16x16x32_bf16 v[102:105], v[180:183], v[212:215], v[102:105]
	v_mfma_f32_16x16x32_bf16 v[102:105], v[176:179], v[208:211], v[102:105]
	v_mfma_f32_16x16x32_bf16 v[86:89], v[176:179], v[216:219], v[86:89]
	v_mfma_f32_16x16x32_bf16 v[86:89], v[180:183], v[220:223], v[86:89]
	v_mfma_f32_16x16x32_bf16 v[70:73], v[180:183], v[228:231], v[70:73]
	v_mfma_f32_16x16x32_bf16 v[70:73], v[176:179], v[224:227], v[70:73]
	v_mfma_f32_16x16x32_bf16 v[66:69], v[184:187], v[224:227], v[66:69]
	v_mfma_f32_16x16x32_bf16 v[66:69], v[188:191], v[228:231], v[66:69]
	v_mfma_f32_16x16x32_bf16 v[114:117], v[188:191], v[204:207], v[114:117]
	v_mfma_f32_16x16x32_bf16 v[114:117], v[184:187], v[200:203], v[114:117]
	v_mfma_f32_16x16x32_bf16 v[98:101], v[184:187], v[208:211], v[98:101]
	v_mfma_f32_16x16x32_bf16 v[98:101], v[188:191], v[212:215], v[98:101]
	v_mfma_f32_16x16x32_bf16 v[82:85], v[188:191], v[220:223], v[82:85]
	v_mfma_f32_16x16x32_bf16 v[82:85], v[184:187], v[216:219], v[82:85]
	s_barrier
; #define PG8_STAGE(bufoff, gbase, voff) do { _Pragma("unroll") for (int _i = 0; _i < 2; ++_i) \
;         __builtin_amdgcn_global_load_lds((const unsigned*)((const char*)(gbase) + (voff)[_i]), (PG8_LAS unsigned*)(lds + (bufoff) + ldsw + _i * 8192), 16, 0, 0); } while (0)
; #define PG8_LDA(dst, b, h) do { _Pragma("unroll") for (int m = 0; m < 4; ++m) _Pragma("unroll") for (int k = 0; k < 2; ++k) dst[m][k] = *(const PG8_LAS bf16x8*)(lds + PG8_SA(b, h) + aoff + m * 2048 + k * 1024); } while (0)
; #define PG8_MMA(ai, bj, At, Bt) do { __builtin_amdgcn_s_setprio(1); _Pragma("unroll") for (int m = 0; m < 4; ++m) _Pragma("unroll") for (int n = 0; n < 2; ++n) _Pragma("unroll") for (int k = 0; k < 2; ++k) \
;         acc[ai][bj][m][n] = __builtin_amdgcn_mfma_f32_16x16x32_bf16(Bt[n][k], At[m][k], acc[ai][bj][m][n], 0, 0, 0); __builtin_amdgcn_s_setprio(0); } while (0)
; #define PG8_WAIT_V(n) asm volatile("s_waitcnt vmcnt(" #n ")" ::: "memory")
; #define PG8_WAIT_L(n) asm volatile("s_waitcnt lgkmcnt(" #n ")" ::: "memory")
; #define PG8_BAR __builtin_amdgcn_s_barrier()
; #define PG8_SCHED __builtin_amdgcn_sched_barrier(0)
; template <class Epi, class Sched, bool ALIGN_EPI = false, bool SP2 = false>
; __device__ __forceinline__ void gemm_phase(PG8_LAS unsigned char* lds, const Gemm g, const Sched& S, const Epi& E) {
;     ...
;             PG8_LDA(At, 1, 1); PG8_STAGE(PG8_SB(1, 0), b3, voffB); PG8_STAGE(PG8_SB(1, 1), b3 + hstep, voffB); PG8_STAGE(PG8_SA(1, 0), a3, voffA);
;             PG8_WAIT_V(8); PG8_WAIT_L(0); PG8_BAR; PG8_MMA(1, 0, At, B0); PG8_MMA(1, 1, At, B1); PG8_BAR; PG8_SCHED;
;     ...
;         if constexpr (ALIGN_EPI) { if (wr == 0) PG8_BAR; }
	s_setprio 0
	s_add_i32 s70, s74, s2
	v_lshl_add_u64 v[150:151], v[150:151], 0, s[8:9]
	s_mov_b32 m0, s70
	ds_read_b128 v[200:203], v157 offset:49152
	ds_read_b128 v[204:207], v157 offset:50176
	ds_read_b128 v[208:211], v157 offset:51200
	ds_read_b128 v[212:215], v157 offset:52224
	ds_read_b128 v[216:219], v157 offset:53248
	ds_read_b128 v[220:223], v157 offset:54272
	ds_read_b128 v[224:227], v157 offset:55296
	ds_read_b128 v[228:231], v157 offset:56320
	global_load_lds_dwordx4 v[150:151], off
	s_add_i32 m0, s70, 0x2000
	s_add_u32 s68, s68, 0x80080
	v_lshl_add_u64 v[150:151], v[162:163], 0, s[8:9]
	s_addc_u32 s69, s69, 0
	s_add_i32 s70, s75, s2
	global_load_lds_dwordx4 v[150:151], off
	v_lshl_add_u64 v[150:151], s[68:69], 0, v[134:135]
	s_mov_b32 m0, s70
	s_nop 0
	global_load_lds_dwordx4 v[150:151], off
	v_lshl_add_u64 v[150:151], s[68:69], 0, v[130:131]
	s_add_i32 m0, s70, 0x2000
	s_nop 0
	global_load_lds_dwordx4 v[150:151], off
	v_lshl_add_u64 v[150:151], v[192:193], 0, s[8:9]
	s_mov_b32 m0, s30
	s_nop 0
	global_load_lds_dwordx4 v[150:151], off
	v_lshl_add_u64 v[150:151], v[232:233], 0, s[8:9]
	s_mov_b32 m0, s33
	s_nop 0
	global_load_lds_dwordx4 v[150:151], off
	s_waitcnt vmcnt(8)
	s_waitcnt lgkmcnt(0)
	s_setprio 1
	s_barrier
	v_mfma_f32_16x16x32_bf16 v[62:65], v[146:149], v[200:203], v[62:65]
	v_mfma_f32_16x16x32_bf16 v[62:65], v[158:161], v[204:207], v[62:65]
	v_mfma_f32_16x16x32_bf16 v[46:49], v[158:161], v[212:215], v[46:49]
	v_mfma_f32_16x16x32_bf16 v[46:49], v[146:149], v[208:211], v[46:49]
	v_mfma_f32_16x16x32_bf16 v[30:33], v[146:149], v[216:219], v[30:33]
	v_mfma_f32_16x16x32_bf16 v[30:33], v[158:161], v[220:223], v[30:33]
	v_mfma_f32_16x16x32_bf16 v[14:17], v[158:161], v[228:231], v[14:17]
	v_mfma_f32_16x16x32_bf16 v[14:17], v[146:149], v[224:227], v[14:17]
	v_mfma_f32_16x16x32_bf16 v[10:13], v[168:171], v[224:227], v[10:13]
	v_mfma_f32_16x16x32_bf16 v[10:13], v[172:175], v[228:231], v[10:13]
	v_mfma_f32_16x16x32_bf16 v[58:61], v[172:175], v[204:207], v[58:61]
	v_mfma_f32_16x16x32_bf16 v[58:61], v[168:171], v[200:203], v[58:61]
	v_mfma_f32_16x16x32_bf16 v[42:45], v[168:171], v[208:211], v[42:45]
	v_mfma_f32_16x16x32_bf16 v[42:45], v[172:175], v[212:215], v[42:45]
	v_mfma_f32_16x16x32_bf16 v[26:29], v[172:175], v[220:223], v[26:29]
	v_mfma_f32_16x16x32_bf16 v[26:29], v[168:171], v[216:219], v[26:29]
	s_setprio 0
	s_setprio 1
	v_mfma_f32_16x16x32_bf16 v[54:57], v[176:179], v[200:203], v[54:57]
	v_mfma_f32_16x16x32_bf16 v[54:57], v[180:183], v[204:207], v[54:57]
	v_mfma_f32_16x16x32_bf16 v[38:41], v[180:183], v[212:215], v[38:41]
	v_mfma_f32_16x16x32_bf16 v[38:41], v[176:179], v[208:211], v[38:41]
	v_mfma_f32_16x16x32_bf16 v[22:25], v[176:179], v[216:219], v[22:25]
	v_mfma_f32_16x16x32_bf16 v[22:25], v[180:183], v[220:223], v[22:25]
	v_mfma_f32_16x16x32_bf16 v[6:9], v[180:183], v[228:231], v[6:9]
	v_mfma_f32_16x16x32_bf16 v[6:9], v[176:179], v[224:227], v[6:9]
	v_mfma_f32_16x16x32_bf16 v[2:5], v[184:187], v[224:227], v[2:5]
	v_mfma_f32_16x16x32_bf16 v[2:5], v[188:191], v[228:231], v[2:5]
	v_mfma_f32_16x16x32_bf16 v[50:53], v[188:191], v[204:207], v[50:53]
	v_mfma_f32_16x16x32_bf16 v[50:53], v[184:187], v[200:203], v[50:53]
	v_mfma_f32_16x16x32_bf16 v[34:37], v[184:187], v[208:211], v[34:37]
	v_mfma_f32_16x16x32_bf16 v[34:37], v[188:191], v[212:215], v[34:37]
	v_mfma_f32_16x16x32_bf16 v[18:21], v[188:191], v[220:223], v[18:21]
	v_mfma_f32_16x16x32_bf16 v[18:21], v[184:187], v[216:219], v[18:21]
	s_barrier
	s_setprio 0
	s_add_i32 s73, s73, 2
	s_add_u32 s66, s66, 0x100
	s_addc_u32 s67, s67, 0
	s_add_u32 s65, s65, 0x100
	s_addc_u32 s72, s72, 0
	s_cmp_gt_u32 s73, 29
	s_cbranch_scc0 .LBB0_1078
	s_and_b64 vcc, exec, s[10:11]
	s_cbranch_vccz .LBB0_1081
	s_barrier

; #define PG8_STAGE(bufoff, gbase, voff) do { _Pragma("unroll") for (int _i = 0; _i < 2; ++_i) \
;         __builtin_amdgcn_global_load_lds((const unsigned*)((const char*)(gbase) + (voff)[_i]), (PG8_LAS unsigned*)(lds + (bufoff) + ldsw + _i * 8192), 16, 0, 0); } while (0)
; #define PG8_LDA(dst, b, h) do { _Pragma("unroll") for (int m = 0; m < 4; ++m) _Pragma("unroll") for (int k = 0; k < 2; ++k) dst[m][k] = *(const PG8_LAS bf16x8*)(lds + PG8_SA(b, h) + aoff + m * 2048 + k * 1024); } while (0)
; #define PG8_LDB(dst, b, h) do { _Pragma("unroll") for (int n = 0; n < 2; ++n) _Pragma("unroll") for (int k = 0; k < 2; ++k) dst[n][k] = *(const PG8_LAS bf16x8*)(lds + PG8_SB(b, h) + boff + n * 2048 + k * 1024); } while (0)
; #define PG8_MMA(ai, bj, At, Bt) do { __builtin_amdgcn_s_setprio(1); _Pragma("unroll") for (int m = 0; m < 4; ++m) _Pragma("unroll") for (int n = 0; n < 2; ++n) _Pragma("unroll") for (int k = 0; k < 2; ++k) \
;         acc[ai][bj][m][n] = __builtin_amdgcn_mfma_f32_16x16x32_bf16(Bt[n][k], At[m][k], acc[ai][bj][m][n], 0, 0, 0); __builtin_amdgcn_s_setprio(0); } while (0)
; #define PG8_WAIT_V(n) asm volatile("s_waitcnt vmcnt(" #n ")" ::: "memory")
; #define PG8_WAIT_L(n) asm volatile("s_waitcnt lgkmcnt(" #n ")" ::: "memory")
; #define PG8_BAR __builtin_amdgcn_s_barrier()
; #define PG8_SCHED __builtin_amdgcn_sched_barrier(0)
; template <class Epi, class Sched, bool ALIGN_EPI = false, bool SP2 = false>
; __device__ __forceinline__ void gemm_phase(PG8_LAS unsigned char* lds, const Gemm g, const Sched& S, const Epi& E) {
;     ...
;             const bool last = (t == nt - 2);
;             const char* a1 = cA + (size_t)(t + 1) * kstep;
;             const char* a2 = last ? nA : cA + (size_t)(t + 2) * kstep; const char* b2 = last ? nB : cB + (size_t)(t + 2) * kstep;
;             const char* a3 = a2 + kstep; const char* b3 = b2 + kstep;
;             if (last && has_next) S.a_ready(nxt);
;             if constexpr (SP2) {
;             PG8_LDB(B0, 0, 0); PG8_LDB(B1, 0, 1); PG8_SCHED; PG8_LDA(At, 0, 0); PG8_STAGE(PG8_SA(1, 1), a1 + hstep, voffA);
;             PG8_WAIT_V(8); PG8_WAIT_L(0); PG8_BAR; PG8_MMA(0, 0, At, B0); PG8_MMA(0, 1, At, B1); PG8_BAR; PG8_SCHED;
;             PG8_LDA(At, 0, 1); PG8_STAGE(PG8_SB(0, 0), b2, voffB); PG8_STAGE(PG8_SB(0, 1), b2 + hstep, voffB); PG8_STAGE(PG8_SA(0, 0), a2, voffA);
.LBB0_1203:
	ds_read_b128 v[146:149], v171
	ds_read_b128 v[176:179], v171 offset:1024
	ds_read_b128 v[180:183], v171 offset:2048
	ds_read_b128 v[184:187], v171 offset:3072
	ds_read_b128 v[188:191], v172
	ds_read_b128 v[200:203], v172 offset:1024
	ds_read_b128 v[204:207], v172 offset:2048
	ds_read_b128 v[208:211], v172 offset:3072
	s_add_u32 s63, s64, 0xfff00080
	s_addc_u32 s66, s65, -1
	s_cmp_eq_u32 s61, 60
	s_cselect_b32 s69, s34, s66
	s_cselect_b32 s68, s35, s63
	s_cselect_b32 s67, s40, s55
	s_cselect_b32 s66, s41, s53
	v_lshl_add_u64 v[150:151], s[64:65], 0, v[138:139]
	s_add_i32 m0, s4, 0xc000
	ds_read_b128 v[212:215], v173
	ds_read_b128 v[216:219], v173 offset:1024
	ds_read_b128 v[220:223], v173 offset:2048
	ds_read_b128 v[224:227], v173 offset:3072
	ds_read_b128 v[228:231], v173 offset:4096
	ds_read_b128 v[240:243], v173 offset:5120
	ds_read_b128 v[244:247], v173 offset:6144
	ds_read_b128 v[248:251], v173 offset:7168
	global_load_lds_dwordx4 v[150:151], off
	v_lshl_add_u64 v[150:151], s[64:65], 0, v[140:141]
	s_add_i32 m0, s4, 0xe000
	s_nop 0
	global_load_lds_dwordx4 v[150:151], off
	s_waitcnt vmcnt(8)
	s_waitcnt lgkmcnt(0)
	s_setprio 1
	s_barrier
	v_mfma_f32_16x16x32_bf16 v[126:129], v[146:149], v[212:215], v[126:129]
	v_mfma_f32_16x16x32_bf16 v[126:129], v[176:179], v[216:219], v[126:129]
	v_mfma_f32_16x16x32_bf16 v[110:113], v[176:179], v[224:227], v[110:113]
	v_mfma_f32_16x16x32_bf16 v[110:113], v[146:149], v[220:223], v[110:113]
	v_mfma_f32_16x16x32_bf16 v[94:97], v[146:149], v[228:231], v[94:97]
	v_mfma_f32_16x16x32_bf16 v[94:97], v[176:179], v[240:243], v[94:97]
	v_mfma_f32_16x16x32_bf16 v[78:81], v[176:179], v[248:251], v[78:81]
	v_mfma_f32_16x16x32_bf16 v[78:81], v[146:149], v[244:247], v[78:81]
	v_mfma_f32_16x16x32_bf16 v[74:77], v[180:183], v[244:247], v[74:77]
	v_mfma_f32_16x16x32_bf16 v[74:77], v[184:187], v[248:251], v[74:77]
	v_mfma_f32_16x16x32_bf16 v[122:125], v[184:187], v[216:219], v[122:125]
	v_mfma_f32_16x16x32_bf16 v[122:125], v[180:183], v[212:215], v[122:125]
	v_mfma_f32_16x16x32_bf16 v[106:109], v[180:183], v[220:223], v[106:109]
	v_mfma_f32_16x16x32_bf16 v[106:109], v[184:187], v[224:227], v[106:109]
	v_mfma_f32_16x16x32_bf16 v[90:93], v[184:187], v[240:243], v[90:93]
	v_mfma_f32_16x16x32_bf16 v[90:93], v[180:183], v[228:231], v[90:93]
	s_setprio 0
	s_setprio 1
	v_mfma_f32_16x16x32_bf16 v[118:121], v[188:191], v[212:215], v[118:121]
	v_mfma_f32_16x16x32_bf16 v[118:121], v[200:203], v[216:219], v[118:121]
	v_mfma_f32_16x16x32_bf16 v[102:105], v[200:203], v[224:227], v[102:105]
	v_mfma_f32_16x16x32_bf16 v[102:105], v[188:191], v[220:223], v[102:105]
	v_mfma_f32_16x16x32_bf16 v[86:89], v[188:191], v[228:231], v[86:89]
	v_mfma_f32_16x16x32_bf16 v[86:89], v[200:203], v[240:243], v[86:89]
	v_mfma_f32_16x16x32_bf16 v[70:73], v[200:203], v[248:251], v[70:73]
	v_mfma_f32_16x16x32_bf16 v[70:73], v[188:191], v[244:247], v[70:73]
	v_mfma_f32_16x16x32_bf16 v[66:69], v[204:207], v[244:247], v[66:69]
	v_mfma_f32_16x16x32_bf16 v[66:69], v[208:211], v[248:251], v[66:69]
	v_mfma_f32_16x16x32_bf16 v[114:117], v[208:211], v[216:219], v[114:117]
	v_mfma_f32_16x16x32_bf16 v[114:117], v[204:207], v[212:215], v[114:117]
	v_mfma_f32_16x16x32_bf16 v[98:101], v[204:207], v[220:223], v[98:101]
	v_mfma_f32_16x16x32_bf16 v[98:101], v[208:211], v[224:227], v[98:101]
	v_mfma_f32_16x16x32_bf16 v[82:85], v[208:211], v[240:243], v[82:85]
	v_mfma_f32_16x16x32_bf16 v[82:85], v[204:207], v[228:231], v[82:85]
	s_barrier
	s_setprio 0
	s_add_i32 s63, s31, s2
	v_lshl_add_u64 v[150:151], s[66:67], 0, v[132:133]
	s_mov_b32 m0, s63
	ds_read_b128 v[212:215], v173 offset:16384
	ds_read_b128 v[216:219], v173 offset:17408
	ds_read_b128 v[220:223], v173 offset:18432
	ds_read_b128 v[224:227], v173 offset:19456
	ds_read_b128 v[228:231], v173 offset:20480
	ds_read_b128 v[240:243], v173 offset:21504
	ds_read_b128 v[244:247], v173 offset:22528
	ds_read_b128 v[248:251], v173 offset:23552
	global_load_lds_dwordx4 v[150:151], off
	s_add_i32 m0, s63, 0x2000
	s_add_u32 s70, s66, 0x100000
	v_lshl_add_u64 v[192:193], s[66:67], 0, v[136:137]
	s_addc_u32 s71, s67, 0
	s_add_i32 s63, s39, s2
	global_load_lds_dwordx4 v[192:193], off
	v_lshl_add_u64 v[232:233], s[70:71], 0, v[132:133]
	s_mov_b32 m0, s63
	v_lshl_add_u64 v[252:253], s[68:69], 0, v[134:135]
	global_load_lds_dwordx4 v[232:233], off
	v_lshl_add_u64 v[232:233], s[70:71], 0, v[136:137]
	s_add_i32 m0, s63, 0x2000
	s_nop 0
	global_load_lds_dwordx4 v[232:233], off
	v_lshl_add_u64 v[232:233], s[68:69], 0, v[130:131]
	s_mov_b32 m0, s4
	s_nop 0
	global_load_lds_dwordx4 v[232:233], off
	s_mov_b32 m0, s5
	s_nop 0
	global_load_lds_dwordx4 v[252:253], off
	s_waitcnt vmcnt(8)
	s_waitcnt lgkmcnt(0)
	s_setprio 1
	s_barrier
; #define PG8_STAGE(bufoff, gbase, voff) do { _Pragma("unroll") for (int _i = 0; _i < 2; ++_i) \
;         __builtin_amdgcn_global_load_lds((const unsigned*)((const char*)(gbase) + (voff)[_i]), (PG8_LAS unsigned*)(lds + (bufoff) + ldsw + _i * 8192), 16, 0, 0); } while (0)
; #define PG8_LDA(dst, b, h) do { _Pragma("unroll") for (int m = 0; m < 4; ++m) _Pragma("unroll") for (int k = 0; k < 2; ++k) dst[m][k] = *(const PG8_LAS bf16x8*)(lds + PG8_SA(b, h) + aoff + m * 2048 + k * 1024); } while (0)
; #define PG8_LDB(dst, b, h) do { _Pragma("unroll") for (int n = 0; n < 2; ++n) _Pragma("unroll") for (int k = 0; k < 2; ++k) dst[n][k] = *(const PG8_LAS bf16x8*)(lds + PG8_SB(b, h) + boff + n * 2048 + k * 1024); } while (0)
; #define PG8_MMA(ai, bj, At, Bt) do { __builtin_amdgcn_s_setprio(1); _Pragma("unroll") for (int m = 0; m < 4; ++m) _Pragma("unroll") for (int n = 0; n < 2; ++n) _Pragma("unroll") for (int k = 0; k < 2; ++k) \
;         acc[ai][bj][m][n] = __builtin_amdgcn_mfma_f32_16x16x32_bf16(Bt[n][k], At[m][k], acc[ai][bj][m][n], 0, 0, 0); __builtin_amdgcn_s_setprio(0); } while (0)
; #define PG8_WAIT_V(n) asm volatile("s_waitcnt vmcnt(" #n ")" ::: "memory")
; #define PG8_WAIT_L(n) asm volatile("s_waitcnt lgkmcnt(" #n ")" ::: "memory")
; #define PG8_BAR __builtin_amdgcn_s_barrier()
; #define PG8_SCHED __builtin_amdgcn_sched_barrier(0)
; template <class Epi, class Sched, bool ALIGN_EPI = false, bool SP2 = false>
; __device__ __forceinline__ void gemm_phase(PG8_LAS unsigned char* lds, const Gemm g, const Sched& S, const Epi& E) {
;     ...
;             PG8_WAIT_V(8); PG8_WAIT_L(0); PG8_BAR; PG8_MMA(1, 0, At, B0); PG8_MMA(1, 1, At, B1); PG8_BAR; PG8_SCHED;
;             PG8_LDB(B0, 1, 0); PG8_LDB(B1, 1, 1); PG8_SCHED; PG8_LDA(At, 1, 0); PG8_STAGE(PG8_SA(0, 1), a2 + hstep, voffA);
;             PG8_WAIT_V(8); PG8_WAIT_L(0); PG8_BAR; PG8_MMA(0, 0, At, B0); PG8_MMA(0, 1, At, B1); PG8_BAR; PG8_SCHED;
	v_mfma_f32_16x16x32_bf16 v[62:65], v[146:149], v[212:215], v[62:65]
	v_mfma_f32_16x16x32_bf16 v[62:65], v[176:179], v[216:219], v[62:65]
	v_mfma_f32_16x16x32_bf16 v[46:49], v[176:179], v[224:227], v[46:49]
	v_mfma_f32_16x16x32_bf16 v[46:49], v[146:149], v[220:223], v[46:49]
	v_mfma_f32_16x16x32_bf16 v[30:33], v[146:149], v[228:231], v[30:33]
	v_mfma_f32_16x16x32_bf16 v[30:33], v[176:179], v[240:243], v[30:33]
	v_mfma_f32_16x16x32_bf16 v[14:17], v[176:179], v[248:251], v[14:17]
	v_mfma_f32_16x16x32_bf16 v[14:17], v[146:149], v[244:247], v[14:17]
	v_mfma_f32_16x16x32_bf16 v[10:13], v[180:183], v[244:247], v[10:13]
	v_mfma_f32_16x16x32_bf16 v[10:13], v[184:187], v[248:251], v[10:13]
	v_mfma_f32_16x16x32_bf16 v[58:61], v[184:187], v[216:219], v[58:61]
	v_mfma_f32_16x16x32_bf16 v[58:61], v[180:183], v[212:215], v[58:61]
	v_mfma_f32_16x16x32_bf16 v[42:45], v[180:183], v[220:223], v[42:45]
	v_mfma_f32_16x16x32_bf16 v[42:45], v[184:187], v[224:227], v[42:45]
	v_mfma_f32_16x16x32_bf16 v[26:29], v[184:187], v[240:243], v[26:29]
	v_mfma_f32_16x16x32_bf16 v[26:29], v[180:183], v[228:231], v[26:29]
	s_setprio 0
	s_setprio 1
	v_mfma_f32_16x16x32_bf16 v[54:57], v[188:191], v[212:215], v[54:57]
	v_mfma_f32_16x16x32_bf16 v[54:57], v[200:203], v[216:219], v[54:57]
	v_mfma_f32_16x16x32_bf16 v[38:41], v[200:203], v[224:227], v[38:41]
	v_mfma_f32_16x16x32_bf16 v[38:41], v[188:191], v[220:223], v[38:41]
	v_mfma_f32_16x16x32_bf16 v[22:25], v[188:191], v[228:231], v[22:25]
	v_mfma_f32_16x16x32_bf16 v[22:25], v[200:203], v[240:243], v[22:25]
	v_mfma_f32_16x16x32_bf16 v[6:9], v[200:203], v[248:251], v[6:9]
	v_mfma_f32_16x16x32_bf16 v[6:9], v[188:191], v[244:247], v[6:9]
	v_mfma_f32_16x16x32_bf16 v[2:5], v[204:207], v[244:247], v[2:5]
	v_mfma_f32_16x16x32_bf16 v[2:5], v[208:211], v[248:251], v[2:5]
	v_mfma_f32_16x16x32_bf16 v[50:53], v[208:211], v[216:219], v[50:53]
	v_mfma_f32_16x16x32_bf16 v[50:53], v[204:207], v[212:215], v[50:53]
	v_mfma_f32_16x16x32_bf16 v[34:37], v[204:207], v[220:223], v[34:37]
	v_mfma_f32_16x16x32_bf16 v[34:37], v[208:211], v[224:227], v[34:37]
	v_mfma_f32_16x16x32_bf16 v[18:21], v[208:211], v[240:243], v[18:21]
	v_mfma_f32_16x16x32_bf16 v[18:21], v[204:207], v[228:231], v[18:21]
	s_barrier
	s_setprio 0
	s_add_i32 s63, 0, 0x18000
	v_add_u32_e32 v175, s63, v153
	s_add_i32 s70, 0, 0x1c000
	ds_read_b128 v[146:149], v175
	ds_read_b128 v[176:179], v175 offset:1024
	ds_read_b128 v[180:183], v175 offset:2048
	ds_read_b128 v[184:187], v175 offset:3072
	v_add_u32_e32 v175, s70, v153
	ds_read_b128 v[188:191], v175
	ds_read_b128 v[200:203], v175 offset:1024
	ds_read_b128 v[204:207], v175 offset:2048
	ds_read_b128 v[208:211], v175 offset:3072
	s_add_u32 s68, s68, 0x100000
	s_addc_u32 s69, s69, 0
	s_mov_b32 m0, s16
	v_lshl_add_u64 v[194:195], s[68:69], 0, v[130:131]
	ds_read_b128 v[212:215], v173 offset:32768
	ds_read_b128 v[216:219], v173 offset:33792
	ds_read_b128 v[220:223], v173 offset:34816
	ds_read_b128 v[224:227], v173 offset:35840
	ds_read_b128 v[228:231], v173 offset:36864
	ds_read_b128 v[240:243], v173 offset:37888
	ds_read_b128 v[244:247], v173 offset:38912
	ds_read_b128 v[248:251], v173 offset:39936
	global_load_lds_dwordx4 v[194:195], off
	v_lshl_add_u64 v[194:195], s[68:69], 0, v[134:135]
	s_mov_b32 m0, s17
	s_nop 0
	global_load_lds_dwordx4 v[194:195], off
	s_waitcnt vmcnt(8)
	s_waitcnt lgkmcnt(0)
	s_setprio 1
	s_barrier
	v_mfma_f32_16x16x32_bf16 v[126:129], v[146:149], v[212:215], v[126:129]
	v_mfma_f32_16x16x32_bf16 v[126:129], v[176:179], v[216:219], v[126:129]
	v_mfma_f32_16x16x32_bf16 v[110:113], v[176:179], v[224:227], v[110:113]
	v_mfma_f32_16x16x32_bf16 v[110:113], v[146:149], v[220:223], v[110:113]
	v_mfma_f32_16x16x32_bf16 v[94:97], v[146:149], v[228:231], v[94:97]
	v_mfma_f32_16x16x32_bf16 v[94:97], v[176:179], v[240:243], v[94:97]
	v_mfma_f32_16x16x32_bf16 v[78:81], v[176:179], v[248:251], v[78:81]
	v_mfma_f32_16x16x32_bf16 v[78:81], v[146:149], v[244:247], v[78:81]
	v_mfma_f32_16x16x32_bf16 v[74:77], v[180:183], v[244:247], v[74:77]
	v_mfma_f32_16x16x32_bf16 v[74:77], v[184:187], v[248:251], v[74:77]
	v_mfma_f32_16x16x32_bf16 v[122:125], v[184:187], v[216:219], v[122:125]
	v_mfma_f32_16x16x32_bf16 v[122:125], v[180:183], v[212:215], v[122:125]
	v_mfma_f32_16x16x32_bf16 v[106:109], v[180:183], v[220:223], v[106:109]
	v_mfma_f32_16x16x32_bf16 v[106:109], v[184:187], v[224:227], v[106:109]
	v_mfma_f32_16x16x32_bf16 v[90:93], v[184:187], v[240:243], v[90:93]
	v_mfma_f32_16x16x32_bf16 v[90:93], v[180:183], v[228:231], v[90:93]
	s_setprio 0
	s_setprio 1
	v_mfma_f32_16x16x32_bf16 v[118:121], v[188:191], v[212:215], v[118:121]
	v_mfma_f32_16x16x32_bf16 v[118:121], v[200:203], v[216:219], v[118:121]
	v_mfma_f32_16x16x32_bf16 v[102:105], v[200:203], v[224:227], v[102:105]
	v_mfma_f32_16x16x32_bf16 v[102:105], v[188:191], v[220:223], v[102:105]
	v_mfma_f32_16x16x32_bf16 v[86:89], v[188:191], v[228:231], v[86:89]
	v_mfma_f32_16x16x32_bf16 v[86:89], v[200:203], v[240:243], v[86:89]
	v_mfma_f32_16x16x32_bf16 v[70:73], v[200:203], v[248:251], v[70:73]
	v_mfma_f32_16x16x32_bf16 v[70:73], v[188:191], v[244:247], v[70:73]
	v_mfma_f32_16x16x32_bf16 v[66:69], v[204:207], v[244:247], v[66:69]
	v_mfma_f32_16x16x32_bf16 v[66:69], v[208:211], v[248:251], v[66:69]
	v_mfma_f32_16x16x32_bf16 v[114:117], v[208:211], v[216:219], v[114:117]
	v_mfma_f32_16x16x32_bf16 v[114:117], v[204:207], v[212:215], v[114:117]
	v_mfma_f32_16x16x32_bf16 v[98:101], v[204:207], v[220:223], v[98:101]
	v_mfma_f32_16x16x32_bf16 v[98:101], v[208:211], v[224:227], v[98:101]
	v_mfma_f32_16x16x32_bf16 v[82:85], v[208:211], v[240:243], v[82:85]
	v_mfma_f32_16x16x32_bf16 v[82:85], v[204:207], v[228:231], v[82:85]
	s_barrier
; #define PG8_STAGE(bufoff, gbase, voff) do { _Pragma("unroll") for (int _i = 0; _i < 2; ++_i) \
;         __builtin_amdgcn_global_load_lds((const unsigned*)((const char*)(gbase) + (voff)[_i]), (PG8_LAS unsigned*)(lds + (bufoff) + ldsw + _i * 8192), 16, 0, 0); } while (0)
; #define PG8_LDA(dst, b, h) do { _Pragma("unroll") for (int m = 0; m < 4; ++m) _Pragma("unroll") for (int k = 0; k < 2; ++k) dst[m][k] = *(const PG8_LAS bf16x8*)(lds + PG8_SA(b, h) + aoff + m * 2048 + k * 1024); } while (0)
; #define PG8_MMA(ai, bj, At, Bt) do { __builtin_amdgcn_s_setprio(1); _Pragma("unroll") for (int m = 0; m < 4; ++m) _Pragma("unroll") for (int n = 0; n < 2; ++n) _Pragma("unroll") for (int k = 0; k < 2; ++k) \
;         acc[ai][bj][m][n] = __builtin_amdgcn_mfma_f32_16x16x32_bf16(Bt[n][k], At[m][k], acc[ai][bj][m][n], 0, 0, 0); __builtin_amdgcn_s_setprio(0); } while (0)
; #define PG8_WAIT_V(n) asm volatile("s_waitcnt vmcnt(" #n ")" ::: "memory")
; #define PG8_WAIT_L(n) asm volatile("s_waitcnt lgkmcnt(" #n ")" ::: "memory")
; #define PG8_BAR __builtin_amdgcn_s_barrier()
; #define PG8_SCHED __builtin_amdgcn_sched_barrier(0)
; template <class Epi, class Sched, bool ALIGN_EPI = false, bool SP2 = false>
; __device__ __forceinline__ void gemm_phase(PG8_LAS unsigned char* lds, const Gemm g, const Sched& S, const Epi& E) {
;     ...
;             PG8_LDA(At, 1, 1); PG8_STAGE(PG8_SB(1, 0), b3, voffB); PG8_STAGE(PG8_SB(1, 1), b3 + hstep, voffB); PG8_STAGE(PG8_SA(1, 0), a3, voffA);
;             PG8_WAIT_V(8); PG8_WAIT_L(0); PG8_BAR; PG8_MMA(1, 0, At, B0); PG8_MMA(1, 1, At, B1); PG8_BAR; PG8_SCHED;
;     ...
;         if constexpr (ALIGN_EPI) { if (wr == 0) PG8_BAR; }
	s_setprio 0
	s_add_i32 s63, s63, s2
	v_lshl_add_u64 v[150:151], v[150:151], 0, s[44:45]
	s_mov_b32 m0, s63
	ds_read_b128 v[212:215], v173 offset:49152
	ds_read_b128 v[216:219], v173 offset:50176
	ds_read_b128 v[220:223], v173 offset:51200
	ds_read_b128 v[224:227], v173 offset:52224
	ds_read_b128 v[228:231], v173 offset:53248
	ds_read_b128 v[240:243], v173 offset:54272
	ds_read_b128 v[244:247], v173 offset:55296
	ds_read_b128 v[248:251], v173 offset:56320
	global_load_lds_dwordx4 v[150:151], off
	s_add_i32 m0, s63, 0x2000
	s_add_u32 s66, s66, 0x100080
	v_lshl_add_u64 v[150:151], v[192:193], 0, s[44:45]
	s_addc_u32 s67, s67, 0
	s_add_i32 s63, s70, s2
	global_load_lds_dwordx4 v[150:151], off
	v_lshl_add_u64 v[150:151], s[66:67], 0, v[132:133]
	s_mov_b32 m0, s63
	s_nop 0
	global_load_lds_dwordx4 v[150:151], off
	v_lshl_add_u64 v[150:151], s[66:67], 0, v[136:137]
	s_add_i32 m0, s63, 0x2000
	s_nop 0
	global_load_lds_dwordx4 v[150:151], off
	v_lshl_add_u64 v[150:151], v[232:233], 0, s[44:45]
	s_mov_b32 m0, s26
	s_nop 0
	global_load_lds_dwordx4 v[150:151], off
	v_lshl_add_u64 v[150:151], v[252:253], 0, s[44:45]
	s_mov_b32 m0, s27
	s_nop 0
	global_load_lds_dwordx4 v[150:151], off
	s_waitcnt vmcnt(8)
	s_waitcnt lgkmcnt(0)
	s_setprio 1
	s_barrier
	v_mfma_f32_16x16x32_bf16 v[62:65], v[146:149], v[212:215], v[62:65]
	v_mfma_f32_16x16x32_bf16 v[62:65], v[176:179], v[216:219], v[62:65]
	v_mfma_f32_16x16x32_bf16 v[46:49], v[176:179], v[224:227], v[46:49]
	v_mfma_f32_16x16x32_bf16 v[46:49], v[146:149], v[220:223], v[46:49]
	v_mfma_f32_16x16x32_bf16 v[30:33], v[146:149], v[228:231], v[30:33]
	v_mfma_f32_16x16x32_bf16 v[30:33], v[176:179], v[240:243], v[30:33]
	v_mfma_f32_16x16x32_bf16 v[14:17], v[176:179], v[248:251], v[14:17]
	v_mfma_f32_16x16x32_bf16 v[14:17], v[146:149], v[244:247], v[14:17]
	v_mfma_f32_16x16x32_bf16 v[10:13], v[180:183], v[244:247], v[10:13]
	v_mfma_f32_16x16x32_bf16 v[10:13], v[184:187], v[248:251], v[10:13]
	v_mfma_f32_16x16x32_bf16 v[58:61], v[184:187], v[216:219], v[58:61]
	v_mfma_f32_16x16x32_bf16 v[58:61], v[180:183], v[212:215], v[58:61]
	v_mfma_f32_16x16x32_bf16 v[42:45], v[180:183], v[220:223], v[42:45]
	v_mfma_f32_16x16x32_bf16 v[42:45], v[184:187], v[224:227], v[42:45]
	v_mfma_f32_16x16x32_bf16 v[26:29], v[184:187], v[240:243], v[26:29]
	v_mfma_f32_16x16x32_bf16 v[26:29], v[180:183], v[228:231], v[26:29]
	s_setprio 0
	s_setprio 1
	v_mfma_f32_16x16x32_bf16 v[54:57], v[188:191], v[212:215], v[54:57]
	v_mfma_f32_16x16x32_bf16 v[54:57], v[200:203], v[216:219], v[54:57]
	v_mfma_f32_16x16x32_bf16 v[38:41], v[200:203], v[224:227], v[38:41]
	v_mfma_f32_16x16x32_bf16 v[38:41], v[188:191], v[220:223], v[38:41]
	v_mfma_f32_16x16x32_bf16 v[22:25], v[188:191], v[228:231], v[22:25]
	v_mfma_f32_16x16x32_bf16 v[22:25], v[200:203], v[240:243], v[22:25]
	v_mfma_f32_16x16x32_bf16 v[6:9], v[200:203], v[248:251], v[6:9]
	v_mfma_f32_16x16x32_bf16 v[6:9], v[188:191], v[244:247], v[6:9]
	v_mfma_f32_16x16x32_bf16 v[2:5], v[204:207], v[244:247], v[2:5]
	v_mfma_f32_16x16x32_bf16 v[2:5], v[208:211], v[248:251], v[2:5]
	v_mfma_f32_16x16x32_bf16 v[50:53], v[208:211], v[216:219], v[50:53]
	v_mfma_f32_16x16x32_bf16 v[50:53], v[204:207], v[212:215], v[50:53]
	v_mfma_f32_16x16x32_bf16 v[34:37], v[204:207], v[220:223], v[34:37]
	v_mfma_f32_16x16x32_bf16 v[34:37], v[208:211], v[224:227], v[34:37]
	v_mfma_f32_16x16x32_bf16 v[18:21], v[208:211], v[240:243], v[18:21]
	v_mfma_f32_16x16x32_bf16 v[18:21], v[204:207], v[228:231], v[18:21]
	s_barrier
	s_setprio 0
	s_add_i32 s61, s61, 2
	s_add_u32 s64, s64, 0x100
	s_addc_u32 s65, s65, 0
	s_add_u32 s53, s53, 0x100
	s_addc_u32 s55, s55, 0
	s_cmp_gt_u32 s61, 61
	s_cbranch_scc0 .LBB0_1203
	s_and_b64 vcc, exec, s[46:47]
	s_cbranch_vccz .LBB0_1206
	s_barrier

; #define PG8_STAGE(bufoff, gbase, voff) do { _Pragma("unroll") for (int _i = 0; _i < 2; ++_i) \
;         __builtin_amdgcn_global_load_lds((const unsigned*)((const char*)(gbase) + (voff)[_i]), (PG8_LAS unsigned*)(lds + (bufoff) + ldsw + _i * 8192), 16, 0, 0); } while (0)
; #define PG8_LDA(dst, b, h) do { _Pragma("unroll") for (int m = 0; m < 4; ++m) _Pragma("unroll") for (int k = 0; k < 2; ++k) dst[m][k] = *(const PG8_LAS bf16x8*)(lds + PG8_SA(b, h) + aoff + m * 2048 + k * 1024); } while (0)
; #define PG8_LDB(dst, b, h) do { _Pragma("unroll") for (int n = 0; n < 2; ++n) _Pragma("unroll") for (int k = 0; k < 2; ++k) dst[n][k] = *(const PG8_LAS bf16x8*)(lds + PG8_SB(b, h) + boff + n * 2048 + k * 1024); } while (0)
; #define PG8_MMA(ai, bj, At, Bt) do { __builtin_amdgcn_s_setprio(1); _Pragma("unroll") for (int m = 0; m < 4; ++m) _Pragma("unroll") for (int n = 0; n < 2; ++n) _Pragma("unroll") for (int k = 0; k < 2; ++k) \
;         acc[ai][bj][m][n] = __builtin_amdgcn_mfma_f32_16x16x32_bf16(Bt[n][k], At[m][k], acc[ai][bj][m][n], 0, 0, 0); __builtin_amdgcn_s_setprio(0); } while (0)
; #define PG8_WAIT_V(n) asm volatile("s_waitcnt vmcnt(" #n ")" ::: "memory")
; #define PG8_WAIT_L(n) asm volatile("s_waitcnt lgkmcnt(" #n ")" ::: "memory")
; #define PG8_BAR __builtin_amdgcn_s_barrier()
; #define PG8_SCHED __builtin_amdgcn_sched_barrier(0)
; template <class Epi, class Sched, bool ALIGN_EPI = false, bool SP2 = false>
; __device__ __forceinline__ void gemm_phase(PG8_LAS unsigned char* lds, const Gemm g, const Sched& S, const Epi& E) {
;     ...
;             const bool last = (t == nt - 2);
;             const char* a1 = cA + (size_t)(t + 1) * kstep;
;             const char* a2 = last ? nA : cA + (size_t)(t + 2) * kstep; const char* b2 = last ? nB : cB + (size_t)(t + 2) * kstep;
;             const char* a3 = a2 + kstep; const char* b3 = b2 + kstep;
;             if (last && has_next) S.a_ready(nxt);
;             if constexpr (SP2) {
;             PG8_LDB(B0, 0, 0); PG8_LDB(B1, 0, 1); PG8_SCHED; PG8_LDA(At, 0, 0); PG8_STAGE(PG8_SA(1, 1), a1 + hstep, voffA);
;             PG8_WAIT_V(8); PG8_WAIT_L(0); PG8_BAR; PG8_MMA(0, 0, At, B0); PG8_MMA(0, 1, At, B1); PG8_BAR; PG8_SCHED;
;             PG8_LDA(At, 0, 1); PG8_STAGE(PG8_SB(0, 0), b2, voffB); PG8_STAGE(PG8_SB(0, 1), b2 + hstep, voffB); PG8_STAGE(PG8_SA(0, 0), a2, voffA);
.LBB0_1230:
	ds_read_b128 v[146:149], v140
	ds_read_b128 v[150:153], v140 offset:1024
	ds_read_b128 v[154:157], v140 offset:2048
	ds_read_b128 v[158:161], v140 offset:3072
	ds_read_b128 v[168:171], v141
	ds_read_b128 v[172:175], v141 offset:1024
	ds_read_b128 v[176:179], v141 offset:2048
	ds_read_b128 v[180:183], v141 offset:3072
	s_add_u32 s50, s46, 0x100
	s_addc_u32 s51, s47, 0
	s_cmp_lg_u32 s30, 12
	s_cselect_b32 s52, s50, 0
	s_cselect_b32 s53, s51, 0
	s_add_u32 s54, s10, s52
	s_addc_u32 s55, s11, s53
	s_add_u32 s52, s8, s52
	s_addc_u32 s53, s9, s53
	s_mov_b32 m0, s33
	v_lshl_add_u64 v[162:163], v[134:135], 0, s[46:47]
	ds_read_b128 v[184:187], v142
	ds_read_b128 v[188:191], v142 offset:1024
	ds_read_b128 v[200:203], v142 offset:2048
	ds_read_b128 v[204:207], v142 offset:3072
	ds_read_b128 v[208:211], v142 offset:4096
	ds_read_b128 v[212:215], v142 offset:5120
	ds_read_b128 v[216:219], v142 offset:6144
	ds_read_b128 v[220:223], v142 offset:7168
	global_load_lds_dwordx4 v[162:163], off
	v_lshl_add_u64 v[162:163], v[136:137], 0, s[46:47]
	s_mov_b32 m0, s34
	s_nop 0
	global_load_lds_dwordx4 v[162:163], off
	s_waitcnt vmcnt(8)
	s_waitcnt lgkmcnt(0)
	s_setprio 1
	s_barrier
	v_mfma_f32_16x16x32_bf16 v[126:129], v[146:149], v[184:187], v[126:129]
	v_mfma_f32_16x16x32_bf16 v[126:129], v[150:153], v[188:191], v[126:129]
	v_mfma_f32_16x16x32_bf16 v[118:121], v[150:153], v[204:207], v[118:121]
	v_mfma_f32_16x16x32_bf16 v[118:121], v[146:149], v[200:203], v[118:121]
	v_mfma_f32_16x16x32_bf16 v[106:109], v[146:149], v[208:211], v[106:109]
	v_mfma_f32_16x16x32_bf16 v[106:109], v[150:153], v[212:215], v[106:109]
	v_mfma_f32_16x16x32_bf16 v[90:93], v[150:153], v[220:223], v[90:93]
	v_mfma_f32_16x16x32_bf16 v[90:93], v[146:149], v[216:219], v[90:93]
	v_mfma_f32_16x16x32_bf16 v[82:85], v[154:157], v[216:219], v[82:85]
	v_mfma_f32_16x16x32_bf16 v[82:85], v[158:161], v[220:223], v[82:85]
	v_mfma_f32_16x16x32_bf16 v[122:125], v[158:161], v[188:191], v[122:125]
	v_mfma_f32_16x16x32_bf16 v[122:125], v[154:157], v[184:187], v[122:125]
	v_mfma_f32_16x16x32_bf16 v[114:117], v[154:157], v[200:203], v[114:117]
	v_mfma_f32_16x16x32_bf16 v[114:117], v[158:161], v[204:207], v[114:117]
	v_mfma_f32_16x16x32_bf16 v[98:101], v[158:161], v[212:215], v[98:101]
	v_mfma_f32_16x16x32_bf16 v[98:101], v[154:157], v[208:211], v[98:101]
	s_setprio 0
	s_setprio 1
	v_mfma_f32_16x16x32_bf16 v[110:113], v[168:171], v[184:187], v[110:113]
	v_mfma_f32_16x16x32_bf16 v[110:113], v[172:175], v[188:191], v[110:113]
	v_mfma_f32_16x16x32_bf16 v[94:97], v[172:175], v[204:207], v[94:97]
	v_mfma_f32_16x16x32_bf16 v[94:97], v[168:171], v[200:203], v[94:97]
	v_mfma_f32_16x16x32_bf16 v[78:81], v[168:171], v[208:211], v[78:81]
	v_mfma_f32_16x16x32_bf16 v[78:81], v[172:175], v[212:215], v[78:81]
	v_mfma_f32_16x16x32_bf16 v[70:73], v[172:175], v[220:223], v[70:73]
	v_mfma_f32_16x16x32_bf16 v[70:73], v[168:171], v[216:219], v[70:73]
	v_mfma_f32_16x16x32_bf16 v[66:69], v[176:179], v[216:219], v[66:69]
	v_mfma_f32_16x16x32_bf16 v[66:69], v[180:183], v[220:223], v[66:69]
	v_mfma_f32_16x16x32_bf16 v[102:105], v[180:183], v[188:191], v[102:105]
	v_mfma_f32_16x16x32_bf16 v[102:105], v[176:179], v[184:187], v[102:105]
	v_mfma_f32_16x16x32_bf16 v[86:89], v[176:179], v[200:203], v[86:89]
	v_mfma_f32_16x16x32_bf16 v[86:89], v[180:183], v[204:207], v[86:89]
	v_mfma_f32_16x16x32_bf16 v[74:77], v[180:183], v[212:215], v[74:77]
	v_mfma_f32_16x16x32_bf16 v[74:77], v[176:179], v[208:211], v[74:77]
	s_barrier
	s_setprio 0
	s_mov_b32 m0, s35
	v_lshl_add_u64 v[162:163], s[52:53], 0, v[130:131]
	s_add_u32 s46, s52, 0x100000
	ds_read_b128 v[184:187], v142 offset:16384
	ds_read_b128 v[188:191], v142 offset:17408
	ds_read_b128 v[200:203], v142 offset:18432
	ds_read_b128 v[204:207], v142 offset:19456
	ds_read_b128 v[208:211], v142 offset:20480
	ds_read_b128 v[212:215], v142 offset:21504
	ds_read_b128 v[216:219], v142 offset:22528
	ds_read_b128 v[220:223], v142 offset:23552
	global_load_lds_dwordx4 v[162:163], off
	v_lshl_add_u64 v[192:193], s[52:53], 0, v[132:133]
	s_mov_b32 m0, s39
	s_addc_u32 s47, s53, 0
	global_load_lds_dwordx4 v[192:193], off
	v_lshl_add_u64 v[194:195], s[46:47], 0, v[130:131]
	s_mov_b32 m0, s40
	v_lshl_add_u64 v[224:225], s[54:55], 0, v[132:133]
	global_load_lds_dwordx4 v[194:195], off
	v_lshl_add_u64 v[194:195], s[46:47], 0, v[132:133]
	s_mov_b32 m0, s41
	s_nop 0
	global_load_lds_dwordx4 v[194:195], off
	v_lshl_add_u64 v[194:195], s[54:55], 0, v[130:131]
	s_mov_b32 m0, s7
	s_nop 0
	global_load_lds_dwordx4 v[194:195], off
	s_mov_b32 m0, s16
	s_nop 0
	global_load_lds_dwordx4 v[224:225], off
	s_waitcnt vmcnt(8)
	s_waitcnt lgkmcnt(0)
	s_setprio 1
	s_barrier
; #define PG8_STAGE(bufoff, gbase, voff) do { _Pragma("unroll") for (int _i = 0; _i < 2; ++_i) \
;         __builtin_amdgcn_global_load_lds((const unsigned*)((const char*)(gbase) + (voff)[_i]), (PG8_LAS unsigned*)(lds + (bufoff) + ldsw + _i * 8192), 16, 0, 0); } while (0)
; #define PG8_LDA(dst, b, h) do { _Pragma("unroll") for (int m = 0; m < 4; ++m) _Pragma("unroll") for (int k = 0; k < 2; ++k) dst[m][k] = *(const PG8_LAS bf16x8*)(lds + PG8_SA(b, h) + aoff + m * 2048 + k * 1024); } while (0)
; #define PG8_LDB(dst, b, h) do { _Pragma("unroll") for (int n = 0; n < 2; ++n) _Pragma("unroll") for (int k = 0; k < 2; ++k) dst[n][k] = *(const PG8_LAS bf16x8*)(lds + PG8_SB(b, h) + boff + n * 2048 + k * 1024); } while (0)
; #define PG8_MMA(ai, bj, At, Bt) do { __builtin_amdgcn_s_setprio(1); _Pragma("unroll") for (int m = 0; m < 4; ++m) _Pragma("unroll") for (int n = 0; n < 2; ++n) _Pragma("unroll") for (int k = 0; k < 2; ++k) \
;         acc[ai][bj][m][n] = __builtin_amdgcn_mfma_f32_16x16x32_bf16(Bt[n][k], At[m][k], acc[ai][bj][m][n], 0, 0, 0); __builtin_amdgcn_s_setprio(0); } while (0)
; #define PG8_WAIT_V(n) asm volatile("s_waitcnt vmcnt(" #n ")" ::: "memory")
; #define PG8_WAIT_L(n) asm volatile("s_waitcnt lgkmcnt(" #n ")" ::: "memory")
; #define PG8_BAR __builtin_amdgcn_s_barrier()
; #define PG8_SCHED __builtin_amdgcn_sched_barrier(0)
; template <class Epi, class Sched, bool ALIGN_EPI = false, bool SP2 = false>
; __device__ __forceinline__ void gemm_phase(PG8_LAS unsigned char* lds, const Gemm g, const Sched& S, const Epi& E) {
;     ...
;             PG8_WAIT_V(8); PG8_WAIT_L(0); PG8_BAR; PG8_MMA(1, 0, At, B0); PG8_MMA(1, 1, At, B1); PG8_BAR; PG8_SCHED;
;             PG8_LDB(B0, 1, 0); PG8_LDB(B1, 1, 1); PG8_SCHED; PG8_LDA(At, 1, 0); PG8_STAGE(PG8_SA(0, 1), a2 + hstep, voffA);
;             PG8_WAIT_V(8); PG8_WAIT_L(0); PG8_BAR; PG8_MMA(0, 0, At, B0); PG8_MMA(0, 1, At, B1); PG8_BAR; PG8_SCHED;
	v_mfma_f32_16x16x32_bf16 v[62:65], v[146:149], v[184:187], v[62:65]
	v_mfma_f32_16x16x32_bf16 v[62:65], v[150:153], v[188:191], v[62:65]
	v_mfma_f32_16x16x32_bf16 v[54:57], v[150:153], v[204:207], v[54:57]
	v_mfma_f32_16x16x32_bf16 v[54:57], v[146:149], v[200:203], v[54:57]
	v_mfma_f32_16x16x32_bf16 v[42:45], v[146:149], v[208:211], v[42:45]
	v_mfma_f32_16x16x32_bf16 v[42:45], v[150:153], v[212:215], v[42:45]
	v_mfma_f32_16x16x32_bf16 v[26:29], v[150:153], v[220:223], v[26:29]
	v_mfma_f32_16x16x32_bf16 v[26:29], v[146:149], v[216:219], v[26:29]
	v_mfma_f32_16x16x32_bf16 v[18:21], v[154:157], v[216:219], v[18:21]
	v_mfma_f32_16x16x32_bf16 v[18:21], v[158:161], v[220:223], v[18:21]
	v_mfma_f32_16x16x32_bf16 v[58:61], v[158:161], v[188:191], v[58:61]
	v_mfma_f32_16x16x32_bf16 v[58:61], v[154:157], v[184:187], v[58:61]
	v_mfma_f32_16x16x32_bf16 v[50:53], v[154:157], v[200:203], v[50:53]
	v_mfma_f32_16x16x32_bf16 v[50:53], v[158:161], v[204:207], v[50:53]
	v_mfma_f32_16x16x32_bf16 v[34:37], v[158:161], v[212:215], v[34:37]
	v_mfma_f32_16x16x32_bf16 v[34:37], v[154:157], v[208:211], v[34:37]
	s_setprio 0
	s_setprio 1
	v_mfma_f32_16x16x32_bf16 v[46:49], v[168:171], v[184:187], v[46:49]
	v_mfma_f32_16x16x32_bf16 v[46:49], v[172:175], v[188:191], v[46:49]
	v_mfma_f32_16x16x32_bf16 v[30:33], v[172:175], v[204:207], v[30:33]
	v_mfma_f32_16x16x32_bf16 v[30:33], v[168:171], v[200:203], v[30:33]
	v_mfma_f32_16x16x32_bf16 v[14:17], v[168:171], v[208:211], v[14:17]
	v_mfma_f32_16x16x32_bf16 v[14:17], v[172:175], v[212:215], v[14:17]
	v_mfma_f32_16x16x32_bf16 v[6:9], v[172:175], v[220:223], v[6:9]
	v_mfma_f32_16x16x32_bf16 v[6:9], v[168:171], v[216:219], v[6:9]
	v_mfma_f32_16x16x32_bf16 v[2:5], v[176:179], v[216:219], v[2:5]
	v_mfma_f32_16x16x32_bf16 v[2:5], v[180:183], v[220:223], v[2:5]
	v_mfma_f32_16x16x32_bf16 v[38:41], v[180:183], v[188:191], v[38:41]
	v_mfma_f32_16x16x32_bf16 v[38:41], v[176:179], v[184:187], v[38:41]
	v_mfma_f32_16x16x32_bf16 v[22:25], v[176:179], v[200:203], v[22:25]
	v_mfma_f32_16x16x32_bf16 v[22:25], v[180:183], v[204:207], v[22:25]
	v_mfma_f32_16x16x32_bf16 v[10:13], v[180:183], v[212:215], v[10:13]
	v_mfma_f32_16x16x32_bf16 v[10:13], v[176:179], v[208:211], v[10:13]
	s_barrier
	s_setprio 0
	ds_read_b128 v[146:149], v143
	ds_read_b128 v[150:153], v143 offset:1024
	ds_read_b128 v[154:157], v143 offset:2048
	ds_read_b128 v[158:161], v143 offset:3072
	ds_read_b128 v[168:171], v144
	ds_read_b128 v[172:175], v144 offset:1024
	ds_read_b128 v[176:179], v144 offset:2048
	ds_read_b128 v[180:183], v144 offset:3072
	s_add_u32 s46, s54, 0x100000
	s_addc_u32 s47, s55, 0
	s_mov_b32 m0, s17
	v_lshl_add_u64 v[226:227], s[46:47], 0, v[130:131]
	ds_read_b128 v[184:187], v142 offset:32768
	ds_read_b128 v[188:191], v142 offset:33792
	ds_read_b128 v[200:203], v142 offset:34816
	ds_read_b128 v[204:207], v142 offset:35840
	ds_read_b128 v[208:211], v142 offset:36864
	ds_read_b128 v[212:215], v142 offset:37888
	ds_read_b128 v[216:219], v142 offset:38912
	ds_read_b128 v[220:223], v142 offset:39936
	global_load_lds_dwordx4 v[226:227], off
	v_lshl_add_u64 v[226:227], s[46:47], 0, v[132:133]
	s_mov_b32 m0, s26
	s_nop 0
	global_load_lds_dwordx4 v[226:227], off
	s_waitcnt vmcnt(8)
	s_waitcnt lgkmcnt(0)
	s_setprio 1
	s_barrier
	v_mfma_f32_16x16x32_bf16 v[126:129], v[146:149], v[184:187], v[126:129]
	v_mfma_f32_16x16x32_bf16 v[126:129], v[150:153], v[188:191], v[126:129]
	v_mfma_f32_16x16x32_bf16 v[118:121], v[150:153], v[204:207], v[118:121]
	v_mfma_f32_16x16x32_bf16 v[118:121], v[146:149], v[200:203], v[118:121]
	v_mfma_f32_16x16x32_bf16 v[106:109], v[146:149], v[208:211], v[106:109]
	v_mfma_f32_16x16x32_bf16 v[106:109], v[150:153], v[212:215], v[106:109]
	v_mfma_f32_16x16x32_bf16 v[90:93], v[150:153], v[220:223], v[90:93]
	v_mfma_f32_16x16x32_bf16 v[90:93], v[146:149], v[216:219], v[90:93]
	v_mfma_f32_16x16x32_bf16 v[82:85], v[154:157], v[216:219], v[82:85]
	v_mfma_f32_16x16x32_bf16 v[82:85], v[158:161], v[220:223], v[82:85]
	v_mfma_f32_16x16x32_bf16 v[122:125], v[158:161], v[188:191], v[122:125]
	v_mfma_f32_16x16x32_bf16 v[122:125], v[154:157], v[184:187], v[122:125]
	v_mfma_f32_16x16x32_bf16 v[114:117], v[154:157], v[200:203], v[114:117]
	v_mfma_f32_16x16x32_bf16 v[114:117], v[158:161], v[204:207], v[114:117]
	v_mfma_f32_16x16x32_bf16 v[98:101], v[158:161], v[212:215], v[98:101]
	v_mfma_f32_16x16x32_bf16 v[98:101], v[154:157], v[208:211], v[98:101]
	s_setprio 0
	s_setprio 1
	v_mfma_f32_16x16x32_bf16 v[110:113], v[168:171], v[184:187], v[110:113]
	v_mfma_f32_16x16x32_bf16 v[110:113], v[172:175], v[188:191], v[110:113]
	v_mfma_f32_16x16x32_bf16 v[94:97], v[172:175], v[204:207], v[94:97]
	v_mfma_f32_16x16x32_bf16 v[94:97], v[168:171], v[200:203], v[94:97]
	v_mfma_f32_16x16x32_bf16 v[78:81], v[168:171], v[208:211], v[78:81]
	v_mfma_f32_16x16x32_bf16 v[78:81], v[172:175], v[212:215], v[78:81]
	v_mfma_f32_16x16x32_bf16 v[70:73], v[172:175], v[220:223], v[70:73]
	v_mfma_f32_16x16x32_bf16 v[70:73], v[168:171], v[216:219], v[70:73]
	v_mfma_f32_16x16x32_bf16 v[66:69], v[176:179], v[216:219], v[66:69]
	v_mfma_f32_16x16x32_bf16 v[66:69], v[180:183], v[220:223], v[66:69]
	v_mfma_f32_16x16x32_bf16 v[102:105], v[180:183], v[188:191], v[102:105]
	v_mfma_f32_16x16x32_bf16 v[102:105], v[176:179], v[184:187], v[102:105]
	v_mfma_f32_16x16x32_bf16 v[86:89], v[176:179], v[200:203], v[86:89]
	v_mfma_f32_16x16x32_bf16 v[86:89], v[180:183], v[204:207], v[86:89]
	v_mfma_f32_16x16x32_bf16 v[74:77], v[180:183], v[212:215], v[74:77]
	v_mfma_f32_16x16x32_bf16 v[74:77], v[176:179], v[208:211], v[74:77]
	s_barrier
; #define PG8_STAGE(bufoff, gbase, voff) do { _Pragma("unroll") for (int _i = 0; _i < 2; ++_i) \
;         __builtin_amdgcn_global_load_lds((const unsigned*)((const char*)(gbase) + (voff)[_i]), (PG8_LAS unsigned*)(lds + (bufoff) + ldsw + _i * 8192), 16, 0, 0); } while (0)
; #define PG8_LDA(dst, b, h) do { _Pragma("unroll") for (int m = 0; m < 4; ++m) _Pragma("unroll") for (int k = 0; k < 2; ++k) dst[m][k] = *(const PG8_LAS bf16x8*)(lds + PG8_SA(b, h) + aoff + m * 2048 + k * 1024); } while (0)
; #define PG8_MMA(ai, bj, At, Bt) do { __builtin_amdgcn_s_setprio(1); _Pragma("unroll") for (int m = 0; m < 4; ++m) _Pragma("unroll") for (int n = 0; n < 2; ++n) _Pragma("unroll") for (int k = 0; k < 2; ++k) \
;         acc[ai][bj][m][n] = __builtin_amdgcn_mfma_f32_16x16x32_bf16(Bt[n][k], At[m][k], acc[ai][bj][m][n], 0, 0, 0); __builtin_amdgcn_s_setprio(0); } while (0)
; #define PG8_WAIT_V(n) asm volatile("s_waitcnt vmcnt(" #n ")" ::: "memory")
; #define PG8_WAIT_L(n) asm volatile("s_waitcnt lgkmcnt(" #n ")" ::: "memory")
; #define PG8_BAR __builtin_amdgcn_s_barrier()
; #define PG8_SCHED __builtin_amdgcn_sched_barrier(0)
; template <class Epi, class Sched, bool ALIGN_EPI = false, bool SP2 = false>
; __device__ __forceinline__ void gemm_phase(PG8_LAS unsigned char* lds, const Gemm g, const Sched& S, const Epi& E) {
;     ...
;             PG8_LDA(At, 1, 1); PG8_STAGE(PG8_SB(1, 0), b3, voffB); PG8_STAGE(PG8_SB(1, 1), b3 + hstep, voffB); PG8_STAGE(PG8_SA(1, 0), a3, voffA);
;             PG8_WAIT_V(8); PG8_WAIT_L(0); PG8_BAR; PG8_MMA(1, 0, At, B0); PG8_MMA(1, 1, At, B1); PG8_BAR; PG8_SCHED;
;     ...
;         if constexpr (ALIGN_EPI) { if (wr == 0) PG8_BAR; }
	s_setprio 0
	s_mov_b32 m0, s44
	v_lshl_add_u64 v[162:163], v[162:163], 0, s[12:13]
	s_add_u32 s46, s52, 0x100080
	ds_read_b128 v[184:187], v142 offset:49152
	ds_read_b128 v[188:191], v142 offset:50176
	ds_read_b128 v[200:203], v142 offset:51200
	ds_read_b128 v[204:207], v142 offset:52224
	ds_read_b128 v[208:211], v142 offset:53248
	ds_read_b128 v[212:215], v142 offset:54272
	ds_read_b128 v[216:219], v142 offset:55296
	ds_read_b128 v[220:223], v142 offset:56320
	global_load_lds_dwordx4 v[162:163], off
	v_lshl_add_u64 v[162:163], v[192:193], 0, s[12:13]
	s_mov_b32 m0, s45
	s_addc_u32 s47, s53, 0
	global_load_lds_dwordx4 v[162:163], off
	v_lshl_add_u64 v[162:163], s[46:47], 0, v[130:131]
	s_mov_b32 m0, s56
	s_nop 0
	global_load_lds_dwordx4 v[162:163], off
	v_lshl_add_u64 v[162:163], s[46:47], 0, v[132:133]
	s_mov_b32 m0, s57
	s_nop 0
	global_load_lds_dwordx4 v[162:163], off
	v_lshl_add_u64 v[162:163], v[194:195], 0, s[12:13]
	s_mov_b32 m0, s28
	s_nop 0
	global_load_lds_dwordx4 v[162:163], off
	v_lshl_add_u64 v[162:163], v[224:225], 0, s[12:13]
	s_mov_b32 m0, s29
	s_nop 0
	global_load_lds_dwordx4 v[162:163], off
	s_waitcnt vmcnt(8)
	s_waitcnt lgkmcnt(0)
	s_setprio 1
	s_barrier
	v_mfma_f32_16x16x32_bf16 v[62:65], v[146:149], v[184:187], v[62:65]
	v_mfma_f32_16x16x32_bf16 v[62:65], v[150:153], v[188:191], v[62:65]
	v_mfma_f32_16x16x32_bf16 v[54:57], v[150:153], v[204:207], v[54:57]
	v_mfma_f32_16x16x32_bf16 v[54:57], v[146:149], v[200:203], v[54:57]
	v_mfma_f32_16x16x32_bf16 v[42:45], v[146:149], v[208:211], v[42:45]
	v_mfma_f32_16x16x32_bf16 v[42:45], v[150:153], v[212:215], v[42:45]
	v_mfma_f32_16x16x32_bf16 v[26:29], v[150:153], v[220:223], v[26:29]
	v_mfma_f32_16x16x32_bf16 v[26:29], v[146:149], v[216:219], v[26:29]
	v_mfma_f32_16x16x32_bf16 v[18:21], v[154:157], v[216:219], v[18:21]
	v_mfma_f32_16x16x32_bf16 v[18:21], v[158:161], v[220:223], v[18:21]
	v_mfma_f32_16x16x32_bf16 v[58:61], v[158:161], v[188:191], v[58:61]
	v_mfma_f32_16x16x32_bf16 v[58:61], v[154:157], v[184:187], v[58:61]
	v_mfma_f32_16x16x32_bf16 v[50:53], v[154:157], v[200:203], v[50:53]
	v_mfma_f32_16x16x32_bf16 v[50:53], v[158:161], v[204:207], v[50:53]
	v_mfma_f32_16x16x32_bf16 v[34:37], v[158:161], v[212:215], v[34:37]
	v_mfma_f32_16x16x32_bf16 v[34:37], v[154:157], v[208:211], v[34:37]
	s_setprio 0
	s_setprio 1
	v_mfma_f32_16x16x32_bf16 v[46:49], v[168:171], v[184:187], v[46:49]
	v_mfma_f32_16x16x32_bf16 v[46:49], v[172:175], v[188:191], v[46:49]
	v_mfma_f32_16x16x32_bf16 v[30:33], v[172:175], v[204:207], v[30:33]
	v_mfma_f32_16x16x32_bf16 v[30:33], v[168:171], v[200:203], v[30:33]
	v_mfma_f32_16x16x32_bf16 v[14:17], v[168:171], v[208:211], v[14:17]
	v_mfma_f32_16x16x32_bf16 v[14:17], v[172:175], v[212:215], v[14:17]
	v_mfma_f32_16x16x32_bf16 v[6:9], v[172:175], v[220:223], v[6:9]
	v_mfma_f32_16x16x32_bf16 v[6:9], v[168:171], v[216:219], v[6:9]
	v_mfma_f32_16x16x32_bf16 v[2:5], v[176:179], v[216:219], v[2:5]
	v_mfma_f32_16x16x32_bf16 v[2:5], v[180:183], v[220:223], v[2:5]
	v_mfma_f32_16x16x32_bf16 v[38:41], v[180:183], v[188:191], v[38:41]
	v_mfma_f32_16x16x32_bf16 v[38:41], v[176:179], v[184:187], v[38:41]
	v_mfma_f32_16x16x32_bf16 v[22:25], v[176:179], v[200:203], v[22:25]
	v_mfma_f32_16x16x32_bf16 v[22:25], v[180:183], v[204:207], v[22:25]
	v_mfma_f32_16x16x32_bf16 v[10:13], v[180:183], v[212:215], v[10:13]
	v_mfma_f32_16x16x32_bf16 v[10:13], v[176:179], v[208:211], v[10:13]
	s_barrier
	s_setprio 0
	s_add_i32 s30, s30, 2
	s_cmp_gt_u32 s30, 13
	s_mov_b64 s[46:47], s[50:51]
	s_cbranch_scc0 .LBB0_1230
	s_cmpk_lt_u32 s2, 0x100
	s_cbranch_scc0 .LBB0_1233
	s_barrier

; #define PG8_STAGE(bufoff, gbase, voff) do { _Pragma("unroll") for (int _i = 0; _i < 2; ++_i) \
;         __builtin_amdgcn_global_load_lds((const unsigned*)((const char*)(gbase) + (voff)[_i]), (PG8_LAS unsigned*)(lds + (bufoff) + ldsw + _i * 8192), 16, 0, 0); } while (0)
; #define PG8_LDA(dst, b, h) do { _Pragma("unroll") for (int m = 0; m < 4; ++m) _Pragma("unroll") for (int k = 0; k < 2; ++k) dst[m][k] = *(const PG8_LAS bf16x8*)(lds + PG8_SA(b, h) + aoff + m * 2048 + k * 1024); } while (0)
; #define PG8_LDB(dst, b, h) do { _Pragma("unroll") for (int n = 0; n < 2; ++n) _Pragma("unroll") for (int k = 0; k < 2; ++k) dst[n][k] = *(const PG8_LAS bf16x8*)(lds + PG8_SB(b, h) + boff + n * 2048 + k * 1024); } while (0)
; #define PG8_MMA(ai, bj, At, Bt) do { __builtin_amdgcn_s_setprio(1); _Pragma("unroll") for (int m = 0; m < 4; ++m) _Pragma("unroll") for (int n = 0; n < 2; ++n) _Pragma("unroll") for (int k = 0; k < 2; ++k) \
;         acc[ai][bj][m][n] = __builtin_amdgcn_mfma_f32_16x16x32_bf16(Bt[n][k], At[m][k], acc[ai][bj][m][n], 0, 0, 0); __builtin_amdgcn_s_setprio(0); } while (0)
; #define PG8_WAIT_V(n) asm volatile("s_waitcnt vmcnt(" #n ")" ::: "memory")
; #define PG8_WAIT_L(n) asm volatile("s_waitcnt lgkmcnt(" #n ")" ::: "memory")
; #define PG8_BAR __builtin_amdgcn_s_barrier()
; #define PG8_SCHED __builtin_amdgcn_sched_barrier(0)
; template <class Epi, class Sched, bool ALIGN_EPI = false, bool SP2 = false>
; __device__ __forceinline__ void gemm_phase(PG8_LAS unsigned char* lds, const Gemm g, const Sched& S, const Epi& E) {
;     ...
;             const bool last = (t == nt - 2);
;             const char* a1 = cA + (size_t)(t + 1) * kstep;
;             const char* a2 = last ? nA : cA + (size_t)(t + 2) * kstep; const char* b2 = last ? nB : cB + (size_t)(t + 2) * kstep;
;             const char* a3 = a2 + kstep; const char* b3 = b2 + kstep;
;             if (last && has_next) S.a_ready(nxt);
;             if constexpr (SP2) {
;             PG8_LDB(B0, 0, 0); PG8_LDB(B1, 0, 1); PG8_SCHED; PG8_LDA(At, 0, 0); PG8_STAGE(PG8_SA(1, 1), a1 + hstep, voffA);
;             PG8_WAIT_V(8); PG8_WAIT_L(0); PG8_BAR; PG8_MMA(0, 0, At, B0); PG8_MMA(0, 1, At, B1); PG8_BAR; PG8_SCHED;
;             PG8_LDA(At, 0, 1); PG8_STAGE(PG8_SB(0, 0), b2, voffB); PG8_STAGE(PG8_SB(0, 1), b2 + hstep, voffB); PG8_STAGE(PG8_SA(0, 0), a2, voffA);
.LBB0_1478:
	v_add_u32_e32 v144, s31, v201
	v_add_u32_e32 v160, s52, v201
	ds_read_b128 v[132:135], v144
	ds_read_b128 v[136:139], v144 offset:1024
	ds_read_b128 v[140:143], v144 offset:2048
	ds_read_b128 v[144:147], v144 offset:3072
	ds_read_b128 v[148:151], v160
	ds_read_b128 v[152:155], v160 offset:1024
	ds_read_b128 v[156:159], v160 offset:2048
	ds_read_b128 v[160:163], v160 offset:3072
	s_add_u32 s50, s82, 0xfff00080
	s_addc_u32 s56, s83, -1
	s_and_b64 s[34:35], s[84:85], exec
	s_cselect_b32 s87, s65, s56
	s_cselect_b32 s86, s69, s50
	s_cselect_b32 s85, s67, s88
	s_cselect_b32 s84, s77, s79
	v_lshl_add_u64 v[192:193], s[82:83], 0, v[220:221]
	s_add_i32 m0, s28, 0xc000
	ds_read_b128 v[164:167], v242
	ds_read_b128 v[168:171], v242 offset:1024
	ds_read_b128 v[172:175], v242 offset:2048
	ds_read_b128 v[176:179], v242 offset:3072
	ds_read_b128 v[180:183], v242 offset:4096
	ds_read_b128 v[184:187], v242 offset:5120
	ds_read_b128 v[188:191], v242 offset:6144
	ds_read_b128 v[226:229], v242 offset:7168
	global_load_lds_dwordx4 v[192:193], off
	v_lshl_add_u64 v[192:193], s[82:83], 0, v[222:223]
	s_add_i32 m0, s28, 0xe000
	s_nop 0
	global_load_lds_dwordx4 v[192:193], off
	s_waitcnt vmcnt(8)
	s_waitcnt lgkmcnt(0)
	s_setprio 1
	s_barrier
	v_mfma_f32_16x16x32_bf16 v[126:129], v[132:135], v[164:167], v[126:129]
	v_mfma_f32_16x16x32_bf16 v[126:129], v[136:139], v[168:171], v[126:129]
	v_mfma_f32_16x16x32_bf16 v[118:121], v[136:139], v[176:179], v[118:121]
	v_mfma_f32_16x16x32_bf16 v[118:121], v[132:135], v[172:175], v[118:121]
	v_mfma_f32_16x16x32_bf16 v[110:113], v[132:135], v[180:183], v[110:113]
	v_mfma_f32_16x16x32_bf16 v[110:113], v[136:139], v[184:187], v[110:113]
	v_mfma_f32_16x16x32_bf16 v[102:105], v[136:139], v[226:229], v[102:105]
	v_mfma_f32_16x16x32_bf16 v[102:105], v[132:135], v[188:191], v[102:105]
	v_mfma_f32_16x16x32_bf16 v[106:109], v[140:143], v[188:191], v[106:109]
	v_mfma_f32_16x16x32_bf16 v[106:109], v[144:147], v[226:229], v[106:109]
	v_mfma_f32_16x16x32_bf16 v[46:49], v[144:147], v[168:171], v[46:49]
	v_mfma_f32_16x16x32_bf16 v[46:49], v[140:143], v[164:167], v[46:49]
	v_mfma_f32_16x16x32_bf16 v[122:125], v[140:143], v[172:175], v[122:125]
	v_mfma_f32_16x16x32_bf16 v[122:125], v[144:147], v[176:179], v[122:125]
	v_mfma_f32_16x16x32_bf16 v[114:117], v[144:147], v[184:187], v[114:117]
	v_mfma_f32_16x16x32_bf16 v[114:117], v[140:143], v[180:183], v[114:117]
	s_setprio 0
	s_setprio 1
	v_mfma_f32_16x16x32_bf16 v[54:57], v[148:151], v[164:167], v[54:57]
	v_mfma_f32_16x16x32_bf16 v[54:57], v[152:155], v[168:171], v[54:57]
	v_mfma_f32_16x16x32_bf16 v[58:61], v[152:155], v[176:179], v[58:61]
	v_mfma_f32_16x16x32_bf16 v[58:61], v[148:151], v[172:175], v[58:61]
	v_mfma_f32_16x16x32_bf16 v[62:65], v[148:151], v[180:183], v[62:65]
	v_mfma_f32_16x16x32_bf16 v[62:65], v[152:155], v[184:187], v[62:65]
	v_mfma_f32_16x16x32_bf16 v[98:101], v[152:155], v[226:229], v[98:101]
	v_mfma_f32_16x16x32_bf16 v[98:101], v[148:151], v[188:191], v[98:101]
	v_mfma_f32_16x16x32_bf16 v[50:53], v[156:159], v[188:191], v[50:53]
	v_mfma_f32_16x16x32_bf16 v[50:53], v[160:163], v[226:229], v[50:53]
	v_mfma_f32_16x16x32_bf16 v[38:41], v[160:163], v[168:171], v[38:41]
	v_mfma_f32_16x16x32_bf16 v[38:41], v[156:159], v[164:167], v[38:41]
	v_mfma_f32_16x16x32_bf16 v[30:33], v[156:159], v[172:175], v[30:33]
	v_mfma_f32_16x16x32_bf16 v[30:33], v[160:163], v[176:179], v[30:33]
	v_mfma_f32_16x16x32_bf16 v[22:25], v[160:163], v[184:187], v[22:25]
	v_mfma_f32_16x16x32_bf16 v[22:25], v[156:159], v[180:183], v[22:25]
	s_barrier
	s_setprio 0
	s_add_i32 s34, s31, s45
	v_lshl_add_u64 v[192:193], s[84:85], 0, v[208:209]
	s_mov_b32 m0, s34
	ds_read_b128 v[164:167], v242 offset:16384
	ds_read_b128 v[168:171], v242 offset:17408
	ds_read_b128 v[172:175], v242 offset:18432
	ds_read_b128 v[176:179], v242 offset:19456
	ds_read_b128 v[180:183], v242 offset:20480
	ds_read_b128 v[184:187], v242 offset:21504
	ds_read_b128 v[188:191], v242 offset:22528
	ds_read_b128 v[226:229], v242 offset:23552
	global_load_lds_dwordx4 v[192:193], off
	s_add_i32 m0, s34, 0x2000
	s_add_u32 s34, s84, 0x100000
	v_lshl_add_u64 v[194:195], s[84:85], 0, v[212:213]
	s_addc_u32 s35, s85, 0
	s_add_i32 s50, s52, s45
	global_load_lds_dwordx4 v[194:195], off
	v_lshl_add_u64 v[230:231], s[34:35], 0, v[208:209]
	s_mov_b32 m0, s50
	v_lshl_add_u64 v[232:233], s[86:87], 0, v[210:211]
	global_load_lds_dwordx4 v[230:231], off
	v_lshl_add_u64 v[230:231], s[34:35], 0, v[212:213]
	s_add_i32 m0, s50, 0x2000
	s_nop 0
	global_load_lds_dwordx4 v[230:231], off
	v_lshl_add_u64 v[230:231], s[86:87], 0, v[206:207]
	s_mov_b32 m0, s28
	s_nop 0
	global_load_lds_dwordx4 v[230:231], off
	s_mov_b32 m0, s29
	s_nop 0
	global_load_lds_dwordx4 v[232:233], off
	s_waitcnt vmcnt(8)
	s_waitcnt lgkmcnt(0)
	s_setprio 1
	s_barrier
; #define PG8_STAGE(bufoff, gbase, voff) do { _Pragma("unroll") for (int _i = 0; _i < 2; ++_i) \
;         __builtin_amdgcn_global_load_lds((const unsigned*)((const char*)(gbase) + (voff)[_i]), (PG8_LAS unsigned*)(lds + (bufoff) + ldsw + _i * 8192), 16, 0, 0); } while (0)
; #define PG8_LDA(dst, b, h) do { _Pragma("unroll") for (int m = 0; m < 4; ++m) _Pragma("unroll") for (int k = 0; k < 2; ++k) dst[m][k] = *(const PG8_LAS bf16x8*)(lds + PG8_SA(b, h) + aoff + m * 2048 + k * 1024); } while (0)
; #define PG8_LDB(dst, b, h) do { _Pragma("unroll") for (int n = 0; n < 2; ++n) _Pragma("unroll") for (int k = 0; k < 2; ++k) dst[n][k] = *(const PG8_LAS bf16x8*)(lds + PG8_SB(b, h) + boff + n * 2048 + k * 1024); } while (0)
; #define PG8_MMA(ai, bj, At, Bt) do { __builtin_amdgcn_s_setprio(1); _Pragma("unroll") for (int m = 0; m < 4; ++m) _Pragma("unroll") for (int n = 0; n < 2; ++n) _Pragma("unroll") for (int k = 0; k < 2; ++k) \
;         acc[ai][bj][m][n] = __builtin_amdgcn_mfma_f32_16x16x32_bf16(Bt[n][k], At[m][k], acc[ai][bj][m][n], 0, 0, 0); __builtin_amdgcn_s_setprio(0); } while (0)
; #define PG8_WAIT_V(n) asm volatile("s_waitcnt vmcnt(" #n ")" ::: "memory")
; #define PG8_WAIT_L(n) asm volatile("s_waitcnt lgkmcnt(" #n ")" ::: "memory")
; #define PG8_BAR __builtin_amdgcn_s_barrier()
; #define PG8_SCHED __builtin_amdgcn_sched_barrier(0)
; template <class Epi, class Sched, bool ALIGN_EPI = false, bool SP2 = false>
; __device__ __forceinline__ void gemm_phase(PG8_LAS unsigned char* lds, const Gemm g, const Sched& S, const Epi& E) {
;     ...
;             PG8_WAIT_V(8); PG8_WAIT_L(0); PG8_BAR; PG8_MMA(1, 0, At, B0); PG8_MMA(1, 1, At, B1); PG8_BAR; PG8_SCHED;
;             PG8_LDB(B0, 1, 0); PG8_LDB(B1, 1, 1); PG8_SCHED; PG8_LDA(At, 1, 0); PG8_STAGE(PG8_SA(0, 1), a2 + hstep, voffA);
;             PG8_WAIT_V(8); PG8_WAIT_L(0); PG8_BAR; PG8_MMA(0, 0, At, B0); PG8_MMA(0, 1, At, B1); PG8_BAR; PG8_SCHED;
	v_mfma_f32_16x16x32_bf16 v[78:81], v[132:135], v[164:167], v[78:81]
	v_mfma_f32_16x16x32_bf16 v[78:81], v[136:139], v[168:171], v[78:81]
	v_mfma_f32_16x16x32_bf16 v[66:69], v[136:139], v[176:179], v[66:69]
	v_mfma_f32_16x16x32_bf16 v[66:69], v[132:135], v[172:175], v[66:69]
	v_mfma_f32_16x16x32_bf16 v[70:73], v[132:135], v[180:183], v[70:73]
	v_mfma_f32_16x16x32_bf16 v[70:73], v[136:139], v[184:187], v[70:73]
	v_mfma_f32_16x16x32_bf16 v[74:77], v[136:139], v[226:229], v[74:77]
	v_mfma_f32_16x16x32_bf16 v[74:77], v[132:135], v[188:191], v[74:77]
	v_mfma_f32_16x16x32_bf16 v[10:13], v[140:143], v[188:191], v[10:13]
	v_mfma_f32_16x16x32_bf16 v[10:13], v[144:147], v[226:229], v[10:13]
	v_mfma_f32_16x16x32_bf16 v[14:17], v[144:147], v[168:171], v[14:17]
	v_mfma_f32_16x16x32_bf16 v[14:17], v[140:143], v[164:167], v[14:17]
	v_mfma_f32_16x16x32_bf16 v[94:97], v[140:143], v[172:175], v[94:97]
	v_mfma_f32_16x16x32_bf16 v[94:97], v[144:147], v[176:179], v[94:97]
	v_mfma_f32_16x16x32_bf16 v[90:93], v[144:147], v[184:187], v[90:93]
	v_mfma_f32_16x16x32_bf16 v[90:93], v[140:143], v[180:183], v[90:93]
	s_setprio 0
	s_setprio 1
	v_mfma_f32_16x16x32_bf16 v[42:45], v[148:151], v[164:167], v[42:45]
	v_mfma_f32_16x16x32_bf16 v[42:45], v[152:155], v[168:171], v[42:45]
	v_mfma_f32_16x16x32_bf16 v[34:37], v[152:155], v[176:179], v[34:37]
	v_mfma_f32_16x16x32_bf16 v[34:37], v[148:151], v[172:175], v[34:37]
	v_mfma_f32_16x16x32_bf16 v[86:89], v[148:151], v[180:183], v[86:89]
	v_mfma_f32_16x16x32_bf16 v[86:89], v[152:155], v[184:187], v[86:89]
	v_mfma_f32_16x16x32_bf16 v[82:85], v[152:155], v[226:229], v[82:85]
	v_mfma_f32_16x16x32_bf16 v[82:85], v[148:151], v[188:191], v[82:85]
	v_mfma_f32_16x16x32_bf16 v[18:21], v[156:159], v[188:191], v[18:21]
	v_mfma_f32_16x16x32_bf16 v[18:21], v[160:163], v[226:229], v[18:21]
	v_mfma_f32_16x16x32_bf16 v[2:5], v[160:163], v[168:171], v[2:5]
	v_mfma_f32_16x16x32_bf16 v[2:5], v[156:159], v[164:167], v[2:5]
	v_mfma_f32_16x16x32_bf16 v[6:9], v[156:159], v[172:175], v[6:9]
	v_mfma_f32_16x16x32_bf16 v[6:9], v[160:163], v[176:179], v[6:9]
	v_mfma_f32_16x16x32_bf16 v[26:29], v[160:163], v[184:187], v[26:29]
	v_mfma_f32_16x16x32_bf16 v[26:29], v[156:159], v[180:183], v[26:29]
	s_barrier
	s_setprio 0
	s_add_i32 s50, 0, 0x18000
	s_add_i32 s56, 0, 0x1c000
	v_add_u32_e32 v144, s50, v201
	v_add_u32_e32 v160, s56, v201
	ds_read_b128 v[132:135], v144
	ds_read_b128 v[136:139], v144 offset:1024
	ds_read_b128 v[140:143], v144 offset:2048
	ds_read_b128 v[144:147], v144 offset:3072
	ds_read_b128 v[148:151], v160
	ds_read_b128 v[152:155], v160 offset:1024
	ds_read_b128 v[156:159], v160 offset:2048
	ds_read_b128 v[160:163], v160 offset:3072
	s_add_u32 s34, s86, 0x100000
	s_addc_u32 s35, s87, 0
	s_mov_b32 m0, s16
	v_lshl_add_u64 v[246:247], s[34:35], 0, v[206:207]
	ds_read_b128 v[164:167], v242 offset:32768
	ds_read_b128 v[168:171], v242 offset:33792
	ds_read_b128 v[172:175], v242 offset:34816
	ds_read_b128 v[176:179], v242 offset:35840
	ds_read_b128 v[180:183], v242 offset:36864
	ds_read_b128 v[184:187], v242 offset:37888
	ds_read_b128 v[188:191], v242 offset:38912
	ds_read_b128 v[226:229], v242 offset:39936
	global_load_lds_dwordx4 v[246:247], off
	v_lshl_add_u64 v[246:247], s[34:35], 0, v[210:211]
	s_mov_b32 m0, s17
	s_nop 0
	global_load_lds_dwordx4 v[246:247], off
	s_waitcnt vmcnt(8)
	s_waitcnt lgkmcnt(0)
	s_setprio 1
	s_barrier
	v_mfma_f32_16x16x32_bf16 v[126:129], v[132:135], v[164:167], v[126:129]
	v_mfma_f32_16x16x32_bf16 v[126:129], v[136:139], v[168:171], v[126:129]
	v_mfma_f32_16x16x32_bf16 v[118:121], v[136:139], v[176:179], v[118:121]
	v_mfma_f32_16x16x32_bf16 v[118:121], v[132:135], v[172:175], v[118:121]
	v_mfma_f32_16x16x32_bf16 v[110:113], v[132:135], v[180:183], v[110:113]
	v_mfma_f32_16x16x32_bf16 v[110:113], v[136:139], v[184:187], v[110:113]
	v_mfma_f32_16x16x32_bf16 v[102:105], v[136:139], v[226:229], v[102:105]
	v_mfma_f32_16x16x32_bf16 v[102:105], v[132:135], v[188:191], v[102:105]
	v_mfma_f32_16x16x32_bf16 v[106:109], v[140:143], v[188:191], v[106:109]
	v_mfma_f32_16x16x32_bf16 v[106:109], v[144:147], v[226:229], v[106:109]
	v_mfma_f32_16x16x32_bf16 v[46:49], v[144:147], v[168:171], v[46:49]
	v_mfma_f32_16x16x32_bf16 v[46:49], v[140:143], v[164:167], v[46:49]
	v_mfma_f32_16x16x32_bf16 v[122:125], v[140:143], v[172:175], v[122:125]
	v_mfma_f32_16x16x32_bf16 v[122:125], v[144:147], v[176:179], v[122:125]
	v_mfma_f32_16x16x32_bf16 v[114:117], v[144:147], v[184:187], v[114:117]
	v_mfma_f32_16x16x32_bf16 v[114:117], v[140:143], v[180:183], v[114:117]
	s_setprio 0
	s_setprio 1
	v_mfma_f32_16x16x32_bf16 v[54:57], v[148:151], v[164:167], v[54:57]
	v_mfma_f32_16x16x32_bf16 v[54:57], v[152:155], v[168:171], v[54:57]
	v_mfma_f32_16x16x32_bf16 v[58:61], v[152:155], v[176:179], v[58:61]
	v_mfma_f32_16x16x32_bf16 v[58:61], v[148:151], v[172:175], v[58:61]
	v_mfma_f32_16x16x32_bf16 v[62:65], v[148:151], v[180:183], v[62:65]
	v_mfma_f32_16x16x32_bf16 v[62:65], v[152:155], v[184:187], v[62:65]
	v_mfma_f32_16x16x32_bf16 v[98:101], v[152:155], v[226:229], v[98:101]
	v_mfma_f32_16x16x32_bf16 v[98:101], v[148:151], v[188:191], v[98:101]
	v_mfma_f32_16x16x32_bf16 v[50:53], v[156:159], v[188:191], v[50:53]
	v_mfma_f32_16x16x32_bf16 v[50:53], v[160:163], v[226:229], v[50:53]
	v_mfma_f32_16x16x32_bf16 v[38:41], v[160:163], v[168:171], v[38:41]
	v_mfma_f32_16x16x32_bf16 v[38:41], v[156:159], v[164:167], v[38:41]
	v_mfma_f32_16x16x32_bf16 v[30:33], v[156:159], v[172:175], v[30:33]
	v_mfma_f32_16x16x32_bf16 v[30:33], v[160:163], v[176:179], v[30:33]
	v_mfma_f32_16x16x32_bf16 v[22:25], v[160:163], v[184:187], v[22:25]
	v_mfma_f32_16x16x32_bf16 v[22:25], v[156:159], v[180:183], v[22:25]
	s_barrier
; #define PG8_STAGE(bufoff, gbase, voff) do { _Pragma("unroll") for (int _i = 0; _i < 2; ++_i) \
;         __builtin_amdgcn_global_load_lds((const unsigned*)((const char*)(gbase) + (voff)[_i]), (PG8_LAS unsigned*)(lds + (bufoff) + ldsw + _i * 8192), 16, 0, 0); } while (0)
; #define PG8_LDA(dst, b, h) do { _Pragma("unroll") for (int m = 0; m < 4; ++m) _Pragma("unroll") for (int k = 0; k < 2; ++k) dst[m][k] = *(const PG8_LAS bf16x8*)(lds + PG8_SA(b, h) + aoff + m * 2048 + k * 1024); } while (0)
; #define PG8_MMA(ai, bj, At, Bt) do { __builtin_amdgcn_s_setprio(1); _Pragma("unroll") for (int m = 0; m < 4; ++m) _Pragma("unroll") for (int n = 0; n < 2; ++n) _Pragma("unroll") for (int k = 0; k < 2; ++k) \
;         acc[ai][bj][m][n] = __builtin_amdgcn_mfma_f32_16x16x32_bf16(Bt[n][k], At[m][k], acc[ai][bj][m][n], 0, 0, 0); __builtin_amdgcn_s_setprio(0); } while (0)
; #define PG8_WAIT_V(n) asm volatile("s_waitcnt vmcnt(" #n ")" ::: "memory")
; #define PG8_WAIT_L(n) asm volatile("s_waitcnt lgkmcnt(" #n ")" ::: "memory")
; #define PG8_BAR __builtin_amdgcn_s_barrier()
; #define PG8_SCHED __builtin_amdgcn_sched_barrier(0)
; template <class Epi, class Sched, bool ALIGN_EPI = false, bool SP2 = false>
; __device__ __forceinline__ void gemm_phase(PG8_LAS unsigned char* lds, const Gemm g, const Sched& S, const Epi& E) {
;     ...
;         for (int t = 0; t < nt; t += 2) {
;             const bool last = (t == nt - 2);
;             const char* a1 = cA + (size_t)(t + 1) * kstep;
;             const char* a2 = last ? nA : cA + (size_t)(t + 2) * kstep; const char* b2 = last ? nB : cB + (size_t)(t + 2) * kstep;
;     ...
;             PG8_LDA(At, 1, 1); PG8_STAGE(PG8_SB(1, 0), b3, voffB); PG8_STAGE(PG8_SB(1, 1), b3 + hstep, voffB); PG8_STAGE(PG8_SA(1, 0), a3, voffA);
;             PG8_WAIT_V(8); PG8_WAIT_L(0); PG8_BAR; PG8_MMA(1, 0, At, B0); PG8_MMA(1, 1, At, B1); PG8_BAR; PG8_SCHED;
	s_setprio 0
	s_add_i32 s34, s50, s45
	v_lshl_add_u64 v[192:193], v[192:193], 0, s[54:55]
	s_mov_b32 m0, s34
	ds_read_b128 v[164:167], v242 offset:49152
	ds_read_b128 v[168:171], v242 offset:50176
	ds_read_b128 v[172:175], v242 offset:51200
	ds_read_b128 v[176:179], v242 offset:52224
	ds_read_b128 v[180:183], v242 offset:53248
	ds_read_b128 v[184:187], v242 offset:54272
	ds_read_b128 v[188:191], v242 offset:55296
	ds_read_b128 v[226:229], v242 offset:56320
	global_load_lds_dwordx4 v[192:193], off
	s_add_i32 m0, s34, 0x2000
	s_add_u32 s34, s84, 0x100080
	v_lshl_add_u64 v[192:193], v[194:195], 0, s[54:55]
	s_addc_u32 s35, s85, 0
	s_add_i32 s50, s56, s45
	global_load_lds_dwordx4 v[192:193], off
	v_lshl_add_u64 v[192:193], s[34:35], 0, v[208:209]
	s_mov_b32 m0, s50
	s_nop 0
	global_load_lds_dwordx4 v[192:193], off
	v_lshl_add_u64 v[192:193], s[34:35], 0, v[212:213]
	s_add_i32 m0, s50, 0x2000
	s_nop 0
	global_load_lds_dwordx4 v[192:193], off
	v_lshl_add_u64 v[192:193], v[230:231], 0, s[54:55]
	s_mov_b32 m0, s39
	s_nop 0
	global_load_lds_dwordx4 v[192:193], off
	v_lshl_add_u64 v[192:193], v[232:233], 0, s[54:55]
	s_mov_b32 m0, s46
	s_nop 0
	global_load_lds_dwordx4 v[192:193], off
	s_waitcnt vmcnt(8)
	s_waitcnt lgkmcnt(0)
	s_setprio 1
	s_barrier
	v_mfma_f32_16x16x32_bf16 v[78:81], v[132:135], v[164:167], v[78:81]
	v_mfma_f32_16x16x32_bf16 v[78:81], v[136:139], v[168:171], v[78:81]
	v_mfma_f32_16x16x32_bf16 v[66:69], v[136:139], v[176:179], v[66:69]
	v_mfma_f32_16x16x32_bf16 v[66:69], v[132:135], v[172:175], v[66:69]
	v_mfma_f32_16x16x32_bf16 v[70:73], v[132:135], v[180:183], v[70:73]
	v_mfma_f32_16x16x32_bf16 v[70:73], v[136:139], v[184:187], v[70:73]
	v_mfma_f32_16x16x32_bf16 v[74:77], v[136:139], v[226:229], v[74:77]
	v_mfma_f32_16x16x32_bf16 v[74:77], v[132:135], v[188:191], v[74:77]
	v_mfma_f32_16x16x32_bf16 v[10:13], v[140:143], v[188:191], v[10:13]
	v_mfma_f32_16x16x32_bf16 v[10:13], v[144:147], v[226:229], v[10:13]
	v_mfma_f32_16x16x32_bf16 v[14:17], v[144:147], v[168:171], v[14:17]
	v_mfma_f32_16x16x32_bf16 v[14:17], v[140:143], v[164:167], v[14:17]
	v_mfma_f32_16x16x32_bf16 v[94:97], v[140:143], v[172:175], v[94:97]
	v_mfma_f32_16x16x32_bf16 v[94:97], v[144:147], v[176:179], v[94:97]
	v_mfma_f32_16x16x32_bf16 v[90:93], v[144:147], v[184:187], v[90:93]
	v_mfma_f32_16x16x32_bf16 v[90:93], v[140:143], v[180:183], v[90:93]
	s_setprio 0
	s_setprio 1
	v_mfma_f32_16x16x32_bf16 v[42:45], v[148:151], v[164:167], v[42:45]
	v_mfma_f32_16x16x32_bf16 v[42:45], v[152:155], v[168:171], v[42:45]
	v_mfma_f32_16x16x32_bf16 v[34:37], v[152:155], v[176:179], v[34:37]
	v_mfma_f32_16x16x32_bf16 v[34:37], v[148:151], v[172:175], v[34:37]
	v_mfma_f32_16x16x32_bf16 v[86:89], v[148:151], v[180:183], v[86:89]
	v_mfma_f32_16x16x32_bf16 v[86:89], v[152:155], v[184:187], v[86:89]
	v_mfma_f32_16x16x32_bf16 v[82:85], v[152:155], v[226:229], v[82:85]
	v_mfma_f32_16x16x32_bf16 v[82:85], v[148:151], v[188:191], v[82:85]
	v_mfma_f32_16x16x32_bf16 v[18:21], v[156:159], v[188:191], v[18:21]
	v_mfma_f32_16x16x32_bf16 v[18:21], v[160:163], v[226:229], v[18:21]
	v_mfma_f32_16x16x32_bf16 v[2:5], v[160:163], v[168:171], v[2:5]
	v_mfma_f32_16x16x32_bf16 v[2:5], v[156:159], v[164:167], v[2:5]
	v_mfma_f32_16x16x32_bf16 v[6:9], v[156:159], v[172:175], v[6:9]
	v_mfma_f32_16x16x32_bf16 v[6:9], v[160:163], v[176:179], v[6:9]
	v_mfma_f32_16x16x32_bf16 v[26:29], v[160:163], v[184:187], v[26:29]
	v_mfma_f32_16x16x32_bf16 v[26:29], v[156:159], v[180:183], v[26:29]
	s_barrier
	s_setprio 0
	s_add_i32 s89, s89, 2
	s_add_u32 s82, s82, 0x100
	s_addc_u32 s83, s83, 0
	s_add_u32 s79, s79, 0x100
	s_addc_u32 s88, s88, 0
	s_cmp_gt_u32 s89, 61
	s_cbranch_scc1 .LBB0_1490

; #define PG8_STAGE(bufoff, gbase, voff) do { _Pragma("unroll") for (int _i = 0; _i < 2; ++_i) \
;         __builtin_amdgcn_global_load_lds((const unsigned*)((const char*)(gbase) + (voff)[_i]), (PG8_LAS unsigned*)(lds + (bufoff) + ldsw + _i * 8192), 16, 0, 0); } while (0)
; #define PG8_LDA(dst, b, h) do { _Pragma("unroll") for (int m = 0; m < 4; ++m) _Pragma("unroll") for (int k = 0; k < 2; ++k) dst[m][k] = *(const PG8_LAS bf16x8*)(lds + PG8_SA(b, h) + aoff + m * 2048 + k * 1024); } while (0)
; #define PG8_LDB(dst, b, h) do { _Pragma("unroll") for (int n = 0; n < 2; ++n) _Pragma("unroll") for (int k = 0; k < 2; ++k) dst[n][k] = *(const PG8_LAS bf16x8*)(lds + PG8_SB(b, h) + boff + n * 2048 + k * 1024); } while (0)
; #define PG8_MMA(ai, bj, At, Bt) do { __builtin_amdgcn_s_setprio(1); _Pragma("unroll") for (int m = 0; m < 4; ++m) _Pragma("unroll") for (int n = 0; n < 2; ++n) _Pragma("unroll") for (int k = 0; k < 2; ++k) \
;         acc[ai][bj][m][n] = __builtin_amdgcn_mfma_f32_16x16x32_bf16(Bt[n][k], At[m][k], acc[ai][bj][m][n], 0, 0, 0); __builtin_amdgcn_s_setprio(0); } while (0)
; #define PG8_WAIT_V(n) asm volatile("s_waitcnt vmcnt(" #n ")" ::: "memory")
; #define PG8_WAIT_L(n) asm volatile("s_waitcnt lgkmcnt(" #n ")" ::: "memory")
; #define PG8_BAR __builtin_amdgcn_s_barrier()
; #define PG8_SCHED __builtin_amdgcn_sched_barrier(0)
; template <class Epi, class Sched, bool ALIGN_EPI = false, bool SP2 = false>
; __device__ __forceinline__ void gemm_phase(PG8_LAS unsigned char* lds, const Gemm g, const Sched& S, const Epi& E) {
;     ...
;             const bool last = (t == nt - 2);
;             const char* a1 = cA + (size_t)(t + 1) * kstep;
;             const char* a2 = last ? nA : cA + (size_t)(t + 2) * kstep; const char* b2 = last ? nB : cB + (size_t)(t + 2) * kstep;
;             const char* a3 = a2 + kstep; const char* b3 = b2 + kstep;
;             if (last && has_next) S.a_ready(nxt);
;             if constexpr (SP2) {
;             PG8_LDB(B0, 0, 0); PG8_LDB(B1, 0, 1); PG8_SCHED; PG8_LDA(At, 0, 0); PG8_STAGE(PG8_SA(1, 1), a1 + hstep, voffA);
;             PG8_WAIT_V(8); PG8_WAIT_L(0); PG8_BAR; PG8_MMA(0, 0, At, B0); PG8_MMA(0, 1, At, B1); PG8_BAR; PG8_SCHED;
;             PG8_LDA(At, 0, 1); PG8_STAGE(PG8_SB(0, 0), b2, voffB); PG8_STAGE(PG8_SB(0, 1), b2 + hstep, voffB); PG8_STAGE(PG8_SA(0, 0), a2, voffA);
.LBB0_1731:
	ds_read_b128 v[170:173], v166
	ds_read_b128 v[174:177], v166 offset:1024
	ds_read_b128 v[178:181], v166 offset:2048
	ds_read_b128 v[182:185], v166 offset:3072
	ds_read_b128 v[186:189], v167
	ds_read_b128 v[190:193], v167 offset:1024
	ds_read_b128 v[196:199], v167 offset:2048
	ds_read_b128 v[202:205], v167 offset:3072
	s_add_u32 s48, s40, 0x100
	s_addc_u32 s49, s41, 0
	s_cmpk_eq_i32 s56, 0xa8
	s_cselect_b32 s53, s7, s49
	s_cselect_b32 s52, s6, s48
	s_cselect_b32 s51, s39, s55
	s_cselect_b32 s50, s38, s54
	v_lshl_add_u64 v[146:147], s[40:41], 0, v[138:139]
	s_add_i32 m0, s16, 0xc000
	ds_read_b128 v[206:209], v168
	ds_read_b128 v[210:213], v168 offset:1024
	ds_read_b128 v[214:217], v168 offset:2048
	ds_read_b128 v[218:221], v168 offset:3072
	ds_read_b128 v[222:225], v168 offset:4096
	ds_read_b128 v[226:229], v168 offset:5120
	ds_read_b128 v[230:233], v168 offset:6144
	ds_read_b128 v[234:237], v168 offset:7168
	global_load_lds_dwordx4 v[146:147], off
	v_lshl_add_u64 v[146:147], s[40:41], 0, v[140:141]
	s_add_i32 m0, s16, 0xe000
	s_nop 0
	global_load_lds_dwordx4 v[146:147], off
	s_waitcnt vmcnt(8)
	s_waitcnt lgkmcnt(0)
	s_setprio 1
	s_barrier
	v_mfma_f32_16x16x32_bf16 v[126:129], v[170:173], v[206:209], v[126:129]
	v_mfma_f32_16x16x32_bf16 v[126:129], v[174:177], v[210:213], v[126:129]
	v_mfma_f32_16x16x32_bf16 v[110:113], v[174:177], v[218:221], v[110:113]
	v_mfma_f32_16x16x32_bf16 v[110:113], v[170:173], v[214:217], v[110:113]
	v_mfma_f32_16x16x32_bf16 v[94:97], v[170:173], v[222:225], v[94:97]
	v_mfma_f32_16x16x32_bf16 v[94:97], v[174:177], v[226:229], v[94:97]
	v_mfma_f32_16x16x32_bf16 v[78:81], v[174:177], v[234:237], v[78:81]
	v_mfma_f32_16x16x32_bf16 v[78:81], v[170:173], v[230:233], v[78:81]
	v_mfma_f32_16x16x32_bf16 v[74:77], v[178:181], v[230:233], v[74:77]
	v_mfma_f32_16x16x32_bf16 v[74:77], v[182:185], v[234:237], v[74:77]
	v_mfma_f32_16x16x32_bf16 v[122:125], v[182:185], v[210:213], v[122:125]
	v_mfma_f32_16x16x32_bf16 v[122:125], v[178:181], v[206:209], v[122:125]
	v_mfma_f32_16x16x32_bf16 v[106:109], v[178:181], v[214:217], v[106:109]
	v_mfma_f32_16x16x32_bf16 v[106:109], v[182:185], v[218:221], v[106:109]
	v_mfma_f32_16x16x32_bf16 v[90:93], v[182:185], v[226:229], v[90:93]
	v_mfma_f32_16x16x32_bf16 v[90:93], v[178:181], v[222:225], v[90:93]
	s_setprio 0
	s_setprio 1
	v_mfma_f32_16x16x32_bf16 v[118:121], v[186:189], v[206:209], v[118:121]
	v_mfma_f32_16x16x32_bf16 v[118:121], v[190:193], v[210:213], v[118:121]
	v_mfma_f32_16x16x32_bf16 v[102:105], v[190:193], v[218:221], v[102:105]
	v_mfma_f32_16x16x32_bf16 v[102:105], v[186:189], v[214:217], v[102:105]
	v_mfma_f32_16x16x32_bf16 v[86:89], v[186:189], v[222:225], v[86:89]
	v_mfma_f32_16x16x32_bf16 v[86:89], v[190:193], v[226:229], v[86:89]
	v_mfma_f32_16x16x32_bf16 v[70:73], v[190:193], v[234:237], v[70:73]
	v_mfma_f32_16x16x32_bf16 v[70:73], v[186:189], v[230:233], v[70:73]
	v_mfma_f32_16x16x32_bf16 v[66:69], v[196:199], v[230:233], v[66:69]
	v_mfma_f32_16x16x32_bf16 v[66:69], v[202:205], v[234:237], v[66:69]
	v_mfma_f32_16x16x32_bf16 v[114:117], v[202:205], v[210:213], v[114:117]
	v_mfma_f32_16x16x32_bf16 v[114:117], v[196:199], v[206:209], v[114:117]
	v_mfma_f32_16x16x32_bf16 v[98:101], v[196:199], v[214:217], v[98:101]
	v_mfma_f32_16x16x32_bf16 v[98:101], v[202:205], v[218:221], v[98:101]
	v_mfma_f32_16x16x32_bf16 v[82:85], v[202:205], v[226:229], v[82:85]
	v_mfma_f32_16x16x32_bf16 v[82:85], v[196:199], v[222:225], v[82:85]
	s_barrier
	s_setprio 0
	s_add_i32 s40, s31, s3
	v_lshl_add_u64 v[146:147], s[50:51], 0, v[132:133]
	s_mov_b32 m0, s40
	ds_read_b128 v[206:209], v168 offset:16384
	ds_read_b128 v[210:213], v168 offset:17408
	ds_read_b128 v[214:217], v168 offset:18432
	ds_read_b128 v[218:221], v168 offset:19456
	ds_read_b128 v[222:225], v168 offset:20480
	ds_read_b128 v[226:229], v168 offset:21504
	ds_read_b128 v[230:233], v168 offset:22528
	ds_read_b128 v[234:237], v168 offset:23552
	global_load_lds_dwordx4 v[146:147], off
	s_add_i32 m0, s40, 0x2000
	s_add_u32 s40, s50, 0x2b0000
	v_lshl_add_u64 v[194:195], s[50:51], 0, v[136:137]
	s_addc_u32 s41, s51, 0
	s_add_i32 s57, s35, s3
	global_load_lds_dwordx4 v[194:195], off
	v_lshl_add_u64 v[238:239], s[40:41], 0, v[132:133]
	s_mov_b32 m0, s57
	v_lshl_add_u64 v[240:241], s[52:53], 0, v[134:135]
	global_load_lds_dwordx4 v[238:239], off
	v_lshl_add_u64 v[238:239], s[40:41], 0, v[136:137]
	s_add_i32 m0, s57, 0x2000
	s_nop 0
	global_load_lds_dwordx4 v[238:239], off
	v_lshl_add_u64 v[238:239], s[52:53], 0, v[130:131]
	s_mov_b32 m0, s16
	s_nop 0
	global_load_lds_dwordx4 v[238:239], off
	s_mov_b32 m0, s17
	s_nop 0
	global_load_lds_dwordx4 v[240:241], off
	s_waitcnt vmcnt(8)
	s_waitcnt lgkmcnt(0)
	s_setprio 1
	s_barrier
; #define PG8_STAGE(bufoff, gbase, voff) do { _Pragma("unroll") for (int _i = 0; _i < 2; ++_i) \
;         __builtin_amdgcn_global_load_lds((const unsigned*)((const char*)(gbase) + (voff)[_i]), (PG8_LAS unsigned*)(lds + (bufoff) + ldsw + _i * 8192), 16, 0, 0); } while (0)
; #define PG8_LDA(dst, b, h) do { _Pragma("unroll") for (int m = 0; m < 4; ++m) _Pragma("unroll") for (int k = 0; k < 2; ++k) dst[m][k] = *(const PG8_LAS bf16x8*)(lds + PG8_SA(b, h) + aoff + m * 2048 + k * 1024); } while (0)
; #define PG8_LDB(dst, b, h) do { _Pragma("unroll") for (int n = 0; n < 2; ++n) _Pragma("unroll") for (int k = 0; k < 2; ++k) dst[n][k] = *(const PG8_LAS bf16x8*)(lds + PG8_SB(b, h) + boff + n * 2048 + k * 1024); } while (0)
; #define PG8_MMA(ai, bj, At, Bt) do { __builtin_amdgcn_s_setprio(1); _Pragma("unroll") for (int m = 0; m < 4; ++m) _Pragma("unroll") for (int n = 0; n < 2; ++n) _Pragma("unroll") for (int k = 0; k < 2; ++k) \
;         acc[ai][bj][m][n] = __builtin_amdgcn_mfma_f32_16x16x32_bf16(Bt[n][k], At[m][k], acc[ai][bj][m][n], 0, 0, 0); __builtin_amdgcn_s_setprio(0); } while (0)
; #define PG8_WAIT_V(n) asm volatile("s_waitcnt vmcnt(" #n ")" ::: "memory")
; #define PG8_WAIT_L(n) asm volatile("s_waitcnt lgkmcnt(" #n ")" ::: "memory")
; #define PG8_BAR __builtin_amdgcn_s_barrier()
; #define PG8_SCHED __builtin_amdgcn_sched_barrier(0)
; template <class Epi, class Sched, bool ALIGN_EPI = false, bool SP2 = false>
; __device__ __forceinline__ void gemm_phase(PG8_LAS unsigned char* lds, const Gemm g, const Sched& S, const Epi& E) {
;     ...
;             PG8_WAIT_V(8); PG8_WAIT_L(0); PG8_BAR; PG8_MMA(1, 0, At, B0); PG8_MMA(1, 1, At, B1); PG8_BAR; PG8_SCHED;
;             PG8_LDB(B0, 1, 0); PG8_LDB(B1, 1, 1); PG8_SCHED; PG8_LDA(At, 1, 0); PG8_STAGE(PG8_SA(0, 1), a2 + hstep, voffA);
;             PG8_WAIT_V(8); PG8_WAIT_L(0); PG8_BAR; PG8_MMA(0, 0, At, B0); PG8_MMA(0, 1, At, B1); PG8_BAR; PG8_SCHED;
	v_mfma_f32_16x16x32_bf16 v[62:65], v[170:173], v[206:209], v[62:65]
	v_mfma_f32_16x16x32_bf16 v[62:65], v[174:177], v[210:213], v[62:65]
	v_mfma_f32_16x16x32_bf16 v[46:49], v[174:177], v[218:221], v[46:49]
	v_mfma_f32_16x16x32_bf16 v[46:49], v[170:173], v[214:217], v[46:49]
	v_mfma_f32_16x16x32_bf16 v[30:33], v[170:173], v[222:225], v[30:33]
	v_mfma_f32_16x16x32_bf16 v[30:33], v[174:177], v[226:229], v[30:33]
	v_mfma_f32_16x16x32_bf16 v[14:17], v[174:177], v[234:237], v[14:17]
	v_mfma_f32_16x16x32_bf16 v[14:17], v[170:173], v[230:233], v[14:17]
	v_mfma_f32_16x16x32_bf16 v[10:13], v[178:181], v[230:233], v[10:13]
	v_mfma_f32_16x16x32_bf16 v[10:13], v[182:185], v[234:237], v[10:13]
	v_mfma_f32_16x16x32_bf16 v[58:61], v[182:185], v[210:213], v[58:61]
	v_mfma_f32_16x16x32_bf16 v[58:61], v[178:181], v[206:209], v[58:61]
	v_mfma_f32_16x16x32_bf16 v[42:45], v[178:181], v[214:217], v[42:45]
	v_mfma_f32_16x16x32_bf16 v[42:45], v[182:185], v[218:221], v[42:45]
	v_mfma_f32_16x16x32_bf16 v[26:29], v[182:185], v[226:229], v[26:29]
	v_mfma_f32_16x16x32_bf16 v[26:29], v[178:181], v[222:225], v[26:29]
	s_setprio 0
	s_setprio 1
	v_mfma_f32_16x16x32_bf16 v[54:57], v[186:189], v[206:209], v[54:57]
	v_mfma_f32_16x16x32_bf16 v[54:57], v[190:193], v[210:213], v[54:57]
	v_mfma_f32_16x16x32_bf16 v[38:41], v[190:193], v[218:221], v[38:41]
	v_mfma_f32_16x16x32_bf16 v[38:41], v[186:189], v[214:217], v[38:41]
	v_mfma_f32_16x16x32_bf16 v[22:25], v[186:189], v[222:225], v[22:25]
	v_mfma_f32_16x16x32_bf16 v[22:25], v[190:193], v[226:229], v[22:25]
	v_mfma_f32_16x16x32_bf16 v[6:9], v[190:193], v[234:237], v[6:9]
	v_mfma_f32_16x16x32_bf16 v[6:9], v[186:189], v[230:233], v[6:9]
	v_mfma_f32_16x16x32_bf16 v[2:5], v[196:199], v[230:233], v[2:5]
	v_mfma_f32_16x16x32_bf16 v[2:5], v[202:205], v[234:237], v[2:5]
	v_mfma_f32_16x16x32_bf16 v[50:53], v[202:205], v[210:213], v[50:53]
	v_mfma_f32_16x16x32_bf16 v[50:53], v[196:199], v[206:209], v[50:53]
	v_mfma_f32_16x16x32_bf16 v[34:37], v[196:199], v[214:217], v[34:37]
	v_mfma_f32_16x16x32_bf16 v[34:37], v[202:205], v[218:221], v[34:37]
	v_mfma_f32_16x16x32_bf16 v[18:21], v[202:205], v[226:229], v[18:21]
	v_mfma_f32_16x16x32_bf16 v[18:21], v[196:199], v[222:225], v[18:21]
	s_barrier
	s_setprio 0
	s_add_i32 s57, 0, 0x18000
	v_add_u32_e32 v169, s57, v148
	s_add_i32 s58, 0, 0x1c000
	ds_read_b128 v[170:173], v169
	ds_read_b128 v[174:177], v169 offset:1024
	ds_read_b128 v[178:181], v169 offset:2048
	ds_read_b128 v[182:185], v169 offset:3072
	v_add_u32_e32 v169, s58, v148
	ds_read_b128 v[186:189], v169
	ds_read_b128 v[190:193], v169 offset:1024
	ds_read_b128 v[196:199], v169 offset:2048
	ds_read_b128 v[202:205], v169 offset:3072
	s_add_u32 s40, s52, 0x2b0000
	s_addc_u32 s41, s53, 0
	s_mov_b32 m0, s25
	v_lshl_add_u64 v[242:243], s[40:41], 0, v[130:131]
	ds_read_b128 v[206:209], v168 offset:32768
	ds_read_b128 v[210:213], v168 offset:33792
	ds_read_b128 v[214:217], v168 offset:34816
	ds_read_b128 v[218:221], v168 offset:35840
	ds_read_b128 v[222:225], v168 offset:36864
	ds_read_b128 v[226:229], v168 offset:37888
	ds_read_b128 v[230:233], v168 offset:38912
	ds_read_b128 v[234:237], v168 offset:39936
	global_load_lds_dwordx4 v[242:243], off
	v_lshl_add_u64 v[242:243], s[40:41], 0, v[134:135]
	s_mov_b32 m0, s26
	s_nop 0
	global_load_lds_dwordx4 v[242:243], off
	s_waitcnt vmcnt(8)
	s_waitcnt lgkmcnt(0)
	s_setprio 1
	s_barrier
	v_mfma_f32_16x16x32_bf16 v[126:129], v[170:173], v[206:209], v[126:129]
	v_mfma_f32_16x16x32_bf16 v[126:129], v[174:177], v[210:213], v[126:129]
	v_mfma_f32_16x16x32_bf16 v[110:113], v[174:177], v[218:221], v[110:113]
	v_mfma_f32_16x16x32_bf16 v[110:113], v[170:173], v[214:217], v[110:113]
	v_mfma_f32_16x16x32_bf16 v[94:97], v[170:173], v[222:225], v[94:97]
	v_mfma_f32_16x16x32_bf16 v[94:97], v[174:177], v[226:229], v[94:97]
	v_mfma_f32_16x16x32_bf16 v[78:81], v[174:177], v[234:237], v[78:81]
	v_mfma_f32_16x16x32_bf16 v[78:81], v[170:173], v[230:233], v[78:81]
	v_mfma_f32_16x16x32_bf16 v[74:77], v[178:181], v[230:233], v[74:77]
	v_mfma_f32_16x16x32_bf16 v[74:77], v[182:185], v[234:237], v[74:77]
	v_mfma_f32_16x16x32_bf16 v[122:125], v[182:185], v[210:213], v[122:125]
	v_mfma_f32_16x16x32_bf16 v[122:125], v[178:181], v[206:209], v[122:125]
	v_mfma_f32_16x16x32_bf16 v[106:109], v[178:181], v[214:217], v[106:109]
	v_mfma_f32_16x16x32_bf16 v[106:109], v[182:185], v[218:221], v[106:109]
	v_mfma_f32_16x16x32_bf16 v[90:93], v[182:185], v[226:229], v[90:93]
	v_mfma_f32_16x16x32_bf16 v[90:93], v[178:181], v[222:225], v[90:93]
	s_setprio 0
	s_setprio 1
	v_mfma_f32_16x16x32_bf16 v[118:121], v[186:189], v[206:209], v[118:121]
	v_mfma_f32_16x16x32_bf16 v[118:121], v[190:193], v[210:213], v[118:121]
	v_mfma_f32_16x16x32_bf16 v[102:105], v[190:193], v[218:221], v[102:105]
	v_mfma_f32_16x16x32_bf16 v[102:105], v[186:189], v[214:217], v[102:105]
	v_mfma_f32_16x16x32_bf16 v[86:89], v[186:189], v[222:225], v[86:89]
	v_mfma_f32_16x16x32_bf16 v[86:89], v[190:193], v[226:229], v[86:89]
	v_mfma_f32_16x16x32_bf16 v[70:73], v[190:193], v[234:237], v[70:73]
	v_mfma_f32_16x16x32_bf16 v[70:73], v[186:189], v[230:233], v[70:73]
	v_mfma_f32_16x16x32_bf16 v[66:69], v[196:199], v[230:233], v[66:69]
	v_mfma_f32_16x16x32_bf16 v[66:69], v[202:205], v[234:237], v[66:69]
	v_mfma_f32_16x16x32_bf16 v[114:117], v[202:205], v[210:213], v[114:117]
	v_mfma_f32_16x16x32_bf16 v[114:117], v[196:199], v[206:209], v[114:117]
	v_mfma_f32_16x16x32_bf16 v[98:101], v[196:199], v[214:217], v[98:101]
	v_mfma_f32_16x16x32_bf16 v[98:101], v[202:205], v[218:221], v[98:101]
	v_mfma_f32_16x16x32_bf16 v[82:85], v[202:205], v[226:229], v[82:85]
	v_mfma_f32_16x16x32_bf16 v[82:85], v[196:199], v[222:225], v[82:85]
	s_barrier
; #define PG8_STAGE(bufoff, gbase, voff) do { _Pragma("unroll") for (int _i = 0; _i < 2; ++_i) \
;         __builtin_amdgcn_global_load_lds((const unsigned*)((const char*)(gbase) + (voff)[_i]), (PG8_LAS unsigned*)(lds + (bufoff) + ldsw + _i * 8192), 16, 0, 0); } while (0)
; #define PG8_LDA(dst, b, h) do { _Pragma("unroll") for (int m = 0; m < 4; ++m) _Pragma("unroll") for (int k = 0; k < 2; ++k) dst[m][k] = *(const PG8_LAS bf16x8*)(lds + PG8_SA(b, h) + aoff + m * 2048 + k * 1024); } while (0)
; #define PG8_MMA(ai, bj, At, Bt) do { __builtin_amdgcn_s_setprio(1); _Pragma("unroll") for (int m = 0; m < 4; ++m) _Pragma("unroll") for (int n = 0; n < 2; ++n) _Pragma("unroll") for (int k = 0; k < 2; ++k) \
;         acc[ai][bj][m][n] = __builtin_amdgcn_mfma_f32_16x16x32_bf16(Bt[n][k], At[m][k], acc[ai][bj][m][n], 0, 0, 0); __builtin_amdgcn_s_setprio(0); } while (0)
; #define PG8_WAIT_V(n) asm volatile("s_waitcnt vmcnt(" #n ")" ::: "memory")
; #define PG8_WAIT_L(n) asm volatile("s_waitcnt lgkmcnt(" #n ")" ::: "memory")
; #define PG8_BAR __builtin_amdgcn_s_barrier()
; #define PG8_SCHED __builtin_amdgcn_sched_barrier(0)
; template <class Epi, class Sched, bool ALIGN_EPI = false, bool SP2 = false>
; __device__ __forceinline__ void gemm_phase(PG8_LAS unsigned char* lds, const Gemm g, const Sched& S, const Epi& E) {
;     ...
;             PG8_LDA(At, 1, 1); PG8_STAGE(PG8_SB(1, 0), b3, voffB); PG8_STAGE(PG8_SB(1, 1), b3 + hstep, voffB); PG8_STAGE(PG8_SA(1, 0), a3, voffA);
;             PG8_WAIT_V(8); PG8_WAIT_L(0); PG8_BAR; PG8_MMA(1, 0, At, B0); PG8_MMA(1, 1, At, B1); PG8_BAR; PG8_SCHED;
;     ...
;         if constexpr (ALIGN_EPI) { if (wr == 0) PG8_BAR; }
	s_setprio 0
	s_add_i32 s40, s57, s3
	v_lshl_add_u64 v[146:147], v[146:147], 0, s[10:11]
	s_mov_b32 m0, s40
	ds_read_b128 v[206:209], v168 offset:49152
	ds_read_b128 v[210:213], v168 offset:50176
	ds_read_b128 v[214:217], v168 offset:51200
	ds_read_b128 v[218:221], v168 offset:52224
	ds_read_b128 v[222:225], v168 offset:53248
	ds_read_b128 v[226:229], v168 offset:54272
	ds_read_b128 v[230:233], v168 offset:55296
	ds_read_b128 v[234:237], v168 offset:56320
	global_load_lds_dwordx4 v[146:147], off
	s_add_i32 m0, s40, 0x2000
	s_add_u32 s40, s50, 0x2b0080
	v_lshl_add_u64 v[146:147], v[194:195], 0, s[10:11]
	s_addc_u32 s41, s51, 0
	s_add_i32 s50, s58, s3
	global_load_lds_dwordx4 v[146:147], off
	v_lshl_add_u64 v[146:147], s[40:41], 0, v[132:133]
	s_mov_b32 m0, s50
	s_nop 0
	global_load_lds_dwordx4 v[146:147], off
	v_lshl_add_u64 v[146:147], s[40:41], 0, v[136:137]
	s_add_i32 m0, s50, 0x2000
	s_nop 0
	global_load_lds_dwordx4 v[146:147], off
	v_lshl_add_u64 v[146:147], v[238:239], 0, s[10:11]
	s_mov_b32 m0, s28
	s_nop 0
	global_load_lds_dwordx4 v[146:147], off
	v_lshl_add_u64 v[146:147], v[240:241], 0, s[10:11]
	s_mov_b32 m0, s29
	s_nop 0
	global_load_lds_dwordx4 v[146:147], off
	s_waitcnt vmcnt(8)
	s_waitcnt lgkmcnt(0)
	s_setprio 1
	s_barrier
	v_mfma_f32_16x16x32_bf16 v[62:65], v[170:173], v[206:209], v[62:65]
	v_mfma_f32_16x16x32_bf16 v[62:65], v[174:177], v[210:213], v[62:65]
	v_mfma_f32_16x16x32_bf16 v[46:49], v[174:177], v[218:221], v[46:49]
	v_mfma_f32_16x16x32_bf16 v[46:49], v[170:173], v[214:217], v[46:49]
	v_mfma_f32_16x16x32_bf16 v[30:33], v[170:173], v[222:225], v[30:33]
	v_mfma_f32_16x16x32_bf16 v[30:33], v[174:177], v[226:229], v[30:33]
	v_mfma_f32_16x16x32_bf16 v[14:17], v[174:177], v[234:237], v[14:17]
	v_mfma_f32_16x16x32_bf16 v[14:17], v[170:173], v[230:233], v[14:17]
	v_mfma_f32_16x16x32_bf16 v[10:13], v[178:181], v[230:233], v[10:13]
	v_mfma_f32_16x16x32_bf16 v[10:13], v[182:185], v[234:237], v[10:13]
	v_mfma_f32_16x16x32_bf16 v[58:61], v[182:185], v[210:213], v[58:61]
	v_mfma_f32_16x16x32_bf16 v[58:61], v[178:181], v[206:209], v[58:61]
	v_mfma_f32_16x16x32_bf16 v[42:45], v[178:181], v[214:217], v[42:45]
	v_mfma_f32_16x16x32_bf16 v[42:45], v[182:185], v[218:221], v[42:45]
	v_mfma_f32_16x16x32_bf16 v[26:29], v[182:185], v[226:229], v[26:29]
	v_mfma_f32_16x16x32_bf16 v[26:29], v[178:181], v[222:225], v[26:29]
	s_setprio 0
	s_setprio 1
	v_mfma_f32_16x16x32_bf16 v[54:57], v[186:189], v[206:209], v[54:57]
	v_mfma_f32_16x16x32_bf16 v[54:57], v[190:193], v[210:213], v[54:57]
	v_mfma_f32_16x16x32_bf16 v[38:41], v[190:193], v[218:221], v[38:41]
	v_mfma_f32_16x16x32_bf16 v[38:41], v[186:189], v[214:217], v[38:41]
	v_mfma_f32_16x16x32_bf16 v[22:25], v[186:189], v[222:225], v[22:25]
	v_mfma_f32_16x16x32_bf16 v[22:25], v[190:193], v[226:229], v[22:25]
	v_mfma_f32_16x16x32_bf16 v[6:9], v[190:193], v[234:237], v[6:9]
	v_mfma_f32_16x16x32_bf16 v[6:9], v[186:189], v[230:233], v[6:9]
	v_mfma_f32_16x16x32_bf16 v[2:5], v[196:199], v[230:233], v[2:5]
	v_mfma_f32_16x16x32_bf16 v[2:5], v[202:205], v[234:237], v[2:5]
	v_mfma_f32_16x16x32_bf16 v[50:53], v[202:205], v[210:213], v[50:53]
	v_mfma_f32_16x16x32_bf16 v[50:53], v[196:199], v[206:209], v[50:53]
	v_mfma_f32_16x16x32_bf16 v[34:37], v[196:199], v[214:217], v[34:37]
	v_mfma_f32_16x16x32_bf16 v[34:37], v[202:205], v[218:221], v[34:37]
	v_mfma_f32_16x16x32_bf16 v[18:21], v[202:205], v[226:229], v[18:21]
	v_mfma_f32_16x16x32_bf16 v[18:21], v[196:199], v[222:225], v[18:21]
	s_barrier
	s_setprio 0
	s_add_i32 s56, s56, 2
	s_add_u32 s54, s54, 0x100
	s_addc_u32 s55, s55, 0
	s_cmpk_gt_u32 s56, 0xa9
	s_mov_b64 s[40:41], s[48:49]
	s_cbranch_scc0 .LBB0_1731
	s_and_b64 vcc, exec, s[12:13]
	s_cbranch_vccz .LBB0_1734
	s_barrier

; #define PG8_STAGE(bufoff, gbase, voff) do { _Pragma("unroll") for (int _i = 0; _i < 2; ++_i) \
;         __builtin_amdgcn_global_load_lds((const unsigned*)((const char*)(gbase) + (voff)[_i]), (PG8_LAS unsigned*)(lds + (bufoff) + ldsw + _i * 8192), 16, 0, 0); } while (0)
; #define PG8_LDA(dst, b, h) do { _Pragma("unroll") for (int m = 0; m < 4; ++m) _Pragma("unroll") for (int k = 0; k < 2; ++k) dst[m][k] = *(const PG8_LAS bf16x8*)(lds + PG8_SA(b, h) + aoff + m * 2048 + k * 1024); } while (0)
; #define PG8_LDB(dst, b, h) do { _Pragma("unroll") for (int n = 0; n < 2; ++n) _Pragma("unroll") for (int k = 0; k < 2; ++k) dst[n][k] = *(const PG8_LAS bf16x8*)(lds + PG8_SB(b, h) + boff + n * 2048 + k * 1024); } while (0)
; #define PG8_MMA(ai, bj, At, Bt) do { __builtin_amdgcn_s_setprio(1); _Pragma("unroll") for (int m = 0; m < 4; ++m) _Pragma("unroll") for (int n = 0; n < 2; ++n) _Pragma("unroll") for (int k = 0; k < 2; ++k) \
;         acc[ai][bj][m][n] = __builtin_amdgcn_mfma_f32_16x16x32_bf16(Bt[n][k], At[m][k], acc[ai][bj][m][n], 0, 0, 0); __builtin_amdgcn_s_setprio(0); } while (0)
; #define PG8_WAIT_V(n) asm volatile("s_waitcnt vmcnt(" #n ")" ::: "memory")
; #define PG8_WAIT_L(n) asm volatile("s_waitcnt lgkmcnt(" #n ")" ::: "memory")
; #define PG8_BAR __builtin_amdgcn_s_barrier()
; #define PG8_SCHED __builtin_amdgcn_sched_barrier(0)
; template <class Epi, class Sched, bool ALIGN_EPI = false, bool SP2 = false>
; __device__ __forceinline__ void gemm_phase(PG8_LAS unsigned char* lds, const Gemm g, const Sched& S, const Epi& E) {
;     ...
;             const bool last = (t == nt - 2);
;             const char* a1 = cA + (size_t)(t + 1) * kstep;
;             const char* a2 = last ? nA : cA + (size_t)(t + 2) * kstep; const char* b2 = last ? nB : cB + (size_t)(t + 2) * kstep;
;             const char* a3 = a2 + kstep; const char* b3 = b2 + kstep;
;             if (last && has_next) S.a_ready(nxt);
;             if constexpr (SP2) {
;             PG8_LDB(B0, 0, 0); PG8_LDB(B1, 0, 1); PG8_SCHED; PG8_LDA(At, 0, 0); PG8_STAGE(PG8_SA(1, 1), a1 + hstep, voffA);
;             PG8_WAIT_V(8); PG8_WAIT_L(0); PG8_BAR; PG8_MMA(0, 0, At, B0); PG8_MMA(0, 1, At, B1); PG8_BAR; PG8_SCHED;
;             PG8_LDA(At, 0, 1); PG8_STAGE(PG8_SB(0, 0), b2, voffB); PG8_STAGE(PG8_SB(0, 1), b2 + hstep, voffB); PG8_STAGE(PG8_SA(0, 0), a2, voffA);
.LBB0_1746:
	ds_read_b128 v[140:143], v134
	ds_read_b128 v[144:147], v134 offset:1024
	ds_read_b128 v[148:151], v134 offset:2048
	ds_read_b128 v[152:155], v134 offset:3072
	ds_read_b128 v[156:159], v135
	ds_read_b128 v[160:163], v135 offset:1024
	ds_read_b128 v[164:167], v135 offset:2048
	ds_read_b128 v[168:171], v135 offset:3072
	s_add_i32 s36, s38, 2
	s_mov_b32 s37, s11
	s_or_b32 s10, s38, 1
	s_lshl_b64 s[40:41], s[36:37], 7
	s_cmp_lg_u32 s38, s42
	s_cselect_b32 s38, s40, 0
	s_cselect_b32 s37, s41, 0
	s_add_u32 s40, s6, s38
	s_addc_u32 s41, s7, s37
	s_add_u32 s38, s2, s38
	s_addc_u32 s39, s3, s37
	s_lshl_b64 s[52:53], s[10:11], 7
	s_add_u32 s52, s8, s52
	s_addc_u32 s53, s9, s53
	s_mov_b32 m0, s43
	v_lshl_add_u64 v[192:193], s[52:53], 0, v[128:129]
	ds_read_b128 v[172:175], v136
	ds_read_b128 v[176:179], v136 offset:1024
	ds_read_b128 v[180:183], v136 offset:2048
	ds_read_b128 v[184:187], v136 offset:3072
	ds_read_b128 v[188:191], v136 offset:4096
	ds_read_b128 v[196:199], v136 offset:5120
	ds_read_b128 v[202:205], v136 offset:6144
	ds_read_b128 v[206:209], v136 offset:7168
	global_load_lds_dwordx4 v[192:193], off
	v_lshl_add_u64 v[192:193], s[52:53], 0, v[130:131]
	s_mov_b32 m0, s44
	s_nop 0
	global_load_lds_dwordx4 v[192:193], off
	s_waitcnt vmcnt(8)
	s_waitcnt lgkmcnt(0)
	s_setprio 1
	s_barrier
	v_mfma_f32_16x16x32_bf16 v[124:127], v[140:143], v[172:175], v[124:127]
	v_mfma_f32_16x16x32_bf16 v[124:127], v[144:147], v[176:179], v[124:127]
	v_mfma_f32_16x16x32_bf16 v[116:119], v[144:147], v[184:187], v[116:119]
	v_mfma_f32_16x16x32_bf16 v[116:119], v[140:143], v[180:183], v[116:119]
	v_mfma_f32_16x16x32_bf16 v[104:107], v[140:143], v[188:191], v[104:107]
	v_mfma_f32_16x16x32_bf16 v[104:107], v[144:147], v[196:199], v[104:107]
	v_mfma_f32_16x16x32_bf16 v[88:91], v[144:147], v[206:209], v[88:91]
	v_mfma_f32_16x16x32_bf16 v[88:91], v[140:143], v[202:205], v[88:91]
	v_mfma_f32_16x16x32_bf16 v[80:83], v[148:151], v[202:205], v[80:83]
	v_mfma_f32_16x16x32_bf16 v[80:83], v[152:155], v[206:209], v[80:83]
	v_mfma_f32_16x16x32_bf16 v[120:123], v[152:155], v[176:179], v[120:123]
	v_mfma_f32_16x16x32_bf16 v[120:123], v[148:151], v[172:175], v[120:123]
	v_mfma_f32_16x16x32_bf16 v[112:115], v[148:151], v[180:183], v[112:115]
	v_mfma_f32_16x16x32_bf16 v[112:115], v[152:155], v[184:187], v[112:115]
	v_mfma_f32_16x16x32_bf16 v[96:99], v[152:155], v[196:199], v[96:99]
	v_mfma_f32_16x16x32_bf16 v[96:99], v[148:151], v[188:191], v[96:99]
	s_setprio 0
	s_setprio 1
	v_mfma_f32_16x16x32_bf16 v[108:111], v[156:159], v[172:175], v[108:111]
	v_mfma_f32_16x16x32_bf16 v[108:111], v[160:163], v[176:179], v[108:111]
	v_mfma_f32_16x16x32_bf16 v[92:95], v[160:163], v[184:187], v[92:95]
	v_mfma_f32_16x16x32_bf16 v[92:95], v[156:159], v[180:183], v[92:95]
	v_mfma_f32_16x16x32_bf16 v[76:79], v[156:159], v[188:191], v[76:79]
	v_mfma_f32_16x16x32_bf16 v[76:79], v[160:163], v[196:199], v[76:79]
	v_mfma_f32_16x16x32_bf16 v[68:71], v[160:163], v[206:209], v[68:71]
	v_mfma_f32_16x16x32_bf16 v[68:71], v[156:159], v[202:205], v[68:71]
	v_mfma_f32_16x16x32_bf16 v[64:67], v[164:167], v[202:205], v[64:67]
	v_mfma_f32_16x16x32_bf16 v[64:67], v[168:171], v[206:209], v[64:67]
	v_mfma_f32_16x16x32_bf16 v[100:103], v[168:171], v[176:179], v[100:103]
	v_mfma_f32_16x16x32_bf16 v[100:103], v[164:167], v[172:175], v[100:103]
	v_mfma_f32_16x16x32_bf16 v[84:87], v[164:167], v[180:183], v[84:87]
	v_mfma_f32_16x16x32_bf16 v[84:87], v[168:171], v[184:187], v[84:87]
	v_mfma_f32_16x16x32_bf16 v[72:75], v[168:171], v[196:199], v[72:75]
	v_mfma_f32_16x16x32_bf16 v[72:75], v[164:167], v[188:191], v[72:75]
	s_barrier
	s_setprio 0
	s_mov_b32 m0, s31
	v_lshl_add_u64 v[192:193], s[38:39], 0, v[128:129]
	s_add_u32 s52, s38, 0x2b0000
	ds_read_b128 v[172:175], v136 offset:16384
	ds_read_b128 v[176:179], v136 offset:17408
	ds_read_b128 v[180:183], v136 offset:18432
	ds_read_b128 v[184:187], v136 offset:19456
	ds_read_b128 v[188:191], v136 offset:20480
	ds_read_b128 v[196:199], v136 offset:21504
	ds_read_b128 v[202:205], v136 offset:22528
	ds_read_b128 v[206:209], v136 offset:23552
	global_load_lds_dwordx4 v[192:193], off
	v_lshl_add_u64 v[194:195], s[38:39], 0, v[130:131]
	s_mov_b32 m0, s45
	s_addc_u32 s53, s39, 0
	global_load_lds_dwordx4 v[194:195], off
	v_lshl_add_u64 v[210:211], s[52:53], 0, v[128:129]
	s_mov_b32 m0, s46
	v_lshl_add_u64 v[212:213], s[40:41], 0, v[130:131]
	global_load_lds_dwordx4 v[210:211], off
	v_lshl_add_u64 v[210:211], s[52:53], 0, v[130:131]
	s_mov_b32 m0, s47
	s_nop 0
	global_load_lds_dwordx4 v[210:211], off
	v_lshl_add_u64 v[210:211], s[40:41], 0, v[128:129]
	s_mov_b32 m0, s26
	s_nop 0
	global_load_lds_dwordx4 v[210:211], off
	s_mov_b32 m0, s27
	s_nop 0
	global_load_lds_dwordx4 v[212:213], off
	s_waitcnt vmcnt(8)
	s_waitcnt lgkmcnt(0)
	s_setprio 1
	s_barrier
; #define PG8_STAGE(bufoff, gbase, voff) do { _Pragma("unroll") for (int _i = 0; _i < 2; ++_i) \
;         __builtin_amdgcn_global_load_lds((const unsigned*)((const char*)(gbase) + (voff)[_i]), (PG8_LAS unsigned*)(lds + (bufoff) + ldsw + _i * 8192), 16, 0, 0); } while (0)
; #define PG8_LDA(dst, b, h) do { _Pragma("unroll") for (int m = 0; m < 4; ++m) _Pragma("unroll") for (int k = 0; k < 2; ++k) dst[m][k] = *(const PG8_LAS bf16x8*)(lds + PG8_SA(b, h) + aoff + m * 2048 + k * 1024); } while (0)
; #define PG8_LDB(dst, b, h) do { _Pragma("unroll") for (int n = 0; n < 2; ++n) _Pragma("unroll") for (int k = 0; k < 2; ++k) dst[n][k] = *(const PG8_LAS bf16x8*)(lds + PG8_SB(b, h) + boff + n * 2048 + k * 1024); } while (0)
; #define PG8_MMA(ai, bj, At, Bt) do { __builtin_amdgcn_s_setprio(1); _Pragma("unroll") for (int m = 0; m < 4; ++m) _Pragma("unroll") for (int n = 0; n < 2; ++n) _Pragma("unroll") for (int k = 0; k < 2; ++k) \
;         acc[ai][bj][m][n] = __builtin_amdgcn_mfma_f32_16x16x32_bf16(Bt[n][k], At[m][k], acc[ai][bj][m][n], 0, 0, 0); __builtin_amdgcn_s_setprio(0); } while (0)
; #define PG8_WAIT_V(n) asm volatile("s_waitcnt vmcnt(" #n ")" ::: "memory")
; #define PG8_WAIT_L(n) asm volatile("s_waitcnt lgkmcnt(" #n ")" ::: "memory")
; #define PG8_BAR __builtin_amdgcn_s_barrier()
; #define PG8_SCHED __builtin_amdgcn_sched_barrier(0)
; template <class Epi, class Sched, bool ALIGN_EPI = false, bool SP2 = false>
; __device__ __forceinline__ void gemm_phase(PG8_LAS unsigned char* lds, const Gemm g, const Sched& S, const Epi& E) {
;     ...
;             PG8_WAIT_V(8); PG8_WAIT_L(0); PG8_BAR; PG8_MMA(1, 0, At, B0); PG8_MMA(1, 1, At, B1); PG8_BAR; PG8_SCHED;
;             PG8_LDB(B0, 1, 0); PG8_LDB(B1, 1, 1); PG8_SCHED; PG8_LDA(At, 1, 0); PG8_STAGE(PG8_SA(0, 1), a2 + hstep, voffA);
;             PG8_WAIT_V(8); PG8_WAIT_L(0); PG8_BAR; PG8_MMA(0, 0, At, B0); PG8_MMA(0, 1, At, B1); PG8_BAR; PG8_SCHED;
	v_mfma_f32_16x16x32_bf16 v[60:63], v[140:143], v[172:175], v[60:63]
	v_mfma_f32_16x16x32_bf16 v[60:63], v[144:147], v[176:179], v[60:63]
	v_mfma_f32_16x16x32_bf16 v[52:55], v[144:147], v[184:187], v[52:55]
	v_mfma_f32_16x16x32_bf16 v[52:55], v[140:143], v[180:183], v[52:55]
	v_mfma_f32_16x16x32_bf16 v[40:43], v[140:143], v[188:191], v[40:43]
	v_mfma_f32_16x16x32_bf16 v[40:43], v[144:147], v[196:199], v[40:43]
	v_mfma_f32_16x16x32_bf16 v[24:27], v[144:147], v[206:209], v[24:27]
	v_mfma_f32_16x16x32_bf16 v[24:27], v[140:143], v[202:205], v[24:27]
	v_mfma_f32_16x16x32_bf16 v[16:19], v[148:151], v[202:205], v[16:19]
	v_mfma_f32_16x16x32_bf16 v[16:19], v[152:155], v[206:209], v[16:19]
	v_mfma_f32_16x16x32_bf16 v[56:59], v[152:155], v[176:179], v[56:59]
	v_mfma_f32_16x16x32_bf16 v[56:59], v[148:151], v[172:175], v[56:59]
	v_mfma_f32_16x16x32_bf16 v[48:51], v[148:151], v[180:183], v[48:51]
	v_mfma_f32_16x16x32_bf16 v[48:51], v[152:155], v[184:187], v[48:51]
	v_mfma_f32_16x16x32_bf16 v[32:35], v[152:155], v[196:199], v[32:35]
	v_mfma_f32_16x16x32_bf16 v[32:35], v[148:151], v[188:191], v[32:35]
	s_setprio 0
	s_setprio 1
	v_mfma_f32_16x16x32_bf16 v[44:47], v[156:159], v[172:175], v[44:47]
	v_mfma_f32_16x16x32_bf16 v[44:47], v[160:163], v[176:179], v[44:47]
	v_mfma_f32_16x16x32_bf16 v[28:31], v[160:163], v[184:187], v[28:31]
	v_mfma_f32_16x16x32_bf16 v[28:31], v[156:159], v[180:183], v[28:31]
	v_mfma_f32_16x16x32_bf16 v[12:15], v[156:159], v[188:191], v[12:15]
	v_mfma_f32_16x16x32_bf16 v[12:15], v[160:163], v[196:199], v[12:15]
	v_mfma_f32_16x16x32_bf16 v[4:7], v[160:163], v[206:209], v[4:7]
	v_mfma_f32_16x16x32_bf16 v[4:7], v[156:159], v[202:205], v[4:7]
	v_mfma_f32_16x16x32_bf16 v[0:3], v[164:167], v[202:205], v[0:3]
	v_mfma_f32_16x16x32_bf16 v[0:3], v[168:171], v[206:209], v[0:3]
	v_mfma_f32_16x16x32_bf16 v[36:39], v[168:171], v[176:179], v[36:39]
	v_mfma_f32_16x16x32_bf16 v[36:39], v[164:167], v[172:175], v[36:39]
	v_mfma_f32_16x16x32_bf16 v[20:23], v[164:167], v[180:183], v[20:23]
	v_mfma_f32_16x16x32_bf16 v[20:23], v[168:171], v[184:187], v[20:23]
	v_mfma_f32_16x16x32_bf16 v[8:11], v[168:171], v[196:199], v[8:11]
	v_mfma_f32_16x16x32_bf16 v[8:11], v[164:167], v[188:191], v[8:11]
	s_barrier
	s_setprio 0
	ds_read_b128 v[140:143], v137
	ds_read_b128 v[144:147], v137 offset:1024
	ds_read_b128 v[148:151], v137 offset:2048
	ds_read_b128 v[152:155], v137 offset:3072
	ds_read_b128 v[156:159], v138
	ds_read_b128 v[160:163], v138 offset:1024
	ds_read_b128 v[164:167], v138 offset:2048
	ds_read_b128 v[168:171], v138 offset:3072
	s_add_u32 s40, s40, 0x2b0000
	s_addc_u32 s41, s41, 0
	s_mov_b32 m0, s28
	v_lshl_add_u64 v[214:215], s[40:41], 0, v[128:129]
	ds_read_b128 v[172:175], v136 offset:32768
	ds_read_b128 v[176:179], v136 offset:33792
	ds_read_b128 v[180:183], v136 offset:34816
	ds_read_b128 v[184:187], v136 offset:35840
	ds_read_b128 v[188:191], v136 offset:36864
	ds_read_b128 v[196:199], v136 offset:37888
	ds_read_b128 v[202:205], v136 offset:38912
	ds_read_b128 v[206:209], v136 offset:39936
	global_load_lds_dwordx4 v[214:215], off
	v_lshl_add_u64 v[214:215], s[40:41], 0, v[130:131]
	s_mov_b32 m0, s30
	s_nop 0
	global_load_lds_dwordx4 v[214:215], off
	s_waitcnt vmcnt(8)
	s_waitcnt lgkmcnt(0)
	s_setprio 1
	s_barrier
	v_mfma_f32_16x16x32_bf16 v[124:127], v[140:143], v[172:175], v[124:127]
	v_mfma_f32_16x16x32_bf16 v[124:127], v[144:147], v[176:179], v[124:127]
	v_mfma_f32_16x16x32_bf16 v[116:119], v[144:147], v[184:187], v[116:119]
	v_mfma_f32_16x16x32_bf16 v[116:119], v[140:143], v[180:183], v[116:119]
	v_mfma_f32_16x16x32_bf16 v[104:107], v[140:143], v[188:191], v[104:107]
	v_mfma_f32_16x16x32_bf16 v[104:107], v[144:147], v[196:199], v[104:107]
	v_mfma_f32_16x16x32_bf16 v[88:91], v[144:147], v[206:209], v[88:91]
	v_mfma_f32_16x16x32_bf16 v[88:91], v[140:143], v[202:205], v[88:91]
	v_mfma_f32_16x16x32_bf16 v[80:83], v[148:151], v[202:205], v[80:83]
	v_mfma_f32_16x16x32_bf16 v[80:83], v[152:155], v[206:209], v[80:83]
	v_mfma_f32_16x16x32_bf16 v[120:123], v[152:155], v[176:179], v[120:123]
	v_mfma_f32_16x16x32_bf16 v[120:123], v[148:151], v[172:175], v[120:123]
	v_mfma_f32_16x16x32_bf16 v[112:115], v[148:151], v[180:183], v[112:115]
	v_mfma_f32_16x16x32_bf16 v[112:115], v[152:155], v[184:187], v[112:115]
	v_mfma_f32_16x16x32_bf16 v[96:99], v[152:155], v[196:199], v[96:99]
	v_mfma_f32_16x16x32_bf16 v[96:99], v[148:151], v[188:191], v[96:99]
	s_setprio 0
	s_setprio 1
	v_mfma_f32_16x16x32_bf16 v[108:111], v[156:159], v[172:175], v[108:111]
	v_mfma_f32_16x16x32_bf16 v[108:111], v[160:163], v[176:179], v[108:111]
	v_mfma_f32_16x16x32_bf16 v[92:95], v[160:163], v[184:187], v[92:95]
	v_mfma_f32_16x16x32_bf16 v[92:95], v[156:159], v[180:183], v[92:95]
	v_mfma_f32_16x16x32_bf16 v[76:79], v[156:159], v[188:191], v[76:79]
	v_mfma_f32_16x16x32_bf16 v[76:79], v[160:163], v[196:199], v[76:79]
	v_mfma_f32_16x16x32_bf16 v[68:71], v[160:163], v[206:209], v[68:71]
	v_mfma_f32_16x16x32_bf16 v[68:71], v[156:159], v[202:205], v[68:71]
	v_mfma_f32_16x16x32_bf16 v[64:67], v[164:167], v[202:205], v[64:67]
	v_mfma_f32_16x16x32_bf16 v[64:67], v[168:171], v[206:209], v[64:67]
	v_mfma_f32_16x16x32_bf16 v[100:103], v[168:171], v[176:179], v[100:103]
	v_mfma_f32_16x16x32_bf16 v[100:103], v[164:167], v[172:175], v[100:103]
	v_mfma_f32_16x16x32_bf16 v[84:87], v[164:167], v[180:183], v[84:87]
	v_mfma_f32_16x16x32_bf16 v[84:87], v[168:171], v[184:187], v[84:87]
	v_mfma_f32_16x16x32_bf16 v[72:75], v[168:171], v[196:199], v[72:75]
	v_mfma_f32_16x16x32_bf16 v[72:75], v[164:167], v[188:191], v[72:75]
	s_barrier
; #define PG8_STAGE(bufoff, gbase, voff) do { _Pragma("unroll") for (int _i = 0; _i < 2; ++_i) \
;         __builtin_amdgcn_global_load_lds((const unsigned*)((const char*)(gbase) + (voff)[_i]), (PG8_LAS unsigned*)(lds + (bufoff) + ldsw + _i * 8192), 16, 0, 0); } while (0)
; #define PG8_LDA(dst, b, h) do { _Pragma("unroll") for (int m = 0; m < 4; ++m) _Pragma("unroll") for (int k = 0; k < 2; ++k) dst[m][k] = *(const PG8_LAS bf16x8*)(lds + PG8_SA(b, h) + aoff + m * 2048 + k * 1024); } while (0)
; #define PG8_MMA(ai, bj, At, Bt) do { __builtin_amdgcn_s_setprio(1); _Pragma("unroll") for (int m = 0; m < 4; ++m) _Pragma("unroll") for (int n = 0; n < 2; ++n) _Pragma("unroll") for (int k = 0; k < 2; ++k) \
;         acc[ai][bj][m][n] = __builtin_amdgcn_mfma_f32_16x16x32_bf16(Bt[n][k], At[m][k], acc[ai][bj][m][n], 0, 0, 0); __builtin_amdgcn_s_setprio(0); } while (0)
; #define PG8_WAIT_V(n) asm volatile("s_waitcnt vmcnt(" #n ")" ::: "memory")
; #define PG8_WAIT_L(n) asm volatile("s_waitcnt lgkmcnt(" #n ")" ::: "memory")
; #define PG8_BAR __builtin_amdgcn_s_barrier()
; #define PG8_SCHED __builtin_amdgcn_sched_barrier(0)
; template <class Epi, class Sched, bool ALIGN_EPI = false, bool SP2 = false>
; __device__ __forceinline__ void gemm_phase(PG8_LAS unsigned char* lds, const Gemm g, const Sched& S, const Epi& E) {
;     ...
;             PG8_LDA(At, 1, 1); PG8_STAGE(PG8_SB(1, 0), b3, voffB); PG8_STAGE(PG8_SB(1, 1), b3 + hstep, voffB); PG8_STAGE(PG8_SA(1, 0), a3, voffA);
;             PG8_WAIT_V(8); PG8_WAIT_L(0); PG8_BAR; PG8_MMA(1, 0, At, B0); PG8_MMA(1, 1, At, B1); PG8_BAR; PG8_SCHED;
;     ...
;         if constexpr (ALIGN_EPI) { if (wr == 0) PG8_BAR; }
	s_setprio 0
	s_mov_b32 m0, s48
	v_lshl_add_u64 v[192:193], v[192:193], 0, s[12:13]
	s_add_u32 s38, s38, 0x2b0080
	ds_read_b128 v[172:175], v136 offset:49152
	ds_read_b128 v[176:179], v136 offset:50176
	ds_read_b128 v[180:183], v136 offset:51200
	ds_read_b128 v[184:187], v136 offset:52224
	ds_read_b128 v[188:191], v136 offset:53248
	ds_read_b128 v[196:199], v136 offset:54272
	ds_read_b128 v[202:205], v136 offset:55296
	ds_read_b128 v[206:209], v136 offset:56320
	global_load_lds_dwordx4 v[192:193], off
	v_lshl_add_u64 v[192:193], v[194:195], 0, s[12:13]
	s_mov_b32 m0, s49
	s_addc_u32 s39, s39, 0
	global_load_lds_dwordx4 v[192:193], off
	v_lshl_add_u64 v[192:193], s[38:39], 0, v[128:129]
	s_mov_b32 m0, s50
	s_nop 0
	global_load_lds_dwordx4 v[192:193], off
	v_lshl_add_u64 v[192:193], s[38:39], 0, v[130:131]
	s_mov_b32 m0, s51
	s_nop 0
	global_load_lds_dwordx4 v[192:193], off
	v_lshl_add_u64 v[192:193], v[210:211], 0, s[12:13]
	s_mov_b32 m0, s34
	s_nop 0
	global_load_lds_dwordx4 v[192:193], off
	v_lshl_add_u64 v[192:193], v[212:213], 0, s[12:13]
	s_mov_b32 m0, s35
	s_nop 0
	global_load_lds_dwordx4 v[192:193], off
	s_waitcnt vmcnt(8)
	s_waitcnt lgkmcnt(0)
	s_setprio 1
	s_barrier
	v_mfma_f32_16x16x32_bf16 v[60:63], v[140:143], v[172:175], v[60:63]
	v_mfma_f32_16x16x32_bf16 v[60:63], v[144:147], v[176:179], v[60:63]
	v_mfma_f32_16x16x32_bf16 v[52:55], v[144:147], v[184:187], v[52:55]
	v_mfma_f32_16x16x32_bf16 v[52:55], v[140:143], v[180:183], v[52:55]
	v_mfma_f32_16x16x32_bf16 v[40:43], v[140:143], v[188:191], v[40:43]
	v_mfma_f32_16x16x32_bf16 v[40:43], v[144:147], v[196:199], v[40:43]
	v_mfma_f32_16x16x32_bf16 v[24:27], v[144:147], v[206:209], v[24:27]
	v_mfma_f32_16x16x32_bf16 v[24:27], v[140:143], v[202:205], v[24:27]
	v_mfma_f32_16x16x32_bf16 v[16:19], v[148:151], v[202:205], v[16:19]
	v_mfma_f32_16x16x32_bf16 v[16:19], v[152:155], v[206:209], v[16:19]
	v_mfma_f32_16x16x32_bf16 v[56:59], v[152:155], v[176:179], v[56:59]
	v_mfma_f32_16x16x32_bf16 v[56:59], v[148:151], v[172:175], v[56:59]
	v_mfma_f32_16x16x32_bf16 v[48:51], v[148:151], v[180:183], v[48:51]
	v_mfma_f32_16x16x32_bf16 v[48:51], v[152:155], v[184:187], v[48:51]
	v_mfma_f32_16x16x32_bf16 v[32:35], v[152:155], v[196:199], v[32:35]
	v_mfma_f32_16x16x32_bf16 v[32:35], v[148:151], v[188:191], v[32:35]
	s_setprio 0
	s_setprio 1
	v_mfma_f32_16x16x32_bf16 v[44:47], v[156:159], v[172:175], v[44:47]
	v_mfma_f32_16x16x32_bf16 v[44:47], v[160:163], v[176:179], v[44:47]
	v_mfma_f32_16x16x32_bf16 v[28:31], v[160:163], v[184:187], v[28:31]
	v_mfma_f32_16x16x32_bf16 v[28:31], v[156:159], v[180:183], v[28:31]
	v_mfma_f32_16x16x32_bf16 v[12:15], v[156:159], v[188:191], v[12:15]
	v_mfma_f32_16x16x32_bf16 v[12:15], v[160:163], v[196:199], v[12:15]
	v_mfma_f32_16x16x32_bf16 v[4:7], v[160:163], v[206:209], v[4:7]
	v_mfma_f32_16x16x32_bf16 v[4:7], v[156:159], v[202:205], v[4:7]
	v_mfma_f32_16x16x32_bf16 v[0:3], v[164:167], v[202:205], v[0:3]
	v_mfma_f32_16x16x32_bf16 v[0:3], v[168:171], v[206:209], v[0:3]
	v_mfma_f32_16x16x32_bf16 v[36:39], v[168:171], v[176:179], v[36:39]
	v_mfma_f32_16x16x32_bf16 v[36:39], v[164:167], v[172:175], v[36:39]
	v_mfma_f32_16x16x32_bf16 v[20:23], v[164:167], v[180:183], v[20:23]
	v_mfma_f32_16x16x32_bf16 v[20:23], v[168:171], v[184:187], v[20:23]
	v_mfma_f32_16x16x32_bf16 v[8:11], v[168:171], v[196:199], v[8:11]
	v_mfma_f32_16x16x32_bf16 v[8:11], v[164:167], v[188:191], v[8:11]
	s_barrier
	s_setprio 0
	s_cmp_ge_u32 s36, s5
	s_mov_b32 s38, s36
	s_cbranch_scc0 .LBB0_1746
	s_cmpk_lt_u32 s16, 0x100
	s_cbranch_scc0 .LBB0_1749
	s_barrier
